# phase B main-tile epilogue stores marked non-temporal (nt) so the streamed outputs do not displace GEMM operands in L2
# speedup vs baseline: 1.0051x; 1.0051x over previous
; __device__ __forceinline__ u32x2 pack4(f32x4 v) { u32x2 r; r.x = cvt_pk(v[0], v[1]); r.y = cvt_pk(v[2], v[3]); return r; }
; __device__ __forceinline__ float sigm_f(float x) { return __builtin_amdgcn_rcpf(1.f + __builtin_amdgcn_exp2f(-1.4426950409f * x)); }
; __device__ __forceinline__ void store_pair16(u16* rowp32, u32x2 a, u32x2 b, int fq) {
;   auto rx = __builtin_amdgcn_permlane16_swap(a.x, b.x, false, false);
;   auto ry = __builtin_amdgcn_permlane16_swap(a.y, b.y, false, false);
;   u32x4 w = {rx[0], ry[0], rx[1], ry[1]};
;   *(u32x4*)(rowp32 + ((fq & 1) * 16 + (fq >> 1) * 8)) = w;
; }
; template <int SEC> __device__ __forceinline__ void epiB2(const Params& p, int row, int col32, f32x4 v0, f32x4 v1, int fq) {
;     ...
;   else { f32x4 o0 = {sigm_f(v0[0]), sigm_f(v0[1]), sigm_f(v0[2]), sigm_f(v0[3])}, o1 = {sigm_f(v1[0]), sigm_f(v1[1]), sigm_f(v1[2]), sigm_f(v1[3])};
;     store_pair16((u16*)(ws + OFF_GATE) + (size_t)row * 3072 + (col32 - 4096), pack4(o0), pack4(o1), fq); }
.LBB0_198:
	s_add_i32 s33, s33, s57
	s_cmpk_lt_u32 s52, 0x1000
	s_cselect_b32 s4, 3, 4
	s_cmpk_gt_u32 s52, 0xdff
	s_cselect_b32 s4, s4, 2
	s_cmpk_gt_u32 s52, 0x7ff
	s_cselect_b32 s4, s4, 1
	s_cmpk_gt_i32 s38, 0x3ff
	s_cselect_b32 s39, s4, 0
	s_cmp_lt_i32 s39, 2
	s_mov_b64 s[4:5], -1
	s_cbranch_scc1 .LBB0_216
	s_cmp_lt_i32 s39, 3
	s_cbranch_scc1 .LBB0_205
	s_cmp_lg_u32 s39, 3
	s_cbranch_scc0 .LBB0_202
	v_mbcnt_lo_u32_b32 v130, -1, 0
	v_mbcnt_hi_u32_b32 v130, -1, v130
	v_mul_f32_e32 v134, 0xbfb8aa3b, v127
	v_and_or_b32 v128, v130, 15, s33
	v_and_b32_e32 v131, 16, v130
	v_ashrrev_i32_e32 v130, 2, v130
	v_and_b32_e32 v130, -8, v130
	v_add_u32_e32 v132, v130, v131
	v_mul_f32_e32 v130, 0xbfb8aa3b, v124
	v_exp_f32_e32 v130, v130
	v_mul_f32_e32 v131, 0xbfb8aa3b, v125
	v_exp_f32_e32 v131, v131
	v_exp_f32_e32 v134, v134
	v_add_f32_e32 v130, 1.0, v130
	v_rcp_f32_e32 v137, v130
	v_add_f32_e32 v130, 1.0, v131
	v_mul_f32_e32 v131, 0xbfb8aa3b, v126
	v_exp_f32_e32 v131, v131
	v_rcp_f32_e32 v138, v130
	s_or_b32 s4, s38, s66
	s_ashr_i32 s5, s4, 31
	v_add_f32_e32 v130, 1.0, v131
	v_mul_f32_e32 v131, 0xbfb8aa3b, v120
	v_rcp_f32_e32 v139, v130
	v_add_f32_e32 v130, 1.0, v134
	v_exp_f32_e32 v131, v131
	v_mul_f32_e32 v134, 0xbfb8aa3b, v121
	v_exp_f32_e32 v134, v134
	v_rcp_f32_e32 v140, v130
	v_add_f32_e32 v130, 1.0, v131
	v_mul_f32_e32 v131, 0xbfb8aa3b, v122
	v_rcp_f32_e32 v141, v130
	v_add_f32_e32 v130, 1.0, v134
	v_exp_f32_e32 v131, v131
	v_mul_f32_e32 v134, 0xbfb8aa3b, v123
	v_exp_f32_e32 v134, v134
	v_rcp_f32_e32 v142, v130
	v_add_f32_e32 v130, 1.0, v131
	v_rcp_f32_e32 v143, v130
	v_add_f32_e32 v130, 1.0, v134
	v_rcp_f32_e32 v144, v130
	v_mov_b64_e32 v[130:131], s[50:51]
	v_ashrrev_i32_e32 v133, 31, v132
	v_mad_u64_u32 v[134:135], s[40:41], v128, s71, v[130:131]
	s_lshl_b64 s[4:5], s[4:5], 1
	v_cvt_pk_bf16_f32 v139, v139, v140
	v_cvt_pk_bf16_f32 v140, v141, v142
	v_mul_f32_e32 v142, 0xbfb8aa3b, v117
	v_lshl_add_u64 v[134:135], v[134:135], 0, s[4:5]
	v_lshlrev_b64 v[132:133], 1, v[132:133]
	v_exp_f32_e32 v142, v142
	v_lshl_add_u64 v[134:135], v[134:135], 0, v[132:133]
	v_cvt_pk_bf16_f32 v138, v137, v138
	v_cvt_pk_bf16_f32 v141, v143, v144
	v_add_co_u32_e32 v134, vcc, s72, v134
	v_permlane16_swap_b32_e32 v138, v140
	v_permlane16_swap_b32_e32 v139, v141
	v_addc_co_u32_e32 v135, vcc, 0, v135, vcc
	v_mul_f32_e32 v137, 0xbfb8aa3b, v116
	global_store_dwordx4 v[134:135], v[138:141], off nt
	v_mul_f32_e32 v143, 0xbfb8aa3b, v114
	v_mul_f32_e32 v144, 0xbfb8aa3b, v115
	v_add_f32_e32 v138, 1.0, v142
	v_mul_f32_e32 v139, 0xbfb8aa3b, v118
	v_mul_f32_e32 v140, 0xbfb8aa3b, v119
	v_mul_f32_e32 v141, 0xbfb8aa3b, v112
	v_mul_f32_e32 v142, 0xbfb8aa3b, v113
	v_exp_f32_e32 v137, v137
	v_exp_f32_e32 v139, v139
	v_exp_f32_e32 v140, v140
	v_exp_f32_e32 v141, v141
	v_exp_f32_e32 v142, v142
	v_exp_f32_e32 v143, v143
	v_exp_f32_e32 v144, v144
	v_add_f32_e32 v137, 1.0, v137
	v_add_f32_e32 v139, 1.0, v139
	v_add_f32_e32 v140, 1.0, v140
	v_add_f32_e32 v141, 1.0, v141
	v_add_f32_e32 v142, 1.0, v142
	v_add_f32_e32 v143, 1.0, v143
	v_add_f32_e32 v144, 1.0, v144
	v_rcp_f32_e32 v137, v137
	v_rcp_f32_e32 v138, v138
	v_rcp_f32_e32 v139, v139
	v_rcp_f32_e32 v140, v140
	v_rcp_f32_e32 v141, v141
	v_rcp_f32_e32 v142, v142
	v_rcp_f32_e32 v143, v143
	v_rcp_f32_e32 v144, v144
	v_cvt_pk_bf16_f32 v138, v137, v138
	v_cvt_pk_bf16_f32 v139, v139, v140
	v_cvt_pk_bf16_f32 v140, v141, v142
	v_cvt_pk_bf16_f32 v141, v143, v144
	s_nop 0
	v_permlane16_swap_b32_e32 v138, v140
	v_permlane16_swap_b32_e32 v139, v141
	global_store_dwordx4 v[134:135], v[138:141], off offset:256 nt
	v_mul_f32_e32 v134, 0xbfb8aa3b, v108
	v_exp_f32_e32 v134, v134
	v_mul_f32_e32 v135, 0xbfb8aa3b, v109
	v_exp_f32_e32 v135, v135
	v_mul_f32_e32 v139, 0xbfb8aa3b, v111
	v_add_f32_e32 v134, 1.0, v134
	v_rcp_f32_e32 v138, v134
	v_add_f32_e32 v134, 1.0, v135
	v_mul_f32_e32 v135, 0xbfb8aa3b, v110
	v_exp_f32_e32 v135, v135
	v_exp_f32_e32 v139, v139
	v_rcp_f32_e32 v140, v134
	v_or_b32_e32 v137, 16, v128
	v_add_f32_e32 v134, 1.0, v135
	v_mul_f32_e32 v135, 0xbfb8aa3b, v104
	v_rcp_f32_e32 v141, v134
	v_add_f32_e32 v134, 1.0, v139
	v_exp_f32_e32 v135, v135
	v_mul_f32_e32 v139, 0xbfb8aa3b, v105
	v_exp_f32_e32 v139, v139
	v_rcp_f32_e32 v142, v134
	v_add_f32_e32 v134, 1.0, v135
	v_mul_f32_e32 v135, 0xbfb8aa3b, v106
	v_rcp_f32_e32 v143, v134
	v_add_f32_e32 v134, 1.0, v139
	v_exp_f32_e32 v135, v135
	v_mul_f32_e32 v139, 0xbfb8aa3b, v107
	v_exp_f32_e32 v139, v139
	v_rcp_f32_e32 v144, v134
	v_add_f32_e32 v134, 1.0, v135
	v_rcp_f32_e32 v145, v134
	v_add_f32_e32 v134, 1.0, v139
	v_rcp_f32_e32 v146, v134
	v_mad_u64_u32 v[134:135], s[40:41], v137, s71, v[130:131]
	v_cvt_pk_bf16_f32 v139, v141, v142
	v_mul_f32_e32 v142, 0xbfb8aa3b, v101
	v_lshl_add_u64 v[134:135], v[134:135], 0, s[4:5]
	v_exp_f32_e32 v142, v142
	v_lshl_add_u64 v[134:135], v[134:135], 0, v[132:133]
	v_cvt_pk_bf16_f32 v138, v138, v140
	v_cvt_pk_bf16_f32 v140, v143, v144
	v_cvt_pk_bf16_f32 v141, v145, v146
	v_add_co_u32_e32 v134, vcc, s72, v134
	v_permlane16_swap_b32_e32 v138, v140
	v_permlane16_swap_b32_e32 v139, v141
	v_addc_co_u32_e32 v135, vcc, 0, v135, vcc
	v_mul_f32_e32 v137, 0xbfb8aa3b, v100
	global_store_dwordx4 v[134:135], v[138:141], off nt
	v_mul_f32_e32 v143, 0xbfb8aa3b, v98
	v_mul_f32_e32 v144, 0xbfb8aa3b, v99
	v_add_f32_e32 v138, 1.0, v142
	v_mul_f32_e32 v139, 0xbfb8aa3b, v102
	v_mul_f32_e32 v140, 0xbfb8aa3b, v103
	v_mul_f32_e32 v141, 0xbfb8aa3b, v96
	v_mul_f32_e32 v142, 0xbfb8aa3b, v97
	v_exp_f32_e32 v137, v137
	v_exp_f32_e32 v139, v139
	v_exp_f32_e32 v140, v140
	v_exp_f32_e32 v141, v141
	v_exp_f32_e32 v142, v142
	v_exp_f32_e32 v143, v143
	v_exp_f32_e32 v144, v144
	v_add_f32_e32 v137, 1.0, v137
; __device__ __forceinline__ u32x2 pack4(f32x4 v) { u32x2 r; r.x = cvt_pk(v[0], v[1]); r.y = cvt_pk(v[2], v[3]); return r; }
; __device__ __forceinline__ float sigm_f(float x) { return __builtin_amdgcn_rcpf(1.f + __builtin_amdgcn_exp2f(-1.4426950409f * x)); }
; __device__ __forceinline__ void store_pair16(u16* rowp32, u32x2 a, u32x2 b, int fq) {
;   auto rx = __builtin_amdgcn_permlane16_swap(a.x, b.x, false, false);
;   auto ry = __builtin_amdgcn_permlane16_swap(a.y, b.y, false, false);
;   u32x4 w = {rx[0], ry[0], rx[1], ry[1]};
;   *(u32x4*)(rowp32 + ((fq & 1) * 16 + (fq >> 1) * 8)) = w;
; }
; template <int SEC> __device__ __forceinline__ void epiB2(const Params& p, int row, int col32, f32x4 v0, f32x4 v1, int fq) {
;     ...
;   else { f32x4 o0 = {sigm_f(v0[0]), sigm_f(v0[1]), sigm_f(v0[2]), sigm_f(v0[3])}, o1 = {sigm_f(v1[0]), sigm_f(v1[1]), sigm_f(v1[2]), sigm_f(v1[3])};
;     store_pair16((u16*)(ws + OFF_GATE) + (size_t)row * 3072 + (col32 - 4096), pack4(o0), pack4(o1), fq); }
	v_add_f32_e32 v139, 1.0, v139
	v_add_f32_e32 v140, 1.0, v140
	v_add_f32_e32 v141, 1.0, v141
	v_add_f32_e32 v142, 1.0, v142
	v_add_f32_e32 v143, 1.0, v143
	v_add_f32_e32 v144, 1.0, v144
	v_rcp_f32_e32 v137, v137
	v_rcp_f32_e32 v138, v138
	v_rcp_f32_e32 v139, v139
	v_rcp_f32_e32 v140, v140
	v_rcp_f32_e32 v141, v141
	v_rcp_f32_e32 v142, v142
	v_rcp_f32_e32 v143, v143
	v_rcp_f32_e32 v144, v144
	v_cvt_pk_bf16_f32 v138, v137, v138
	v_cvt_pk_bf16_f32 v139, v139, v140
	v_cvt_pk_bf16_f32 v140, v141, v142
	v_cvt_pk_bf16_f32 v141, v143, v144
	s_nop 0
	v_permlane16_swap_b32_e32 v138, v140
	v_permlane16_swap_b32_e32 v139, v141
	global_store_dwordx4 v[134:135], v[138:141], off offset:256 nt
	v_mul_f32_e32 v134, 0xbfb8aa3b, v92
	v_exp_f32_e32 v134, v134
	v_mul_f32_e32 v135, 0xbfb8aa3b, v93
	v_exp_f32_e32 v135, v135
	v_mul_f32_e32 v139, 0xbfb8aa3b, v95
	v_add_f32_e32 v134, 1.0, v134
	v_rcp_f32_e32 v138, v134
	v_add_f32_e32 v134, 1.0, v135
	v_mul_f32_e32 v135, 0xbfb8aa3b, v94
	v_exp_f32_e32 v135, v135
	v_exp_f32_e32 v139, v139
	v_rcp_f32_e32 v140, v134
	v_or_b32_e32 v137, 32, v128
	v_add_f32_e32 v134, 1.0, v135
	v_mul_f32_e32 v135, 0xbfb8aa3b, v88
	v_rcp_f32_e32 v141, v134
	v_add_f32_e32 v134, 1.0, v139
	v_exp_f32_e32 v135, v135
	v_mul_f32_e32 v139, 0xbfb8aa3b, v89
	v_exp_f32_e32 v139, v139
	v_rcp_f32_e32 v142, v134
	v_add_f32_e32 v134, 1.0, v135
	v_mul_f32_e32 v135, 0xbfb8aa3b, v90
	v_rcp_f32_e32 v143, v134
	v_add_f32_e32 v134, 1.0, v139
	v_exp_f32_e32 v135, v135
	v_mul_f32_e32 v139, 0xbfb8aa3b, v91
	v_exp_f32_e32 v139, v139
	v_rcp_f32_e32 v144, v134
	v_add_f32_e32 v134, 1.0, v135
	v_rcp_f32_e32 v145, v134
	v_add_f32_e32 v134, 1.0, v139
	v_rcp_f32_e32 v146, v134
	v_mad_u64_u32 v[134:135], s[40:41], v137, s71, v[130:131]
	v_cvt_pk_bf16_f32 v139, v141, v142
	v_mul_f32_e32 v142, 0xbfb8aa3b, v85
	v_lshl_add_u64 v[134:135], v[134:135], 0, s[4:5]
	v_exp_f32_e32 v142, v142
	v_lshl_add_u64 v[134:135], v[134:135], 0, v[132:133]
	v_cvt_pk_bf16_f32 v138, v138, v140
	v_cvt_pk_bf16_f32 v140, v143, v144
	v_cvt_pk_bf16_f32 v141, v145, v146
	v_add_co_u32_e32 v134, vcc, s72, v134
	v_permlane16_swap_b32_e32 v138, v140
	v_permlane16_swap_b32_e32 v139, v141
	v_addc_co_u32_e32 v135, vcc, 0, v135, vcc
	v_mul_f32_e32 v137, 0xbfb8aa3b, v84
	global_store_dwordx4 v[134:135], v[138:141], off nt
	v_mul_f32_e32 v143, 0xbfb8aa3b, v82
	v_mul_f32_e32 v144, 0xbfb8aa3b, v83
	v_add_f32_e32 v138, 1.0, v142
	v_mul_f32_e32 v139, 0xbfb8aa3b, v86
	v_mul_f32_e32 v140, 0xbfb8aa3b, v87
	v_mul_f32_e32 v141, 0xbfb8aa3b, v80
	v_mul_f32_e32 v142, 0xbfb8aa3b, v81
	v_exp_f32_e32 v137, v137
	v_exp_f32_e32 v139, v139
	v_exp_f32_e32 v140, v140
	v_exp_f32_e32 v141, v141
	v_exp_f32_e32 v142, v142
	v_exp_f32_e32 v143, v143
	v_exp_f32_e32 v144, v144
	v_add_f32_e32 v137, 1.0, v137
	v_add_f32_e32 v139, 1.0, v139
	v_add_f32_e32 v140, 1.0, v140
	v_add_f32_e32 v141, 1.0, v141
	v_add_f32_e32 v142, 1.0, v142
	v_add_f32_e32 v143, 1.0, v143
	v_add_f32_e32 v144, 1.0, v144
	v_rcp_f32_e32 v137, v137
	v_rcp_f32_e32 v138, v138
	v_rcp_f32_e32 v139, v139
	v_rcp_f32_e32 v140, v140
	v_rcp_f32_e32 v141, v141
	v_rcp_f32_e32 v142, v142
	v_rcp_f32_e32 v143, v143
	v_rcp_f32_e32 v144, v144
	v_cvt_pk_bf16_f32 v138, v137, v138
	v_cvt_pk_bf16_f32 v139, v139, v140
	v_cvt_pk_bf16_f32 v140, v141, v142
	v_cvt_pk_bf16_f32 v141, v143, v144
	s_nop 0
	v_permlane16_swap_b32_e32 v138, v140
	v_permlane16_swap_b32_e32 v139, v141
	global_store_dwordx4 v[134:135], v[138:141], off offset:256 nt
	v_mul_f32_e32 v134, 0xbfb8aa3b, v76
	v_exp_f32_e32 v134, v134
	v_mul_f32_e32 v135, 0xbfb8aa3b, v77
	v_exp_f32_e32 v135, v135
	v_mul_f32_e32 v139, 0xbfb8aa3b, v79
	v_add_f32_e32 v134, 1.0, v134
	v_rcp_f32_e32 v138, v134
	v_add_f32_e32 v134, 1.0, v135
	v_mul_f32_e32 v135, 0xbfb8aa3b, v78
	v_exp_f32_e32 v135, v135
	v_exp_f32_e32 v139, v139
	v_rcp_f32_e32 v140, v134
	v_or_b32_e32 v137, 48, v128
	v_add_f32_e32 v134, 1.0, v135
	v_mul_f32_e32 v135, 0xbfb8aa3b, v72
	v_rcp_f32_e32 v141, v134
	v_add_f32_e32 v134, 1.0, v139
	v_exp_f32_e32 v135, v135
	v_mul_f32_e32 v139, 0xbfb8aa3b, v73
	v_exp_f32_e32 v139, v139
	v_rcp_f32_e32 v142, v134
	v_add_f32_e32 v134, 1.0, v135
	v_mul_f32_e32 v135, 0xbfb8aa3b, v74
	v_rcp_f32_e32 v143, v134
	v_add_f32_e32 v134, 1.0, v139
	v_exp_f32_e32 v135, v135
	v_mul_f32_e32 v139, 0xbfb8aa3b, v75
	v_exp_f32_e32 v139, v139
	v_rcp_f32_e32 v144, v134
	v_add_f32_e32 v134, 1.0, v135
	v_rcp_f32_e32 v145, v134
	v_add_f32_e32 v134, 1.0, v139
	v_rcp_f32_e32 v146, v134
	v_mad_u64_u32 v[134:135], s[40:41], v137, s71, v[130:131]
	v_cvt_pk_bf16_f32 v139, v141, v142
	v_mul_f32_e32 v142, 0xbfb8aa3b, v69
	v_lshl_add_u64 v[134:135], v[134:135], 0, s[4:5]
	v_exp_f32_e32 v142, v142
	v_lshl_add_u64 v[134:135], v[134:135], 0, v[132:133]
	v_cvt_pk_bf16_f32 v138, v138, v140
	v_cvt_pk_bf16_f32 v140, v143, v144
	v_cvt_pk_bf16_f32 v141, v145, v146
	v_add_co_u32_e32 v134, vcc, s72, v134
	v_permlane16_swap_b32_e32 v138, v140
	v_permlane16_swap_b32_e32 v139, v141
	v_addc_co_u32_e32 v135, vcc, 0, v135, vcc
	v_mul_f32_e32 v137, 0xbfb8aa3b, v68
	global_store_dwordx4 v[134:135], v[138:141], off nt
	v_mul_f32_e32 v143, 0xbfb8aa3b, v66
	v_mul_f32_e32 v144, 0xbfb8aa3b, v67
	v_add_f32_e32 v138, 1.0, v142
	v_mul_f32_e32 v139, 0xbfb8aa3b, v70
	v_mul_f32_e32 v140, 0xbfb8aa3b, v71
	v_mul_f32_e32 v141, 0xbfb8aa3b, v64
	v_mul_f32_e32 v142, 0xbfb8aa3b, v65
	v_exp_f32_e32 v137, v137
	v_exp_f32_e32 v139, v139
	v_exp_f32_e32 v140, v140
	v_exp_f32_e32 v141, v141
	v_exp_f32_e32 v142, v142
	v_exp_f32_e32 v143, v143
	v_exp_f32_e32 v144, v144
	v_add_f32_e32 v137, 1.0, v137
	v_add_f32_e32 v139, 1.0, v139
	v_add_f32_e32 v140, 1.0, v140
	v_add_f32_e32 v141, 1.0, v141
	v_add_f32_e32 v142, 1.0, v142
; __device__ __forceinline__ u32x2 pack4(f32x4 v) { u32x2 r; r.x = cvt_pk(v[0], v[1]); r.y = cvt_pk(v[2], v[3]); return r; }
; __device__ __forceinline__ float sigm_f(float x) { return __builtin_amdgcn_rcpf(1.f + __builtin_amdgcn_exp2f(-1.4426950409f * x)); }
; __device__ __forceinline__ void store_pair16(u16* rowp32, u32x2 a, u32x2 b, int fq) {
;   auto rx = __builtin_amdgcn_permlane16_swap(a.x, b.x, false, false);
;   auto ry = __builtin_amdgcn_permlane16_swap(a.y, b.y, false, false);
;   u32x4 w = {rx[0], ry[0], rx[1], ry[1]};
;   *(u32x4*)(rowp32 + ((fq & 1) * 16 + (fq >> 1) * 8)) = w;
; }
; template <int SEC> __device__ __forceinline__ void epiB2(const Params& p, int row, int col32, f32x4 v0, f32x4 v1, int fq) {
;     ...
;   else { f32x4 o0 = {sigm_f(v0[0]), sigm_f(v0[1]), sigm_f(v0[2]), sigm_f(v0[3])}, o1 = {sigm_f(v1[0]), sigm_f(v1[1]), sigm_f(v1[2]), sigm_f(v1[3])};
;     store_pair16((u16*)(ws + OFF_GATE) + (size_t)row * 3072 + (col32 - 4096), pack4(o0), pack4(o1), fq); }
	v_add_f32_e32 v143, 1.0, v143
	v_add_f32_e32 v144, 1.0, v144
	v_rcp_f32_e32 v137, v137
	v_rcp_f32_e32 v138, v138
	v_rcp_f32_e32 v139, v139
	v_rcp_f32_e32 v140, v140
	v_rcp_f32_e32 v141, v141
	v_rcp_f32_e32 v142, v142
	v_rcp_f32_e32 v143, v143
	v_rcp_f32_e32 v144, v144
	v_cvt_pk_bf16_f32 v138, v137, v138
	v_cvt_pk_bf16_f32 v139, v139, v140
	v_cvt_pk_bf16_f32 v140, v141, v142
	v_cvt_pk_bf16_f32 v141, v143, v144
	s_nop 0
	v_permlane16_swap_b32_e32 v138, v140
	v_permlane16_swap_b32_e32 v139, v141
	global_store_dwordx4 v[134:135], v[138:141], off offset:256 nt
	v_mul_f32_e32 v134, 0xbfb8aa3b, v60
	v_exp_f32_e32 v134, v134
	v_mul_f32_e32 v135, 0xbfb8aa3b, v61
	v_exp_f32_e32 v135, v135
	v_mul_f32_e32 v139, 0xbfb8aa3b, v63
	v_add_f32_e32 v134, 1.0, v134
	v_rcp_f32_e32 v138, v134
	v_add_f32_e32 v134, 1.0, v135
	v_mul_f32_e32 v135, 0xbfb8aa3b, v62
	v_exp_f32_e32 v135, v135
	v_exp_f32_e32 v139, v139
	v_rcp_f32_e32 v140, v134
	v_add_u32_e32 v137, 0x80, v128
	v_add_f32_e32 v134, 1.0, v135
	v_mul_f32_e32 v135, 0xbfb8aa3b, v56
	v_rcp_f32_e32 v141, v134
	v_add_f32_e32 v134, 1.0, v139
	v_exp_f32_e32 v135, v135
	v_mul_f32_e32 v139, 0xbfb8aa3b, v57
	v_exp_f32_e32 v139, v139
	v_rcp_f32_e32 v142, v134
	v_add_f32_e32 v134, 1.0, v135
	v_mul_f32_e32 v135, 0xbfb8aa3b, v58
	v_rcp_f32_e32 v143, v134
	v_add_f32_e32 v134, 1.0, v139
	v_exp_f32_e32 v135, v135
	v_mul_f32_e32 v139, 0xbfb8aa3b, v59
	v_exp_f32_e32 v139, v139
	v_rcp_f32_e32 v144, v134
	v_add_f32_e32 v134, 1.0, v135
	v_rcp_f32_e32 v145, v134
	v_add_f32_e32 v134, 1.0, v139
	v_rcp_f32_e32 v146, v134
	v_mad_u64_u32 v[134:135], s[40:41], v137, s71, v[130:131]
	v_cvt_pk_bf16_f32 v139, v141, v142
	v_mul_f32_e32 v142, 0xbfb8aa3b, v53
	v_lshl_add_u64 v[134:135], v[134:135], 0, s[4:5]
	v_exp_f32_e32 v142, v142
	v_lshl_add_u64 v[134:135], v[134:135], 0, v[132:133]
	v_cvt_pk_bf16_f32 v138, v138, v140
	v_cvt_pk_bf16_f32 v140, v143, v144
	v_cvt_pk_bf16_f32 v141, v145, v146
	v_add_co_u32_e32 v134, vcc, s72, v134
	v_permlane16_swap_b32_e32 v138, v140
	v_permlane16_swap_b32_e32 v139, v141
	v_addc_co_u32_e32 v135, vcc, 0, v135, vcc
	v_mul_f32_e32 v137, 0xbfb8aa3b, v52
	global_store_dwordx4 v[134:135], v[138:141], off nt
	v_mul_f32_e32 v143, 0xbfb8aa3b, v50
	v_mul_f32_e32 v144, 0xbfb8aa3b, v51
	v_add_f32_e32 v138, 1.0, v142
	v_mul_f32_e32 v139, 0xbfb8aa3b, v54
	v_mul_f32_e32 v140, 0xbfb8aa3b, v55
	v_mul_f32_e32 v141, 0xbfb8aa3b, v48
	v_mul_f32_e32 v142, 0xbfb8aa3b, v49
	v_exp_f32_e32 v137, v137
	v_exp_f32_e32 v139, v139
	v_exp_f32_e32 v140, v140
	v_exp_f32_e32 v141, v141
	v_exp_f32_e32 v142, v142
	v_exp_f32_e32 v143, v143
	v_exp_f32_e32 v144, v144
	v_add_f32_e32 v137, 1.0, v137
	v_add_f32_e32 v139, 1.0, v139
	v_add_f32_e32 v140, 1.0, v140
	v_add_f32_e32 v141, 1.0, v141
	v_add_f32_e32 v142, 1.0, v142
	v_add_f32_e32 v143, 1.0, v143
	v_add_f32_e32 v144, 1.0, v144
	v_rcp_f32_e32 v137, v137
	v_rcp_f32_e32 v138, v138
	v_rcp_f32_e32 v139, v139
	v_rcp_f32_e32 v140, v140
	v_rcp_f32_e32 v141, v141
	v_rcp_f32_e32 v142, v142
	v_rcp_f32_e32 v143, v143
	v_rcp_f32_e32 v144, v144
	v_cvt_pk_bf16_f32 v138, v137, v138
	v_cvt_pk_bf16_f32 v139, v139, v140
	v_cvt_pk_bf16_f32 v140, v141, v142
	v_cvt_pk_bf16_f32 v141, v143, v144
	s_nop 0
	v_permlane16_swap_b32_e32 v138, v140
	v_permlane16_swap_b32_e32 v139, v141
	global_store_dwordx4 v[134:135], v[138:141], off offset:256 nt
	v_mul_f32_e32 v134, 0xbfb8aa3b, v44
	v_exp_f32_e32 v134, v134
	v_mul_f32_e32 v135, 0xbfb8aa3b, v45
	v_exp_f32_e32 v135, v135
	v_mul_f32_e32 v139, 0xbfb8aa3b, v47
	v_add_f32_e32 v134, 1.0, v134
	v_rcp_f32_e32 v138, v134
	v_add_f32_e32 v134, 1.0, v135
	v_mul_f32_e32 v135, 0xbfb8aa3b, v46
	v_exp_f32_e32 v135, v135
	v_exp_f32_e32 v139, v139
	v_rcp_f32_e32 v140, v134
	v_add_u32_e32 v137, 0x90, v128
	v_add_f32_e32 v134, 1.0, v135
	v_mul_f32_e32 v135, 0xbfb8aa3b, v40
	v_rcp_f32_e32 v141, v134
	v_add_f32_e32 v134, 1.0, v139
	v_exp_f32_e32 v135, v135
	v_mul_f32_e32 v139, 0xbfb8aa3b, v41
	v_exp_f32_e32 v139, v139
	v_rcp_f32_e32 v142, v134
	v_add_f32_e32 v134, 1.0, v135
	v_mul_f32_e32 v135, 0xbfb8aa3b, v42
	v_rcp_f32_e32 v143, v134
	v_add_f32_e32 v134, 1.0, v139
	v_exp_f32_e32 v135, v135
	v_mul_f32_e32 v139, 0xbfb8aa3b, v43
	v_exp_f32_e32 v139, v139
	v_rcp_f32_e32 v144, v134
	v_add_f32_e32 v134, 1.0, v135
	v_rcp_f32_e32 v145, v134
	v_add_f32_e32 v134, 1.0, v139
	v_rcp_f32_e32 v146, v134
	v_mad_u64_u32 v[134:135], s[40:41], v137, s71, v[130:131]
	v_cvt_pk_bf16_f32 v139, v141, v142
	v_mul_f32_e32 v142, 0xbfb8aa3b, v37
	v_lshl_add_u64 v[134:135], v[134:135], 0, s[4:5]
	v_exp_f32_e32 v142, v142
	v_lshl_add_u64 v[134:135], v[134:135], 0, v[132:133]
	v_cvt_pk_bf16_f32 v138, v138, v140
	v_cvt_pk_bf16_f32 v140, v143, v144
	v_cvt_pk_bf16_f32 v141, v145, v146
	v_add_co_u32_e32 v134, vcc, s72, v134
	v_permlane16_swap_b32_e32 v138, v140
	v_permlane16_swap_b32_e32 v139, v141
	v_addc_co_u32_e32 v135, vcc, 0, v135, vcc
	v_mul_f32_e32 v137, 0xbfb8aa3b, v36
	global_store_dwordx4 v[134:135], v[138:141], off nt
	v_mul_f32_e32 v143, 0xbfb8aa3b, v34
	v_mul_f32_e32 v144, 0xbfb8aa3b, v35
	v_add_f32_e32 v138, 1.0, v142
	v_mul_f32_e32 v139, 0xbfb8aa3b, v38
	v_mul_f32_e32 v140, 0xbfb8aa3b, v39
	v_mul_f32_e32 v141, 0xbfb8aa3b, v32
	v_mul_f32_e32 v142, 0xbfb8aa3b, v33
	v_exp_f32_e32 v137, v137
	v_exp_f32_e32 v139, v139
	v_exp_f32_e32 v140, v140
	v_exp_f32_e32 v141, v141
	v_exp_f32_e32 v142, v142
	v_exp_f32_e32 v143, v143
	v_exp_f32_e32 v144, v144
	v_add_f32_e32 v137, 1.0, v137
	v_add_f32_e32 v139, 1.0, v139
	v_add_f32_e32 v140, 1.0, v140
	v_add_f32_e32 v141, 1.0, v141
	v_add_f32_e32 v142, 1.0, v142
	v_add_f32_e32 v143, 1.0, v143
	v_add_f32_e32 v144, 1.0, v144
	v_rcp_f32_e32 v137, v137
	v_rcp_f32_e32 v138, v138
; __device__ __forceinline__ u32x2 pack4(f32x4 v) { u32x2 r; r.x = cvt_pk(v[0], v[1]); r.y = cvt_pk(v[2], v[3]); return r; }
; __device__ __forceinline__ float sigm_f(float x) { return __builtin_amdgcn_rcpf(1.f + __builtin_amdgcn_exp2f(-1.4426950409f * x)); }
; __device__ __forceinline__ void store_pair16(u16* rowp32, u32x2 a, u32x2 b, int fq) {
;   auto rx = __builtin_amdgcn_permlane16_swap(a.x, b.x, false, false);
;   auto ry = __builtin_amdgcn_permlane16_swap(a.y, b.y, false, false);
;   u32x4 w = {rx[0], ry[0], rx[1], ry[1]};
;   *(u32x4*)(rowp32 + ((fq & 1) * 16 + (fq >> 1) * 8)) = w;
; }
; template <int SEC> __device__ __forceinline__ void epiB2(const Params& p, int row, int col32, f32x4 v0, f32x4 v1, int fq) {
;     ...
;   else { f32x4 o0 = {sigm_f(v0[0]), sigm_f(v0[1]), sigm_f(v0[2]), sigm_f(v0[3])}, o1 = {sigm_f(v1[0]), sigm_f(v1[1]), sigm_f(v1[2]), sigm_f(v1[3])};
;     store_pair16((u16*)(ws + OFF_GATE) + (size_t)row * 3072 + (col32 - 4096), pack4(o0), pack4(o1), fq); }
	v_rcp_f32_e32 v139, v139
	v_rcp_f32_e32 v140, v140
	v_rcp_f32_e32 v141, v141
	v_rcp_f32_e32 v142, v142
	v_rcp_f32_e32 v143, v143
	v_rcp_f32_e32 v144, v144
	v_cvt_pk_bf16_f32 v138, v137, v138
	v_cvt_pk_bf16_f32 v139, v139, v140
	v_cvt_pk_bf16_f32 v140, v141, v142
	v_cvt_pk_bf16_f32 v141, v143, v144
	s_nop 0
	v_permlane16_swap_b32_e32 v138, v140
	v_permlane16_swap_b32_e32 v139, v141
	global_store_dwordx4 v[134:135], v[138:141], off offset:256 nt
	v_mul_f32_e32 v134, 0xbfb8aa3b, v28
	v_exp_f32_e32 v134, v134
	v_mul_f32_e32 v135, 0xbfb8aa3b, v29
	v_exp_f32_e32 v135, v135
	v_mul_f32_e32 v139, 0xbfb8aa3b, v31
	v_add_f32_e32 v134, 1.0, v134
	v_rcp_f32_e32 v138, v134
	v_add_f32_e32 v134, 1.0, v135
	v_mul_f32_e32 v135, 0xbfb8aa3b, v30
	v_exp_f32_e32 v135, v135
	v_exp_f32_e32 v139, v139
	v_rcp_f32_e32 v140, v134
	v_add_u32_e32 v137, 0xa0, v128
	v_add_f32_e32 v134, 1.0, v135
	v_mul_f32_e32 v135, 0xbfb8aa3b, v24
	v_rcp_f32_e32 v141, v134
	v_add_f32_e32 v134, 1.0, v139
	v_exp_f32_e32 v135, v135
	v_mul_f32_e32 v139, 0xbfb8aa3b, v25
	v_exp_f32_e32 v139, v139
	v_rcp_f32_e32 v142, v134
	v_add_f32_e32 v134, 1.0, v135
	v_mul_f32_e32 v135, 0xbfb8aa3b, v26
	v_rcp_f32_e32 v143, v134
	v_add_f32_e32 v134, 1.0, v139
	v_exp_f32_e32 v135, v135
	v_mul_f32_e32 v139, 0xbfb8aa3b, v27
	v_exp_f32_e32 v139, v139
	v_rcp_f32_e32 v144, v134
	v_add_f32_e32 v134, 1.0, v135
	v_rcp_f32_e32 v145, v134
	v_add_f32_e32 v134, 1.0, v139
	v_rcp_f32_e32 v146, v134
	v_mad_u64_u32 v[134:135], s[40:41], v137, s71, v[130:131]
	v_cvt_pk_bf16_f32 v139, v141, v142
	v_mul_f32_e32 v142, 0xbfb8aa3b, v21
	v_lshl_add_u64 v[134:135], v[134:135], 0, s[4:5]
	v_exp_f32_e32 v142, v142
	v_lshl_add_u64 v[134:135], v[134:135], 0, v[132:133]
	v_cvt_pk_bf16_f32 v138, v138, v140
	v_cvt_pk_bf16_f32 v140, v143, v144
	v_cvt_pk_bf16_f32 v141, v145, v146
	v_add_co_u32_e32 v134, vcc, s72, v134
	v_permlane16_swap_b32_e32 v138, v140
	v_permlane16_swap_b32_e32 v139, v141
	v_addc_co_u32_e32 v135, vcc, 0, v135, vcc
	v_mul_f32_e32 v137, 0xbfb8aa3b, v20
	global_store_dwordx4 v[134:135], v[138:141], off nt
	v_mul_f32_e32 v143, 0xbfb8aa3b, v18
	v_mul_f32_e32 v144, 0xbfb8aa3b, v19
	v_add_f32_e32 v138, 1.0, v142
	v_mul_f32_e32 v139, 0xbfb8aa3b, v22
	v_mul_f32_e32 v140, 0xbfb8aa3b, v23
	v_mul_f32_e32 v141, 0xbfb8aa3b, v16
	v_mul_f32_e32 v142, 0xbfb8aa3b, v17
	v_exp_f32_e32 v137, v137
	v_exp_f32_e32 v139, v139
	v_exp_f32_e32 v140, v140
	v_exp_f32_e32 v141, v141
	v_exp_f32_e32 v142, v142
	v_exp_f32_e32 v143, v143
	v_exp_f32_e32 v144, v144
	v_add_f32_e32 v137, 1.0, v137
	v_add_f32_e32 v139, 1.0, v139
	v_add_f32_e32 v140, 1.0, v140
	v_add_f32_e32 v141, 1.0, v141
	v_add_f32_e32 v142, 1.0, v142
	v_add_f32_e32 v143, 1.0, v143
	v_add_f32_e32 v144, 1.0, v144
	v_rcp_f32_e32 v137, v137
	v_rcp_f32_e32 v138, v138
	v_rcp_f32_e32 v139, v139
	v_rcp_f32_e32 v140, v140
	v_rcp_f32_e32 v141, v141
	v_rcp_f32_e32 v142, v142
	v_rcp_f32_e32 v143, v143
	v_rcp_f32_e32 v144, v144
	v_cvt_pk_bf16_f32 v138, v137, v138
	v_cvt_pk_bf16_f32 v139, v139, v140
	v_cvt_pk_bf16_f32 v140, v141, v142
	v_cvt_pk_bf16_f32 v141, v143, v144
	s_nop 0
	v_permlane16_swap_b32_e32 v138, v140
	v_permlane16_swap_b32_e32 v139, v141
	global_store_dwordx4 v[134:135], v[138:141], off offset:256 nt
	v_mul_f32_e32 v134, 0xbfb8aa3b, v12
	v_mul_f32_e32 v135, 0xbfb8aa3b, v13
	v_mul_f32_e32 v138, 0xbfb8aa3b, v15
	v_exp_f32_e32 v138, v138
	v_mul_f32_e32 v139, 0xbfb8aa3b, v8
	v_exp_f32_e32 v139, v139
	v_mul_f32_e32 v140, 0xbfb8aa3b, v9
	v_exp_f32_e32 v140, v140
	v_add_f32_e32 v138, 1.0, v138
	v_rcp_f32_e32 v141, v138
	v_add_f32_e32 v138, 1.0, v139
	v_mul_f32_e32 v139, 0xbfb8aa3b, v10
	v_mul_f32_e32 v137, 0xbfb8aa3b, v14
	v_rcp_f32_e32 v142, v138
	v_add_f32_e32 v138, 1.0, v140
	v_exp_f32_e32 v139, v139
	v_mul_f32_e32 v140, 0xbfb8aa3b, v11
	v_exp_f32_e32 v134, v134
	v_exp_f32_e32 v135, v135
	v_exp_f32_e32 v137, v137
	v_exp_f32_e32 v140, v140
	v_rcp_f32_e32 v143, v138
	v_add_f32_e32 v138, 1.0, v139
	v_add_f32_e32 v134, 1.0, v134
	v_add_f32_e32 v135, 1.0, v135
	v_add_f32_e32 v137, 1.0, v137
	v_rcp_f32_e32 v144, v138
	v_add_f32_e32 v138, 1.0, v140
	v_add_u32_e32 v128, 0xb0, v128
	v_rcp_f32_e32 v134, v134
	v_rcp_f32_e32 v135, v135
	v_rcp_f32_e32 v137, v137
	v_rcp_f32_e32 v145, v138
	v_mad_u64_u32 v[130:131], s[40:41], v128, s71, v[130:131]
	v_lshl_add_u64 v[130:131], v[130:131], 0, s[4:5]
	v_lshl_add_u64 v[130:131], v[130:131], 0, v[132:133]
	v_cvt_pk_bf16_f32 v138, v134, v135
	v_cvt_pk_bf16_f32 v139, v137, v141
	v_cvt_pk_bf16_f32 v140, v142, v143
	v_cvt_pk_bf16_f32 v141, v144, v145
	v_add_co_u32_e32 v134, vcc, s72, v130
	v_permlane16_swap_b32_e32 v138, v140
	v_permlane16_swap_b32_e32 v139, v141
	v_addc_co_u32_e32 v135, vcc, 0, v131, vcc
	v_mul_f32_e32 v128, 0xbfb8aa3b, v4
	v_mul_f32_e32 v130, 0xbfb8aa3b, v5
	global_store_dwordx4 v[134:135], v[138:141], off nt
	v_mul_f32_e32 v131, 0xbfb8aa3b, v6
	v_mul_f32_e32 v132, 0xbfb8aa3b, v7
	v_mul_f32_e32 v133, 0xbfb8aa3b, v0
	v_mul_f32_e32 v137, 0xbfb8aa3b, v1
	v_mul_f32_e32 v138, 0xbfb8aa3b, v2
	v_mul_f32_e32 v139, 0xbfb8aa3b, v3
	v_exp_f32_e32 v128, v128
	v_exp_f32_e32 v130, v130
	v_exp_f32_e32 v131, v131
	v_exp_f32_e32 v132, v132
	v_exp_f32_e32 v133, v133
	v_exp_f32_e32 v137, v137
	v_exp_f32_e32 v138, v138
	v_exp_f32_e32 v139, v139
	v_add_f32_e32 v128, 1.0, v128
	v_add_f32_e32 v130, 1.0, v130
	v_add_f32_e32 v131, 1.0, v131
	v_add_f32_e32 v132, 1.0, v132
	v_add_f32_e32 v133, 1.0, v133
	v_add_f32_e32 v137, 1.0, v137
	v_add_f32_e32 v138, 1.0, v138
	v_add_f32_e32 v139, 1.0, v139
	v_rcp_f32_e32 v128, v128
	v_rcp_f32_e32 v130, v130
	v_rcp_f32_e32 v131, v131
	v_rcp_f32_e32 v132, v132
	v_rcp_f32_e32 v133, v133
	v_rcp_f32_e32 v137, v137
	v_rcp_f32_e32 v138, v138
	v_rcp_f32_e32 v139, v139
	v_cvt_pk_bf16_f32 v130, v128, v130
	v_cvt_pk_bf16_f32 v131, v131, v132
	v_cvt_pk_bf16_f32 v132, v133, v137
	v_cvt_pk_bf16_f32 v133, v138, v139
	s_nop 0
	v_permlane16_swap_b32_e32 v130, v132
	v_permlane16_swap_b32_e32 v131, v133
	global_store_dwordx4 v[134:135], v[130:133], off offset:256 nt
	s_mov_b64 s[4:5], 0
; __device__ __forceinline__ u32x2 pack4(f32x4 v) { u32x2 r; r.x = cvt_pk(v[0], v[1]); r.y = cvt_pk(v[2], v[3]); return r; }
; __device__ __forceinline__ void store_pair16(u16* rowp32, u32x2 a, u32x2 b, int fq) {
;   auto rx = __builtin_amdgcn_permlane16_swap(a.x, b.x, false, false);
;   auto ry = __builtin_amdgcn_permlane16_swap(a.y, b.y, false, false);
;   u32x4 w = {rx[0], ry[0], rx[1], ry[1]};
;   *(u32x4*)(rowp32 + ((fq & 1) * 16 + (fq >> 1) * 8)) = w;
; }
; template <int SEC> __device__ __forceinline__ void epiB2(const Params& p, int row, int col32, f32x4 v0, f32x4 v1, int fq) {
;     ...
;   else if (SEC == 3) { store_pair16((u16*)((char*)p.out + OOFF_Q) + (size_t)row * 512 + (col32 - 3584), pack4(v0), pack4(v1), fq); }
.LBB0_202:
	s_andn2_b64 vcc, exec, s[4:5]
	s_cbranch_vccnz .LBB0_204
	v_mbcnt_lo_u32_b32 v130, -1, 0
	v_mbcnt_hi_u32_b32 v130, -1, v130
	s_or_b32 s4, s38, s66
	v_and_or_b32 v128, v130, 15, s33
	v_and_b32_e32 v131, 16, v130
	v_ashrrev_i32_e32 v130, 2, v130
	v_and_b32_e32 v130, -8, v130
	v_add_u32_e32 v130, v130, v131
	v_lshlrev_b64 v[132:133], 10, v[128:129]
	s_ashr_i32 s5, s4, 31
	v_ashrrev_i32_e32 v131, 31, v130
	v_lshl_add_u64 v[132:133], s[48:49], 0, v[132:133]
	s_lshl_b64 s[4:5], s[4:5], 1
	v_lshl_add_u64 v[138:139], v[132:133], 0, s[4:5]
	v_lshlrev_b64 v[130:131], 1, v[130:131]
	v_lshl_add_u64 v[138:139], v[138:139], 0, v[130:131]
	v_cvt_pk_bf16_f32 v132, v124, v125
	v_cvt_pk_bf16_f32 v133, v126, v127
	v_cvt_pk_bf16_f32 v134, v120, v121
	v_cvt_pk_bf16_f32 v135, v122, v123
	v_add_co_u32_e32 v138, vcc, s73, v138
	v_permlane16_swap_b32_e32 v132, v134
	v_permlane16_swap_b32_e32 v133, v135
	v_addc_co_u32_e32 v139, vcc, 0, v139, vcc
	global_store_dwordx4 v[138:139], v[132:135], off offset:1024 nt
	s_nop 1
	v_cvt_pk_bf16_f32 v132, v116, v117
	v_cvt_pk_bf16_f32 v133, v118, v119
	v_cvt_pk_bf16_f32 v134, v112, v113
	v_cvt_pk_bf16_f32 v135, v114, v115
	s_nop 0
	v_permlane16_swap_b32_e32 v132, v134
	v_permlane16_swap_b32_e32 v133, v135
	global_store_dwordx4 v[138:139], v[132:135], off offset:1280 nt
	s_nop 1
	v_or_b32_e32 v132, 16, v128
	v_mov_b32_e32 v133, v129
	v_lshlrev_b64 v[132:133], 10, v[132:133]
	v_lshl_add_u64 v[132:133], s[48:49], 0, v[132:133]
	v_lshl_add_u64 v[138:139], v[132:133], 0, s[4:5]
	v_lshl_add_u64 v[138:139], v[138:139], 0, v[130:131]
	v_cvt_pk_bf16_f32 v132, v108, v109
	v_cvt_pk_bf16_f32 v133, v110, v111
	v_cvt_pk_bf16_f32 v134, v104, v105
	v_cvt_pk_bf16_f32 v135, v106, v107
	v_add_co_u32_e32 v138, vcc, s73, v138
	v_permlane16_swap_b32_e32 v132, v134
	v_permlane16_swap_b32_e32 v133, v135
	v_addc_co_u32_e32 v139, vcc, 0, v139, vcc
	global_store_dwordx4 v[138:139], v[132:135], off offset:1024 nt
	s_nop 1
	v_cvt_pk_bf16_f32 v132, v100, v101
	v_cvt_pk_bf16_f32 v133, v102, v103
	v_cvt_pk_bf16_f32 v134, v96, v97
	v_cvt_pk_bf16_f32 v135, v98, v99
	s_nop 0
	v_permlane16_swap_b32_e32 v132, v134
	v_permlane16_swap_b32_e32 v133, v135
	global_store_dwordx4 v[138:139], v[132:135], off offset:1280 nt
	s_nop 1
	v_or_b32_e32 v132, 32, v128
	v_mov_b32_e32 v133, v129
	v_lshlrev_b64 v[132:133], 10, v[132:133]
	v_lshl_add_u64 v[132:133], s[48:49], 0, v[132:133]
	v_lshl_add_u64 v[138:139], v[132:133], 0, s[4:5]
	v_lshl_add_u64 v[138:139], v[138:139], 0, v[130:131]
	v_cvt_pk_bf16_f32 v132, v92, v93
	v_cvt_pk_bf16_f32 v133, v94, v95
	v_cvt_pk_bf16_f32 v134, v88, v89
	v_cvt_pk_bf16_f32 v135, v90, v91
	v_add_co_u32_e32 v138, vcc, s73, v138
	v_permlane16_swap_b32_e32 v132, v134
	v_permlane16_swap_b32_e32 v133, v135
	v_addc_co_u32_e32 v139, vcc, 0, v139, vcc
	global_store_dwordx4 v[138:139], v[132:135], off offset:1024 nt
	s_nop 1
	v_cvt_pk_bf16_f32 v132, v84, v85
	v_cvt_pk_bf16_f32 v133, v86, v87
	v_cvt_pk_bf16_f32 v134, v80, v81
	v_cvt_pk_bf16_f32 v135, v82, v83
	s_nop 0
	v_permlane16_swap_b32_e32 v132, v134
	v_permlane16_swap_b32_e32 v133, v135
	global_store_dwordx4 v[138:139], v[132:135], off offset:1280 nt
	s_nop 1
	v_or_b32_e32 v132, 48, v128
	v_mov_b32_e32 v133, v129
	v_lshlrev_b64 v[132:133], 10, v[132:133]
	v_lshl_add_u64 v[132:133], s[48:49], 0, v[132:133]
	v_lshl_add_u64 v[138:139], v[132:133], 0, s[4:5]
	v_lshl_add_u64 v[138:139], v[138:139], 0, v[130:131]
	v_cvt_pk_bf16_f32 v132, v76, v77
	v_cvt_pk_bf16_f32 v133, v78, v79
	v_cvt_pk_bf16_f32 v134, v72, v73
	v_cvt_pk_bf16_f32 v135, v74, v75
	v_add_co_u32_e32 v138, vcc, s73, v138
	v_permlane16_swap_b32_e32 v132, v134
	v_permlane16_swap_b32_e32 v133, v135
	v_addc_co_u32_e32 v139, vcc, 0, v139, vcc
	global_store_dwordx4 v[138:139], v[132:135], off offset:1024 nt
	s_nop 1
	v_cvt_pk_bf16_f32 v132, v68, v69
	v_cvt_pk_bf16_f32 v133, v70, v71
; __device__ __forceinline__ u32x2 pack4(f32x4 v) { u32x2 r; r.x = cvt_pk(v[0], v[1]); r.y = cvt_pk(v[2], v[3]); return r; }
; __device__ __forceinline__ void store_pair16(u16* rowp32, u32x2 a, u32x2 b, int fq) {
;   auto rx = __builtin_amdgcn_permlane16_swap(a.x, b.x, false, false);
;   auto ry = __builtin_amdgcn_permlane16_swap(a.y, b.y, false, false);
;   u32x4 w = {rx[0], ry[0], rx[1], ry[1]};
;   *(u32x4*)(rowp32 + ((fq & 1) * 16 + (fq >> 1) * 8)) = w;
; }
; template <int SEC> __device__ __forceinline__ void epiB2(const Params& p, int row, int col32, f32x4 v0, f32x4 v1, int fq) {
;     ...
;   else if (SEC == 3) { store_pair16((u16*)((char*)p.out + OOFF_Q) + (size_t)row * 512 + (col32 - 3584), pack4(v0), pack4(v1), fq); }
	v_cvt_pk_bf16_f32 v134, v64, v65
	v_cvt_pk_bf16_f32 v135, v66, v67
	s_nop 0
	v_permlane16_swap_b32_e32 v132, v134
	v_permlane16_swap_b32_e32 v133, v135
	global_store_dwordx4 v[138:139], v[132:135], off offset:1280 nt
	s_nop 1
	v_add_u32_e32 v132, 0x80, v128
	v_mov_b32_e32 v133, v129
	v_lshlrev_b64 v[132:133], 10, v[132:133]
	v_lshl_add_u64 v[132:133], s[48:49], 0, v[132:133]
	v_lshl_add_u64 v[138:139], v[132:133], 0, s[4:5]
	v_lshl_add_u64 v[138:139], v[138:139], 0, v[130:131]
	v_cvt_pk_bf16_f32 v132, v60, v61
	v_cvt_pk_bf16_f32 v133, v62, v63
	v_cvt_pk_bf16_f32 v134, v56, v57
	v_cvt_pk_bf16_f32 v135, v58, v59
	v_add_co_u32_e32 v138, vcc, s73, v138
	v_permlane16_swap_b32_e32 v132, v134
	v_permlane16_swap_b32_e32 v133, v135
	v_addc_co_u32_e32 v139, vcc, 0, v139, vcc
	global_store_dwordx4 v[138:139], v[132:135], off offset:1024 nt
	s_nop 1
	v_cvt_pk_bf16_f32 v132, v52, v53
	v_cvt_pk_bf16_f32 v133, v54, v55
	v_cvt_pk_bf16_f32 v134, v48, v49
	v_cvt_pk_bf16_f32 v135, v50, v51
	s_nop 0
	v_permlane16_swap_b32_e32 v132, v134
	v_permlane16_swap_b32_e32 v133, v135
	global_store_dwordx4 v[138:139], v[132:135], off offset:1280 nt
	s_nop 1
	v_add_u32_e32 v132, 0x90, v128
	v_mov_b32_e32 v133, v129
	v_lshlrev_b64 v[132:133], 10, v[132:133]
	v_lshl_add_u64 v[132:133], s[48:49], 0, v[132:133]
	v_lshl_add_u64 v[138:139], v[132:133], 0, s[4:5]
	v_lshl_add_u64 v[138:139], v[138:139], 0, v[130:131]
	v_cvt_pk_bf16_f32 v132, v44, v45
	v_cvt_pk_bf16_f32 v133, v46, v47
	v_cvt_pk_bf16_f32 v134, v40, v41
	v_cvt_pk_bf16_f32 v135, v42, v43
	v_add_co_u32_e32 v138, vcc, s73, v138
	v_permlane16_swap_b32_e32 v132, v134
	v_permlane16_swap_b32_e32 v133, v135
	v_addc_co_u32_e32 v139, vcc, 0, v139, vcc
	global_store_dwordx4 v[138:139], v[132:135], off offset:1024 nt
	s_nop 1
	v_cvt_pk_bf16_f32 v132, v36, v37
	v_cvt_pk_bf16_f32 v133, v38, v39
	v_cvt_pk_bf16_f32 v134, v32, v33
	v_cvt_pk_bf16_f32 v135, v34, v35
	s_nop 0
	v_permlane16_swap_b32_e32 v132, v134
	v_permlane16_swap_b32_e32 v133, v135
	global_store_dwordx4 v[138:139], v[132:135], off offset:1280 nt
	s_nop 1
	v_add_u32_e32 v132, 0xa0, v128
	v_mov_b32_e32 v133, v129
	v_lshlrev_b64 v[132:133], 10, v[132:133]
	v_lshl_add_u64 v[132:133], s[48:49], 0, v[132:133]
	v_lshl_add_u64 v[138:139], v[132:133], 0, s[4:5]
	v_lshl_add_u64 v[138:139], v[138:139], 0, v[130:131]
	v_cvt_pk_bf16_f32 v132, v28, v29
	v_cvt_pk_bf16_f32 v133, v30, v31
	v_cvt_pk_bf16_f32 v134, v24, v25
	v_cvt_pk_bf16_f32 v135, v26, v27
	v_add_co_u32_e32 v138, vcc, s73, v138
	v_permlane16_swap_b32_e32 v132, v134
	v_permlane16_swap_b32_e32 v133, v135
	v_addc_co_u32_e32 v139, vcc, 0, v139, vcc
	global_store_dwordx4 v[138:139], v[132:135], off offset:1024 nt
	v_add_u32_e32 v128, 0xb0, v128
	s_nop 0
	v_cvt_pk_bf16_f32 v132, v20, v21
	v_cvt_pk_bf16_f32 v133, v22, v23
	v_cvt_pk_bf16_f32 v134, v16, v17
	v_cvt_pk_bf16_f32 v135, v18, v19
	s_nop 0
	v_permlane16_swap_b32_e32 v132, v134
	v_permlane16_swap_b32_e32 v133, v135
	global_store_dwordx4 v[138:139], v[132:135], off offset:1280 nt
	s_nop 1
	v_lshlrev_b64 v[132:133], 10, v[128:129]
	v_lshl_add_u64 v[132:133], s[48:49], 0, v[132:133]
	v_lshl_add_u64 v[138:139], v[132:133], 0, s[4:5]
	v_lshl_add_u64 v[130:131], v[138:139], 0, v[130:131]
	v_cvt_pk_bf16_f32 v132, v12, v13
	v_cvt_pk_bf16_f32 v133, v14, v15
	v_cvt_pk_bf16_f32 v134, v8, v9
	v_cvt_pk_bf16_f32 v135, v10, v11
	v_add_co_u32_e32 v138, vcc, s73, v130
	v_permlane16_swap_b32_e32 v132, v134
	v_permlane16_swap_b32_e32 v133, v135
	v_addc_co_u32_e32 v139, vcc, 0, v131, vcc
	global_store_dwordx4 v[138:139], v[132:135], off offset:1024 nt
	v_cvt_pk_bf16_f32 v130, v4, v5
	v_cvt_pk_bf16_f32 v131, v6, v7
	v_cvt_pk_bf16_f32 v132, v0, v1
	v_cvt_pk_bf16_f32 v133, v2, v3
	s_nop 0
	v_permlane16_swap_b32_e32 v130, v132
	v_permlane16_swap_b32_e32 v131, v133
	global_store_dwordx4 v[138:139], v[130:133], off offset:1280 nt

; __device__ __forceinline__ u32x2 pack4(f32x4 v) { u32x2 r; r.x = cvt_pk(v[0], v[1]); r.y = cvt_pk(v[2], v[3]); return r; }
; __device__ __forceinline__ void store_pair16(u16* rowp32, u32x2 a, u32x2 b, int fq) {
;   auto rx = __builtin_amdgcn_permlane16_swap(a.x, b.x, false, false);
;   auto ry = __builtin_amdgcn_permlane16_swap(a.y, b.y, false, false);
;   u32x4 w = {rx[0], ry[0], rx[1], ry[1]};
;   *(u32x4*)(rowp32 + ((fq & 1) * 16 + (fq >> 1) * 8)) = w;
; }
; template <int SEC> __device__ __forceinline__ void epiB2(const Params& p, int row, int col32, f32x4 v0, f32x4 v1, int fq) {
;     ...
;   else if (SEC == 2) {
;     const int c32 = col32 - 2048;
;     store_pair16((u16*)(ws + OFF_XBC) + (size_t)row * 1536 + c32, pack4(v0), pack4(v1), fq);
;     const int pos = row & 2047;
;     if (pos >= 2045) {
;       float* cp = p.out + O_CONVP + (size_t)(row >> 11) * 4608 + (pos - 2045) * 1536 + c32 + fq * 4;
;       *(f32x4*)cp = v0; *(f32x4*)(cp + 16) = v1;
;     }
;   }
.LBB0_205:
	s_andn2_b64 vcc, exec, s[4:5]
	s_cbranch_vccnz .LBB0_215
	v_mbcnt_lo_u32_b32 v128, -1, 0
	v_mbcnt_hi_u32_b32 v128, -1, v128
	s_add_i32 s40, s38, s67
	v_and_or_b32 v137, v128, 15, s33
	v_and_b32_e32 v130, 16, v128
	v_ashrrev_i32_e32 v128, 2, v128
	v_and_b32_e32 v131, -8, v128
	v_add_u32_e32 v132, v131, v130
	v_mov_b64_e32 v[134:135], s[8:9]
	s_ashr_i32 s41, s40, 31
	v_ashrrev_i32_e32 v133, 31, v132
	v_mad_u64_u32 v[138:139], s[4:5], v137, s74, v[134:135]
	s_lshl_b64 s[42:43], s[40:41], 1
	v_lshl_add_u64 v[142:143], v[138:139], 0, s[42:43]
	v_cvt_pk_bf16_f32 v138, v124, v125
	v_cvt_pk_bf16_f32 v139, v126, v127
	v_cvt_pk_bf16_f32 v140, v120, v121
	v_cvt_pk_bf16_f32 v141, v122, v123
	v_lshlrev_b64 v[132:133], 1, v[132:133]
	v_permlane16_swap_b32_e32 v138, v140
	v_permlane16_swap_b32_e32 v139, v141
	v_lshl_add_u64 v[142:143], v[142:143], 0, v[132:133]
	global_store_dwordx4 v[142:143], v[138:141], off nt
	v_and_b32_e32 v130, -4, v128
	v_or_b32_e32 v128, 16, v137
	v_cvt_pk_bf16_f32 v138, v116, v117
	v_cvt_pk_bf16_f32 v139, v118, v119
	v_cvt_pk_bf16_f32 v140, v112, v113
	v_cvt_pk_bf16_f32 v141, v114, v115
	s_nop 0
	v_permlane16_swap_b32_e32 v138, v140
	v_permlane16_swap_b32_e32 v139, v141
	global_store_dwordx4 v[142:143], v[138:141], off offset:256 nt
	s_lshr_b32 s80, s33, 11
	v_ashrrev_i32_e32 v131, 31, v130
	v_mad_u64_u32 v[138:139], s[4:5], v128, s74, v[134:135]
	v_lshl_add_u64 v[142:143], v[138:139], 0, s[42:43]
	v_cvt_pk_bf16_f32 v138, v108, v109
	v_cvt_pk_bf16_f32 v139, v110, v111
	v_cvt_pk_bf16_f32 v140, v104, v105
	v_cvt_pk_bf16_f32 v141, v106, v107
	s_nop 0
	v_permlane16_swap_b32_e32 v138, v140
	v_permlane16_swap_b32_e32 v139, v141
	v_lshl_add_u64 v[142:143], v[142:143], 0, v[132:133]
	global_store_dwordx4 v[142:143], v[138:141], off nt
	v_or_b32_e32 v128, 32, v137
	s_mul_hi_u32 s79, s80, 0x4800
	v_cvt_pk_bf16_f32 v138, v100, v101
	v_cvt_pk_bf16_f32 v139, v102, v103
	v_cvt_pk_bf16_f32 v140, v96, v97
	v_cvt_pk_bf16_f32 v141, v98, v99
	s_nop 0
	v_permlane16_swap_b32_e32 v138, v140
	v_permlane16_swap_b32_e32 v139, v141
	global_store_dwordx4 v[142:143], v[138:141], off offset:256 nt
	s_mulk_i32 s80, 0x4800
	s_nop 0
	v_mad_u64_u32 v[138:139], s[4:5], v128, s74, v[134:135]
	v_lshl_add_u64 v[142:143], v[138:139], 0, s[42:43]
	v_cvt_pk_bf16_f32 v138, v92, v93
	v_cvt_pk_bf16_f32 v139, v94, v95
	v_cvt_pk_bf16_f32 v140, v88, v89
	v_cvt_pk_bf16_f32 v141, v90, v91
	s_nop 0
	v_permlane16_swap_b32_e32 v138, v140
	v_permlane16_swap_b32_e32 v139, v141
	v_lshl_add_u64 v[142:143], v[142:143], 0, v[132:133]
	global_store_dwordx4 v[142:143], v[138:141], off nt
	v_or_b32_e32 v128, 48, v137
	s_movk_i32 s4, 0x7ff
	v_cvt_pk_bf16_f32 v138, v84, v85
	v_cvt_pk_bf16_f32 v139, v86, v87
	v_cvt_pk_bf16_f32 v140, v80, v81
	v_cvt_pk_bf16_f32 v141, v82, v83
	s_nop 0
	v_permlane16_swap_b32_e32 v138, v140
	v_permlane16_swap_b32_e32 v139, v141
	global_store_dwordx4 v[142:143], v[138:141], off offset:256 nt
	v_mad_u64_u32 v[134:135], s[44:45], v128, s74, v[134:135]
	s_nop 0
	v_bitop3_b32 v138, v137, s4, 48 bitop3:0xc8
	v_cmp_lt_u32_e64 s[4:5], s75, v138
	v_mul_u32_u24_e32 v142, 0x600, v138
	v_lshl_add_u64 v[134:135], v[134:135], 0, s[42:43]
	v_cvt_pk_bf16_f32 v138, v76, v77
	v_cvt_pk_bf16_f32 v139, v78, v79
	v_cvt_pk_bf16_f32 v140, v72, v73
	v_cvt_pk_bf16_f32 v141, v74, v75
	s_nop 0
	v_permlane16_swap_b32_e32 v138, v140
	v_permlane16_swap_b32_e32 v139, v141
	v_lshl_add_u64 v[134:135], v[134:135], 0, v[132:133]
	v_lshlrev_b32_e32 v128, 2, v142
	global_store_dwordx4 v[134:135], v[138:141], off nt
	s_and_saveexec_b64 s[44:45], s[4:5]
	s_cbranch_execz .LBB0_208
	s_add_u32 s52, s48, s80
	s_addc_u32 s53, s49, s79
	v_lshl_add_u64 v[138:139], s[52:53], 0, v[128:129]
	v_lshl_add_u64 v[138:139], s[40:41], 2, v[138:139]
	v_lshl_add_u64 v[138:139], v[130:131], 2, v[138:139]
	v_lshl_add_u64 v[140:141], v[138:139], 0, s[24:25]
	v_add_co_u32_e32 v138, vcc, 0x3c84000, v138
	s_nop 1
	v_addc_co_u32_e32 v139, vcc, 0, v139, vcc
	global_store_dwordx4 v[138:139], v[76:79], off offset:2048 nt
	global_store_dwordx4 v[140:141], v[72:75], off offset:64 nt
.LBB0_208:
	s_or_b64 exec, exec, s[44:45]
	s_or_b32 s44, s40, 0x80
	v_cvt_pk_bf16_f32 v138, v68, v69
	v_cvt_pk_bf16_f32 v139, v70, v71
	v_cvt_pk_bf16_f32 v140, v64, v65
	v_cvt_pk_bf16_f32 v141, v66, v67
	s_ashr_i32 s45, s44, 31
	v_permlane16_swap_b32_e32 v138, v140
	v_permlane16_swap_b32_e32 v139, v141
	global_store_dwordx4 v[134:135], v[138:141], off offset:256 nt
	s_and_saveexec_b64 s[52:53], s[4:5]
	s_cbranch_execz .LBB0_210
	s_add_u32 s4, s48, s80
	s_addc_u32 s5, s49, s79
	v_lshl_add_u64 v[134:135], s[4:5], 0, v[128:129]
	v_lshl_add_u64 v[134:135], v[130:131], 2, v[134:135]
	v_lshl_add_u64 v[134:135], s[44:45], 2, v[134:135]
	v_lshl_add_u64 v[138:139], v[134:135], 0, s[24:25]
	v_add_co_u32_e32 v134, vcc, 0x3c84000, v134
	s_nop 1
	v_addc_co_u32_e32 v135, vcc, 0, v135, vcc
	global_store_dwordx4 v[134:135], v[68:71], off offset:2048 nt
	global_store_dwordx4 v[138:139], v[64:67], off offset:64 nt
; __device__ __forceinline__ u32x2 pack4(f32x4 v) { u32x2 r; r.x = cvt_pk(v[0], v[1]); r.y = cvt_pk(v[2], v[3]); return r; }
; __device__ __forceinline__ void store_pair16(u16* rowp32, u32x2 a, u32x2 b, int fq) {
;   auto rx = __builtin_amdgcn_permlane16_swap(a.x, b.x, false, false);
;   auto ry = __builtin_amdgcn_permlane16_swap(a.y, b.y, false, false);
;   u32x4 w = {rx[0], ry[0], rx[1], ry[1]};
;   *(u32x4*)(rowp32 + ((fq & 1) * 16 + (fq >> 1) * 8)) = w;
; }
; template <int SEC> __device__ __forceinline__ void epiB2(const Params& p, int row, int col32, f32x4 v0, f32x4 v1, int fq) {
;     ...
;   else if (SEC == 2) {
;     const int c32 = col32 - 2048;
;     store_pair16((u16*)(ws + OFF_XBC) + (size_t)row * 1536 + c32, pack4(v0), pack4(v1), fq);
;     const int pos = row & 2047;
;     if (pos >= 2045) {
;       float* cp = p.out + O_CONVP + (size_t)(row >> 11) * 4608 + (pos - 2045) * 1536 + c32 + fq * 4;
;       *(f32x4*)cp = v0; *(f32x4*)(cp + 16) = v1;
;     }
;   }
.LBB0_210:
	s_or_b64 exec, exec, s[52:53]
	v_add_u32_e32 v128, 0x80, v137
	v_mov_b64_e32 v[134:135], s[8:9]
	v_mad_u64_u32 v[138:139], s[4:5], v128, s74, v[134:135]
	v_lshl_add_u64 v[142:143], v[138:139], 0, s[42:43]
	v_cvt_pk_bf16_f32 v138, v60, v61
	v_cvt_pk_bf16_f32 v139, v62, v63
	v_cvt_pk_bf16_f32 v140, v56, v57
	v_cvt_pk_bf16_f32 v141, v58, v59
	s_nop 0
	v_permlane16_swap_b32_e32 v138, v140
	v_permlane16_swap_b32_e32 v139, v141
	v_lshl_add_u64 v[142:143], v[142:143], 0, v[132:133]
	global_store_dwordx4 v[142:143], v[138:141], off nt
	v_add_u32_e32 v128, 0x90, v137
	s_nop 0
	v_cvt_pk_bf16_f32 v138, v52, v53
	v_cvt_pk_bf16_f32 v139, v54, v55
	v_cvt_pk_bf16_f32 v140, v48, v49
	v_cvt_pk_bf16_f32 v141, v50, v51
	s_nop 0
	v_permlane16_swap_b32_e32 v138, v140
	v_permlane16_swap_b32_e32 v139, v141
	global_store_dwordx4 v[142:143], v[138:141], off offset:256 nt
	s_nop 1
	v_mad_u64_u32 v[138:139], s[4:5], v128, s74, v[134:135]
	v_lshl_add_u64 v[142:143], v[138:139], 0, s[42:43]
	v_cvt_pk_bf16_f32 v138, v44, v45
	v_cvt_pk_bf16_f32 v139, v46, v47
	v_cvt_pk_bf16_f32 v140, v40, v41
	v_cvt_pk_bf16_f32 v141, v42, v43
	s_nop 0
	v_permlane16_swap_b32_e32 v138, v140
	v_permlane16_swap_b32_e32 v139, v141
	v_lshl_add_u64 v[142:143], v[142:143], 0, v[132:133]
	global_store_dwordx4 v[142:143], v[138:141], off nt
	v_add_u32_e32 v128, 0xa0, v137
	s_nop 0
	v_cvt_pk_bf16_f32 v138, v36, v37
	v_cvt_pk_bf16_f32 v139, v38, v39
	v_cvt_pk_bf16_f32 v140, v32, v33
	v_cvt_pk_bf16_f32 v141, v34, v35
	s_nop 0
	v_permlane16_swap_b32_e32 v138, v140
	v_permlane16_swap_b32_e32 v139, v141
	global_store_dwordx4 v[142:143], v[138:141], off offset:256 nt
	s_nop 1
	v_mad_u64_u32 v[138:139], s[4:5], v128, s74, v[134:135]
	v_lshl_add_u64 v[142:143], v[138:139], 0, s[42:43]
	v_cvt_pk_bf16_f32 v138, v28, v29
	v_cvt_pk_bf16_f32 v139, v30, v31
	v_cvt_pk_bf16_f32 v140, v24, v25
	v_cvt_pk_bf16_f32 v141, v26, v27
	s_nop 0
	v_permlane16_swap_b32_e32 v138, v140
	v_permlane16_swap_b32_e32 v139, v141
	v_lshl_add_u64 v[142:143], v[142:143], 0, v[132:133]
	global_store_dwordx4 v[142:143], v[138:141], off nt
	v_add_u32_e32 v128, 0xb0, v137
	v_and_b32_e32 v137, 0x7ff, v128
	v_cvt_pk_bf16_f32 v138, v20, v21
	v_cvt_pk_bf16_f32 v139, v22, v23
	v_cvt_pk_bf16_f32 v140, v16, v17
	v_cvt_pk_bf16_f32 v141, v18, v19
	s_nop 0
	v_permlane16_swap_b32_e32 v138, v140
	v_permlane16_swap_b32_e32 v139, v141
	global_store_dwordx4 v[142:143], v[138:141], off offset:256 nt
	v_mad_u64_u32 v[134:135], s[52:53], v128, s74, v[134:135]
	s_nop 0
	v_lshrrev_b32_e32 v138, 11, v128
	v_cmp_lt_u32_e64 s[4:5], s75, v137
	v_mul_hi_u32_u24_e32 v143, 0x4800, v138
	v_mul_u32_u24_e32 v142, 0x4800, v138
	v_mul_u32_u24_e32 v137, 0x600, v137
	v_lshl_add_u64 v[134:135], v[134:135], 0, s[42:43]
	v_cvt_pk_bf16_f32 v138, v12, v13
	v_cvt_pk_bf16_f32 v139, v14, v15
	v_cvt_pk_bf16_f32 v140, v8, v9
	v_cvt_pk_bf16_f32 v141, v10, v11
	s_nop 0
	v_permlane16_swap_b32_e32 v138, v140
	v_permlane16_swap_b32_e32 v139, v141
	v_lshl_add_u64 v[134:135], v[134:135], 0, v[132:133]
	v_lshl_add_u64 v[132:133], s[48:49], 0, v[142:143]
	v_lshlrev_b32_e32 v128, 2, v137
	global_store_dwordx4 v[134:135], v[138:141], off nt
	s_and_saveexec_b64 s[42:43], s[4:5]
	s_cbranch_execz .LBB0_212
	v_lshl_add_u64 v[138:139], v[132:133], 0, v[128:129]
	v_lshl_add_u64 v[138:139], s[40:41], 2, v[138:139]
	v_lshl_add_u64 v[138:139], v[130:131], 2, v[138:139]
	v_lshl_add_u64 v[140:141], v[138:139], 0, s[24:25]
	v_add_co_u32_e32 v138, vcc, 0x3c84000, v138
	s_nop 1
	v_addc_co_u32_e32 v139, vcc, 0, v139, vcc
	global_store_dwordx4 v[138:139], v[12:15], off offset:2048 nt
	global_store_dwordx4 v[140:141], v[8:11], off offset:64 nt
.LBB0_212:
	s_or_b64 exec, exec, s[42:43]
	v_cvt_pk_bf16_f32 v138, v4, v5
	v_cvt_pk_bf16_f32 v139, v6, v7
	v_cvt_pk_bf16_f32 v140, v0, v1
	v_cvt_pk_bf16_f32 v141, v2, v3
	s_nop 0
	v_permlane16_swap_b32_e32 v138, v140
	v_permlane16_swap_b32_e32 v139, v141
	global_store_dwordx4 v[134:135], v[138:141], off offset:256 nt
	s_and_saveexec_b64 s[40:41], s[4:5]
	s_cbranch_execz .LBB0_214
	v_lshl_add_u64 v[132:133], v[132:133], 0, v[128:129]
	v_lshl_add_u64 v[130:131], v[130:131], 2, v[132:133]
	v_lshl_add_u64 v[130:131], s[44:45], 2, v[130:131]
	v_lshl_add_u64 v[132:133], v[130:131], 0, s[24:25]
	v_add_co_u32_e32 v130, vcc, 0x3c84000, v130
	s_nop 1
	v_addc_co_u32_e32 v131, vcc, 0, v131, vcc
	global_store_dwordx4 v[130:131], v[4:7], off offset:2048 nt
	global_store_dwordx4 v[132:133], v[0:3], off offset:64 nt

; __device__ __forceinline__ u32x2 pack4(f32x4 v) { u32x2 r; r.x = cvt_pk(v[0], v[1]); r.y = cvt_pk(v[2], v[3]); return r; }
; __device__ __forceinline__ float silu_f(float x) { return x * __builtin_amdgcn_rcpf(1.f + __builtin_amdgcn_exp2f(-1.4426950409f * x)); }
; __device__ __forceinline__ void store_pair16(u16* rowp32, u32x2 a, u32x2 b, int fq) {
;   auto rx = __builtin_amdgcn_permlane16_swap(a.x, b.x, false, false);
;   auto ry = __builtin_amdgcn_permlane16_swap(a.y, b.y, false, false);
;   u32x4 w = {rx[0], ry[0], rx[1], ry[1]};
;   *(u32x4*)(rowp32 + ((fq & 1) * 16 + (fq >> 1) * 8)) = w;
; }
; template <int SEC> __device__ __forceinline__ void epiB2(const Params& p, int row, int col32, f32x4 v0, f32x4 v1, int fq) {
;     ...
;   else if (SEC == 1) { f32x4 o0 = {silu_f(v0[0]), silu_f(v0[1]), silu_f(v0[2]), silu_f(v0[3])}, o1 = {silu_f(v1[0]), silu_f(v1[1]), silu_f(v1[2]), silu_f(v1[3])};
;     store_pair16((u16*)(ws + OFF_ZS) + (size_t)row * 1024 + (col32 - 1024), pack4(o0), pack4(o1), fq); }
.LBB0_216:
	s_andn2_b64 vcc, exec, s[4:5]
	s_cbranch_vccnz .LBB0_189
	s_cmp_gt_i32 s39, 0
	s_mov_b64 s[4:5], -1
	s_cbranch_scc0 .LBB0_219
	v_mul_f32_e32 v137, 0xbfb8aa3b, v126
	v_exp_f32_e32 v137, v137
	v_mul_f32_e32 v138, 0xbfb8aa3b, v127
	v_exp_f32_e32 v139, v138
	v_mul_f32_e32 v132, 0xbfb8aa3b, v124
	v_add_f32_e32 v137, 1.0, v137
	v_rcp_f32_e32 v138, v137
	v_add_f32_e32 v137, 1.0, v139
	v_mul_f32_e32 v139, 0xbfb8aa3b, v120
	v_exp_f32_e32 v140, v139
	v_mul_f32_e32 v139, 0xbfb8aa3b, v121
	v_exp_f32_e32 v141, v139
	v_exp_f32_e32 v134, v132
	v_mul_f32_e32 v132, 0xbfb8aa3b, v125
	v_rcp_f32_e32 v139, v137
	v_add_f32_e32 v137, 1.0, v140
	v_exp_f32_e32 v135, v132
	v_rcp_f32_e32 v140, v137
	v_add_f32_e32 v137, 1.0, v141
	v_mul_f32_e32 v141, 0xbfb8aa3b, v122
	v_exp_f32_e32 v142, v141
	v_mul_f32_e32 v141, 0xbfb8aa3b, v123
	v_exp_f32_e32 v143, v141
	v_add_f32_e32 v134, 1.0, v134
	v_add_f32_e32 v135, 1.0, v135
	v_mbcnt_lo_u32_b32 v130, -1, 0
	v_mbcnt_hi_u32_b32 v130, -1, v130
	v_rcp_f32_e32 v134, v134
	v_rcp_f32_e32 v135, v135
	v_rcp_f32_e32 v141, v137
	v_add_f32_e32 v137, 1.0, v142
	v_and_or_b32 v128, v130, 15, s33
	v_and_b32_e32 v131, 16, v130
	v_ashrrev_i32_e32 v130, 2, v130
	v_rcp_f32_e32 v142, v137
	v_add_f32_e32 v137, 1.0, v143
	s_or_b32 s4, s38, s66
	v_and_b32_e32 v130, -8, v130
	v_rcp_f32_e32 v143, v137
	v_add_u32_e32 v130, v130, v131
	v_lshlrev_b64 v[132:133], 11, v[128:129]
	s_ashr_i32 s5, s4, 31
	v_ashrrev_i32_e32 v131, 31, v130
	v_pk_mul_f32 v[134:135], v[124:125], v[134:135]
	v_pk_mul_f32 v[140:141], v[120:121], v[140:141]
	v_lshl_add_u64 v[132:133], s[50:51], 0, v[132:133]
	s_lshl_b64 s[4:5], s[4:5], 1
	v_mul_f32_e32 v137, 0xbfb8aa3b, v116
	v_pk_mul_f32 v[138:139], v[126:127], v[138:139]
	v_lshl_add_u64 v[144:145], v[132:133], 0, s[4:5]
	v_cvt_pk_bf16_f32 v132, v134, v135
	v_cvt_pk_bf16_f32 v134, v140, v141
	v_lshlrev_b64 v[130:131], 1, v[130:131]
	v_exp_f32_e32 v137, v137
	v_mul_f32_e32 v140, 0xbfb8aa3b, v117
	v_pk_mul_f32 v[142:143], v[122:123], v[142:143]
	v_cvt_pk_bf16_f32 v133, v138, v139
	v_lshl_add_u64 v[138:139], v[144:145], 0, v[130:131]
	v_exp_f32_e32 v140, v140
	v_cvt_pk_bf16_f32 v135, v142, v143
	v_add_co_u32_e32 v138, vcc, s76, v138
	v_permlane16_swap_b32_e32 v132, v134
	v_permlane16_swap_b32_e32 v133, v135
	v_addc_co_u32_e32 v139, vcc, 0, v139, vcc
	global_store_dwordx4 v[138:139], v[132:135], off offset:2048 nt
	s_nop 1
	v_add_f32_e32 v132, 1.0, v137
	v_mul_f32_e32 v137, 0xbfb8aa3b, v112
	v_add_f32_e32 v133, 1.0, v140
	v_exp_f32_e32 v137, v137
	v_mul_f32_e32 v140, 0xbfb8aa3b, v113
	v_exp_f32_e32 v141, v140
	v_mul_f32_e32 v134, 0xbfb8aa3b, v118
	v_add_f32_e32 v137, 1.0, v137
	v_rcp_f32_e32 v140, v137
	v_add_f32_e32 v137, 1.0, v141
	v_mul_f32_e32 v141, 0xbfb8aa3b, v114
	v_mul_f32_e32 v135, 0xbfb8aa3b, v119
	v_exp_f32_e32 v142, v141
	v_mul_f32_e32 v141, 0xbfb8aa3b, v115
	v_exp_f32_e32 v134, v134
	v_exp_f32_e32 v135, v135
	v_exp_f32_e32 v143, v141
	v_rcp_f32_e32 v141, v137
	v_add_f32_e32 v137, 1.0, v142
	v_add_f32_e32 v134, 1.0, v134
	v_add_f32_e32 v135, 1.0, v135
	v_rcp_f32_e32 v142, v137
	v_add_f32_e32 v137, 1.0, v143
	v_rcp_f32_e32 v132, v132
	v_rcp_f32_e32 v133, v133
	v_rcp_f32_e32 v134, v134
	v_rcp_f32_e32 v135, v135
	v_rcp_f32_e32 v143, v137
	v_pk_mul_f32 v[132:133], v[116:117], v[132:133]
	v_pk_mul_f32 v[140:141], v[112:113], v[140:141]
	v_pk_mul_f32 v[134:135], v[118:119], v[134:135]
	v_pk_mul_f32 v[142:143], v[114:115], v[142:143]
	v_cvt_pk_bf16_f32 v132, v132, v133
	v_cvt_pk_bf16_f32 v133, v134, v135
	v_cvt_pk_bf16_f32 v134, v140, v141
	v_cvt_pk_bf16_f32 v135, v142, v143
	s_nop 0
	v_permlane16_swap_b32_e32 v132, v134
	v_permlane16_swap_b32_e32 v133, v135
	v_mul_f32_e32 v137, 0xbfb8aa3b, v110
	global_store_dwordx4 v[138:139], v[132:135], off offset:2304 nt
	v_exp_f32_e32 v137, v137
	v_mul_f32_e32 v138, 0xbfb8aa3b, v111
	v_exp_f32_e32 v139, v138
	v_mul_f32_e32 v134, 0xbfb8aa3b, v108
	v_add_f32_e32 v137, 1.0, v137
	v_rcp_f32_e32 v138, v137
	v_add_f32_e32 v137, 1.0, v139
	v_mul_f32_e32 v139, 0xbfb8aa3b, v104
	v_exp_f32_e32 v140, v139
	v_mul_f32_e32 v139, 0xbfb8aa3b, v105
	v_exp_f32_e32 v141, v139
	v_mul_f32_e32 v135, 0xbfb8aa3b, v109
	v_rcp_f32_e32 v139, v137
	v_add_f32_e32 v137, 1.0, v140
	v_exp_f32_e32 v134, v134
	v_exp_f32_e32 v135, v135
	v_rcp_f32_e32 v140, v137
	v_add_f32_e32 v137, 1.0, v141
	v_mul_f32_e32 v141, 0xbfb8aa3b, v106
	v_exp_f32_e32 v142, v141
	v_mul_f32_e32 v141, 0xbfb8aa3b, v107
	v_exp_f32_e32 v143, v141
	v_add_f32_e32 v134, 1.0, v134
	v_add_f32_e32 v135, 1.0, v135
	v_rcp_f32_e32 v134, v134
	v_rcp_f32_e32 v135, v135
	v_rcp_f32_e32 v141, v137
	v_add_f32_e32 v137, 1.0, v142
	v_rcp_f32_e32 v142, v137
	v_add_f32_e32 v137, 1.0, v143
	v_or_b32_e32 v132, 16, v128
	v_mov_b32_e32 v133, v129
	v_rcp_f32_e32 v143, v137
	v_lshlrev_b64 v[132:133], 11, v[132:133]
	v_pk_mul_f32 v[134:135], v[108:109], v[134:135]
	v_pk_mul_f32 v[140:141], v[104:105], v[140:141]
	v_lshl_add_u64 v[132:133], s[50:51], 0, v[132:133]
	v_mul_f32_e32 v137, 0xbfb8aa3b, v100
	v_pk_mul_f32 v[138:139], v[110:111], v[138:139]
	v_lshl_add_u64 v[144:145], v[132:133], 0, s[4:5]
	v_cvt_pk_bf16_f32 v132, v134, v135
	v_cvt_pk_bf16_f32 v134, v140, v141
	v_exp_f32_e32 v137, v137
	v_mul_f32_e32 v140, 0xbfb8aa3b, v101
	v_pk_mul_f32 v[142:143], v[106:107], v[142:143]
	v_cvt_pk_bf16_f32 v133, v138, v139
	v_lshl_add_u64 v[138:139], v[144:145], 0, v[130:131]
	v_exp_f32_e32 v140, v140
	v_cvt_pk_bf16_f32 v135, v142, v143
	v_add_co_u32_e32 v138, vcc, s76, v138
	v_permlane16_swap_b32_e32 v132, v134
	v_permlane16_swap_b32_e32 v133, v135
	v_addc_co_u32_e32 v139, vcc, 0, v139, vcc
	global_store_dwordx4 v[138:139], v[132:135], off offset:2048 nt
	s_nop 1
; __device__ __forceinline__ u32x2 pack4(f32x4 v) { u32x2 r; r.x = cvt_pk(v[0], v[1]); r.y = cvt_pk(v[2], v[3]); return r; }
; __device__ __forceinline__ float silu_f(float x) { return x * __builtin_amdgcn_rcpf(1.f + __builtin_amdgcn_exp2f(-1.4426950409f * x)); }
; __device__ __forceinline__ void store_pair16(u16* rowp32, u32x2 a, u32x2 b, int fq) {
;   auto rx = __builtin_amdgcn_permlane16_swap(a.x, b.x, false, false);
;   auto ry = __builtin_amdgcn_permlane16_swap(a.y, b.y, false, false);
;   u32x4 w = {rx[0], ry[0], rx[1], ry[1]};
;   *(u32x4*)(rowp32 + ((fq & 1) * 16 + (fq >> 1) * 8)) = w;
; }
; template <int SEC> __device__ __forceinline__ void epiB2(const Params& p, int row, int col32, f32x4 v0, f32x4 v1, int fq) {
;     ...
;   else if (SEC == 1) { f32x4 o0 = {silu_f(v0[0]), silu_f(v0[1]), silu_f(v0[2]), silu_f(v0[3])}, o1 = {silu_f(v1[0]), silu_f(v1[1]), silu_f(v1[2]), silu_f(v1[3])};
;     store_pair16((u16*)(ws + OFF_ZS) + (size_t)row * 1024 + (col32 - 1024), pack4(o0), pack4(o1), fq); }
	v_add_f32_e32 v132, 1.0, v137
	v_mul_f32_e32 v137, 0xbfb8aa3b, v96
	v_add_f32_e32 v133, 1.0, v140
	v_exp_f32_e32 v137, v137
	v_mul_f32_e32 v140, 0xbfb8aa3b, v97
	v_exp_f32_e32 v141, v140
	v_mul_f32_e32 v134, 0xbfb8aa3b, v102
	v_add_f32_e32 v137, 1.0, v137
	v_rcp_f32_e32 v140, v137
	v_add_f32_e32 v137, 1.0, v141
	v_mul_f32_e32 v141, 0xbfb8aa3b, v98
	v_mul_f32_e32 v135, 0xbfb8aa3b, v103
	v_exp_f32_e32 v142, v141
	v_mul_f32_e32 v141, 0xbfb8aa3b, v99
	v_exp_f32_e32 v134, v134
	v_exp_f32_e32 v135, v135
	v_exp_f32_e32 v143, v141
	v_rcp_f32_e32 v141, v137
	v_add_f32_e32 v137, 1.0, v142
	v_add_f32_e32 v134, 1.0, v134
	v_add_f32_e32 v135, 1.0, v135
	v_rcp_f32_e32 v142, v137
	v_add_f32_e32 v137, 1.0, v143
	v_rcp_f32_e32 v132, v132
	v_rcp_f32_e32 v133, v133
	v_rcp_f32_e32 v134, v134
	v_rcp_f32_e32 v135, v135
	v_rcp_f32_e32 v143, v137
	v_pk_mul_f32 v[132:133], v[100:101], v[132:133]
	v_pk_mul_f32 v[140:141], v[96:97], v[140:141]
	v_pk_mul_f32 v[134:135], v[102:103], v[134:135]
	v_pk_mul_f32 v[142:143], v[98:99], v[142:143]
	v_cvt_pk_bf16_f32 v132, v132, v133
	v_cvt_pk_bf16_f32 v133, v134, v135
	v_cvt_pk_bf16_f32 v134, v140, v141
	v_cvt_pk_bf16_f32 v135, v142, v143
	s_nop 0
	v_permlane16_swap_b32_e32 v132, v134
	v_permlane16_swap_b32_e32 v133, v135
	v_mul_f32_e32 v137, 0xbfb8aa3b, v94
	global_store_dwordx4 v[138:139], v[132:135], off offset:2304 nt
	v_exp_f32_e32 v137, v137
	v_mul_f32_e32 v138, 0xbfb8aa3b, v95
	v_exp_f32_e32 v139, v138
	v_mul_f32_e32 v134, 0xbfb8aa3b, v92
	v_add_f32_e32 v137, 1.0, v137
	v_rcp_f32_e32 v138, v137
	v_add_f32_e32 v137, 1.0, v139
	v_mul_f32_e32 v139, 0xbfb8aa3b, v88
	v_exp_f32_e32 v140, v139
	v_mul_f32_e32 v139, 0xbfb8aa3b, v89
	v_exp_f32_e32 v141, v139
	v_mul_f32_e32 v135, 0xbfb8aa3b, v93
	v_rcp_f32_e32 v139, v137
	v_add_f32_e32 v137, 1.0, v140
	v_exp_f32_e32 v134, v134
	v_exp_f32_e32 v135, v135
	v_rcp_f32_e32 v140, v137
	v_add_f32_e32 v137, 1.0, v141
	v_mul_f32_e32 v141, 0xbfb8aa3b, v90
	v_exp_f32_e32 v142, v141
	v_mul_f32_e32 v141, 0xbfb8aa3b, v91
	v_exp_f32_e32 v143, v141
	v_add_f32_e32 v134, 1.0, v134
	v_add_f32_e32 v135, 1.0, v135
	v_rcp_f32_e32 v134, v134
	v_rcp_f32_e32 v135, v135
	v_rcp_f32_e32 v141, v137
	v_add_f32_e32 v137, 1.0, v142
	v_rcp_f32_e32 v142, v137
	v_add_f32_e32 v137, 1.0, v143
	v_or_b32_e32 v132, 32, v128
	v_mov_b32_e32 v133, v129
	v_rcp_f32_e32 v143, v137
	v_lshlrev_b64 v[132:133], 11, v[132:133]
	v_pk_mul_f32 v[134:135], v[92:93], v[134:135]
	v_pk_mul_f32 v[140:141], v[88:89], v[140:141]
	v_lshl_add_u64 v[132:133], s[50:51], 0, v[132:133]
	v_mul_f32_e32 v137, 0xbfb8aa3b, v84
	v_pk_mul_f32 v[138:139], v[94:95], v[138:139]
	v_lshl_add_u64 v[144:145], v[132:133], 0, s[4:5]
	v_cvt_pk_bf16_f32 v132, v134, v135
	v_cvt_pk_bf16_f32 v134, v140, v141
	v_exp_f32_e32 v137, v137
	v_mul_f32_e32 v140, 0xbfb8aa3b, v85
	v_pk_mul_f32 v[142:143], v[90:91], v[142:143]
	v_cvt_pk_bf16_f32 v133, v138, v139
	v_lshl_add_u64 v[138:139], v[144:145], 0, v[130:131]
	v_exp_f32_e32 v140, v140
	v_cvt_pk_bf16_f32 v135, v142, v143
	v_add_co_u32_e32 v138, vcc, s76, v138
	v_permlane16_swap_b32_e32 v132, v134
	v_permlane16_swap_b32_e32 v133, v135
	v_addc_co_u32_e32 v139, vcc, 0, v139, vcc
	global_store_dwordx4 v[138:139], v[132:135], off offset:2048 nt
	s_nop 1
	v_add_f32_e32 v132, 1.0, v137
	v_mul_f32_e32 v137, 0xbfb8aa3b, v80
	v_add_f32_e32 v133, 1.0, v140
	v_exp_f32_e32 v137, v137
	v_mul_f32_e32 v140, 0xbfb8aa3b, v81
	v_exp_f32_e32 v141, v140
	v_mul_f32_e32 v134, 0xbfb8aa3b, v86
	v_add_f32_e32 v137, 1.0, v137
	v_rcp_f32_e32 v140, v137
	v_add_f32_e32 v137, 1.0, v141
	v_mul_f32_e32 v141, 0xbfb8aa3b, v82
	v_mul_f32_e32 v135, 0xbfb8aa3b, v87
	v_exp_f32_e32 v142, v141
	v_mul_f32_e32 v141, 0xbfb8aa3b, v83
	v_exp_f32_e32 v134, v134
	v_exp_f32_e32 v135, v135
	v_exp_f32_e32 v143, v141
	v_rcp_f32_e32 v141, v137
	v_add_f32_e32 v137, 1.0, v142
	v_add_f32_e32 v134, 1.0, v134
	v_add_f32_e32 v135, 1.0, v135
	v_rcp_f32_e32 v142, v137
	v_add_f32_e32 v137, 1.0, v143
	v_rcp_f32_e32 v132, v132
	v_rcp_f32_e32 v133, v133
	v_rcp_f32_e32 v134, v134
	v_rcp_f32_e32 v135, v135
	v_rcp_f32_e32 v143, v137
	v_pk_mul_f32 v[132:133], v[84:85], v[132:133]
	v_pk_mul_f32 v[140:141], v[80:81], v[140:141]
	v_pk_mul_f32 v[134:135], v[86:87], v[134:135]
	v_pk_mul_f32 v[142:143], v[82:83], v[142:143]
	v_cvt_pk_bf16_f32 v132, v132, v133
	v_cvt_pk_bf16_f32 v133, v134, v135
	v_cvt_pk_bf16_f32 v134, v140, v141
	v_cvt_pk_bf16_f32 v135, v142, v143
	s_nop 0
	v_permlane16_swap_b32_e32 v132, v134
	v_permlane16_swap_b32_e32 v133, v135
	v_mul_f32_e32 v137, 0xbfb8aa3b, v78
	global_store_dwordx4 v[138:139], v[132:135], off offset:2304 nt
	v_exp_f32_e32 v137, v137
	v_mul_f32_e32 v138, 0xbfb8aa3b, v79
	v_exp_f32_e32 v139, v138
	v_mul_f32_e32 v134, 0xbfb8aa3b, v76
	v_add_f32_e32 v137, 1.0, v137
	v_rcp_f32_e32 v138, v137
	v_add_f32_e32 v137, 1.0, v139
	v_mul_f32_e32 v139, 0xbfb8aa3b, v72
	v_exp_f32_e32 v140, v139
	v_mul_f32_e32 v139, 0xbfb8aa3b, v73
	v_exp_f32_e32 v141, v139
	v_mul_f32_e32 v135, 0xbfb8aa3b, v77
	v_rcp_f32_e32 v139, v137
	v_add_f32_e32 v137, 1.0, v140
	v_exp_f32_e32 v134, v134
	v_exp_f32_e32 v135, v135
	v_rcp_f32_e32 v140, v137
	v_add_f32_e32 v137, 1.0, v141
	v_mul_f32_e32 v141, 0xbfb8aa3b, v74
	v_exp_f32_e32 v142, v141
	v_mul_f32_e32 v141, 0xbfb8aa3b, v75
	v_exp_f32_e32 v143, v141
	v_add_f32_e32 v134, 1.0, v134
	v_add_f32_e32 v135, 1.0, v135
	v_rcp_f32_e32 v134, v134
	v_rcp_f32_e32 v135, v135
	v_rcp_f32_e32 v141, v137
	v_add_f32_e32 v137, 1.0, v142
	v_rcp_f32_e32 v142, v137
	v_add_f32_e32 v137, 1.0, v143
	v_or_b32_e32 v132, 48, v128
	v_mov_b32_e32 v133, v129
	v_rcp_f32_e32 v143, v137
	v_lshlrev_b64 v[132:133], 11, v[132:133]
	v_pk_mul_f32 v[134:135], v[76:77], v[134:135]
; __device__ __forceinline__ u32x2 pack4(f32x4 v) { u32x2 r; r.x = cvt_pk(v[0], v[1]); r.y = cvt_pk(v[2], v[3]); return r; }
; __device__ __forceinline__ float silu_f(float x) { return x * __builtin_amdgcn_rcpf(1.f + __builtin_amdgcn_exp2f(-1.4426950409f * x)); }
; __device__ __forceinline__ void store_pair16(u16* rowp32, u32x2 a, u32x2 b, int fq) {
;   auto rx = __builtin_amdgcn_permlane16_swap(a.x, b.x, false, false);
;   auto ry = __builtin_amdgcn_permlane16_swap(a.y, b.y, false, false);
;   u32x4 w = {rx[0], ry[0], rx[1], ry[1]};
;   *(u32x4*)(rowp32 + ((fq & 1) * 16 + (fq >> 1) * 8)) = w;
; }
; template <int SEC> __device__ __forceinline__ void epiB2(const Params& p, int row, int col32, f32x4 v0, f32x4 v1, int fq) {
;     ...
;   else if (SEC == 1) { f32x4 o0 = {silu_f(v0[0]), silu_f(v0[1]), silu_f(v0[2]), silu_f(v0[3])}, o1 = {silu_f(v1[0]), silu_f(v1[1]), silu_f(v1[2]), silu_f(v1[3])};
;     store_pair16((u16*)(ws + OFF_ZS) + (size_t)row * 1024 + (col32 - 1024), pack4(o0), pack4(o1), fq); }
	v_pk_mul_f32 v[140:141], v[72:73], v[140:141]
	v_lshl_add_u64 v[132:133], s[50:51], 0, v[132:133]
	v_mul_f32_e32 v137, 0xbfb8aa3b, v68
	v_pk_mul_f32 v[138:139], v[78:79], v[138:139]
	v_lshl_add_u64 v[144:145], v[132:133], 0, s[4:5]
	v_cvt_pk_bf16_f32 v132, v134, v135
	v_cvt_pk_bf16_f32 v134, v140, v141
	v_exp_f32_e32 v137, v137
	v_mul_f32_e32 v140, 0xbfb8aa3b, v69
	v_pk_mul_f32 v[142:143], v[74:75], v[142:143]
	v_cvt_pk_bf16_f32 v133, v138, v139
	v_lshl_add_u64 v[138:139], v[144:145], 0, v[130:131]
	v_exp_f32_e32 v140, v140
	v_cvt_pk_bf16_f32 v135, v142, v143
	v_add_co_u32_e32 v138, vcc, s76, v138
	v_permlane16_swap_b32_e32 v132, v134
	v_permlane16_swap_b32_e32 v133, v135
	v_addc_co_u32_e32 v139, vcc, 0, v139, vcc
	global_store_dwordx4 v[138:139], v[132:135], off offset:2048 nt
	s_nop 1
	v_add_f32_e32 v132, 1.0, v137
	v_mul_f32_e32 v137, 0xbfb8aa3b, v64
	v_add_f32_e32 v133, 1.0, v140
	v_exp_f32_e32 v137, v137
	v_mul_f32_e32 v140, 0xbfb8aa3b, v65
	v_exp_f32_e32 v141, v140
	v_mul_f32_e32 v134, 0xbfb8aa3b, v70
	v_add_f32_e32 v137, 1.0, v137
	v_rcp_f32_e32 v140, v137
	v_add_f32_e32 v137, 1.0, v141
	v_mul_f32_e32 v141, 0xbfb8aa3b, v66
	v_mul_f32_e32 v135, 0xbfb8aa3b, v71
	v_exp_f32_e32 v142, v141
	v_mul_f32_e32 v141, 0xbfb8aa3b, v67
	v_exp_f32_e32 v134, v134
	v_exp_f32_e32 v135, v135
	v_exp_f32_e32 v143, v141
	v_rcp_f32_e32 v141, v137
	v_add_f32_e32 v137, 1.0, v142
	v_add_f32_e32 v134, 1.0, v134
	v_add_f32_e32 v135, 1.0, v135
	v_rcp_f32_e32 v142, v137
	v_add_f32_e32 v137, 1.0, v143
	v_rcp_f32_e32 v132, v132
	v_rcp_f32_e32 v133, v133
	v_rcp_f32_e32 v134, v134
	v_rcp_f32_e32 v135, v135
	v_rcp_f32_e32 v143, v137
	v_pk_mul_f32 v[132:133], v[68:69], v[132:133]
	v_pk_mul_f32 v[140:141], v[64:65], v[140:141]
	v_pk_mul_f32 v[134:135], v[70:71], v[134:135]
	v_pk_mul_f32 v[142:143], v[66:67], v[142:143]
	v_cvt_pk_bf16_f32 v132, v132, v133
	v_cvt_pk_bf16_f32 v133, v134, v135
	v_cvt_pk_bf16_f32 v134, v140, v141
	v_cvt_pk_bf16_f32 v135, v142, v143
	s_nop 0
	v_permlane16_swap_b32_e32 v132, v134
	v_permlane16_swap_b32_e32 v133, v135
	v_mul_f32_e32 v137, 0xbfb8aa3b, v62
	global_store_dwordx4 v[138:139], v[132:135], off offset:2304 nt
	v_exp_f32_e32 v137, v137
	v_mul_f32_e32 v138, 0xbfb8aa3b, v63
	v_exp_f32_e32 v139, v138
	v_mul_f32_e32 v134, 0xbfb8aa3b, v60
	v_add_f32_e32 v137, 1.0, v137
	v_rcp_f32_e32 v138, v137
	v_add_f32_e32 v137, 1.0, v139
	v_mul_f32_e32 v139, 0xbfb8aa3b, v56
	v_exp_f32_e32 v140, v139
	v_mul_f32_e32 v139, 0xbfb8aa3b, v57
	v_exp_f32_e32 v141, v139
	v_mul_f32_e32 v135, 0xbfb8aa3b, v61
	v_rcp_f32_e32 v139, v137
	v_add_f32_e32 v137, 1.0, v140
	v_exp_f32_e32 v134, v134
	v_exp_f32_e32 v135, v135
	v_rcp_f32_e32 v140, v137
	v_add_f32_e32 v137, 1.0, v141
	v_mul_f32_e32 v141, 0xbfb8aa3b, v58
	v_exp_f32_e32 v142, v141
	v_mul_f32_e32 v141, 0xbfb8aa3b, v59
	v_exp_f32_e32 v143, v141
	v_add_f32_e32 v134, 1.0, v134
	v_add_f32_e32 v135, 1.0, v135
	v_rcp_f32_e32 v134, v134
	v_rcp_f32_e32 v135, v135
	v_rcp_f32_e32 v141, v137
	v_add_f32_e32 v137, 1.0, v142
	v_rcp_f32_e32 v142, v137
	v_add_f32_e32 v137, 1.0, v143
	v_add_u32_e32 v132, 0x80, v128
	v_mov_b32_e32 v133, v129
	v_rcp_f32_e32 v143, v137
	v_lshlrev_b64 v[132:133], 11, v[132:133]
	v_pk_mul_f32 v[134:135], v[60:61], v[134:135]
	v_pk_mul_f32 v[140:141], v[56:57], v[140:141]
	v_lshl_add_u64 v[132:133], s[50:51], 0, v[132:133]
	v_mul_f32_e32 v137, 0xbfb8aa3b, v52
	v_pk_mul_f32 v[138:139], v[62:63], v[138:139]
	v_lshl_add_u64 v[144:145], v[132:133], 0, s[4:5]
	v_cvt_pk_bf16_f32 v132, v134, v135
	v_cvt_pk_bf16_f32 v134, v140, v141
	v_exp_f32_e32 v137, v137
	v_mul_f32_e32 v140, 0xbfb8aa3b, v53
	v_pk_mul_f32 v[142:143], v[58:59], v[142:143]
	v_cvt_pk_bf16_f32 v133, v138, v139
	v_lshl_add_u64 v[138:139], v[144:145], 0, v[130:131]
	v_exp_f32_e32 v140, v140
	v_cvt_pk_bf16_f32 v135, v142, v143
	v_add_co_u32_e32 v138, vcc, s76, v138
	v_permlane16_swap_b32_e32 v132, v134
	v_permlane16_swap_b32_e32 v133, v135
	v_addc_co_u32_e32 v139, vcc, 0, v139, vcc
	global_store_dwordx4 v[138:139], v[132:135], off offset:2048 nt
	s_nop 1
	v_add_f32_e32 v132, 1.0, v137
	v_mul_f32_e32 v137, 0xbfb8aa3b, v48
	v_add_f32_e32 v133, 1.0, v140
	v_exp_f32_e32 v137, v137
	v_mul_f32_e32 v140, 0xbfb8aa3b, v49
	v_exp_f32_e32 v141, v140
	v_mul_f32_e32 v134, 0xbfb8aa3b, v54
	v_add_f32_e32 v137, 1.0, v137
	v_rcp_f32_e32 v140, v137
	v_add_f32_e32 v137, 1.0, v141
	v_mul_f32_e32 v141, 0xbfb8aa3b, v50
	v_mul_f32_e32 v135, 0xbfb8aa3b, v55
	v_exp_f32_e32 v142, v141
	v_mul_f32_e32 v141, 0xbfb8aa3b, v51
	v_exp_f32_e32 v134, v134
	v_exp_f32_e32 v135, v135
	v_exp_f32_e32 v143, v141
	v_rcp_f32_e32 v141, v137
	v_add_f32_e32 v137, 1.0, v142
	v_add_f32_e32 v134, 1.0, v134
	v_add_f32_e32 v135, 1.0, v135
	v_rcp_f32_e32 v142, v137
	v_add_f32_e32 v137, 1.0, v143
	v_rcp_f32_e32 v132, v132
	v_rcp_f32_e32 v133, v133
	v_rcp_f32_e32 v134, v134
	v_rcp_f32_e32 v135, v135
	v_rcp_f32_e32 v143, v137
	v_pk_mul_f32 v[132:133], v[52:53], v[132:133]
	v_pk_mul_f32 v[140:141], v[48:49], v[140:141]
	v_pk_mul_f32 v[134:135], v[54:55], v[134:135]
	v_pk_mul_f32 v[142:143], v[50:51], v[142:143]
	v_cvt_pk_bf16_f32 v132, v132, v133
	v_cvt_pk_bf16_f32 v133, v134, v135
	v_cvt_pk_bf16_f32 v134, v140, v141
	v_cvt_pk_bf16_f32 v135, v142, v143
	s_nop 0
	v_permlane16_swap_b32_e32 v132, v134
	v_permlane16_swap_b32_e32 v133, v135
	v_mul_f32_e32 v137, 0xbfb8aa3b, v46
	global_store_dwordx4 v[138:139], v[132:135], off offset:2304 nt
	v_exp_f32_e32 v137, v137
	v_mul_f32_e32 v138, 0xbfb8aa3b, v47
	v_exp_f32_e32 v139, v138
	v_mul_f32_e32 v134, 0xbfb8aa3b, v44
	v_add_f32_e32 v137, 1.0, v137
	v_rcp_f32_e32 v138, v137
	v_add_f32_e32 v137, 1.0, v139
	v_mul_f32_e32 v139, 0xbfb8aa3b, v40
	v_exp_f32_e32 v140, v139
; __device__ __forceinline__ u32x2 pack4(f32x4 v) { u32x2 r; r.x = cvt_pk(v[0], v[1]); r.y = cvt_pk(v[2], v[3]); return r; }
; __device__ __forceinline__ float silu_f(float x) { return x * __builtin_amdgcn_rcpf(1.f + __builtin_amdgcn_exp2f(-1.4426950409f * x)); }
; __device__ __forceinline__ void store_pair16(u16* rowp32, u32x2 a, u32x2 b, int fq) {
;   auto rx = __builtin_amdgcn_permlane16_swap(a.x, b.x, false, false);
;   auto ry = __builtin_amdgcn_permlane16_swap(a.y, b.y, false, false);
;   u32x4 w = {rx[0], ry[0], rx[1], ry[1]};
;   *(u32x4*)(rowp32 + ((fq & 1) * 16 + (fq >> 1) * 8)) = w;
; }
; template <int SEC> __device__ __forceinline__ void epiB2(const Params& p, int row, int col32, f32x4 v0, f32x4 v1, int fq) {
;     ...
;   else if (SEC == 1) { f32x4 o0 = {silu_f(v0[0]), silu_f(v0[1]), silu_f(v0[2]), silu_f(v0[3])}, o1 = {silu_f(v1[0]), silu_f(v1[1]), silu_f(v1[2]), silu_f(v1[3])};
;     store_pair16((u16*)(ws + OFF_ZS) + (size_t)row * 1024 + (col32 - 1024), pack4(o0), pack4(o1), fq); }
	v_mul_f32_e32 v139, 0xbfb8aa3b, v41
	v_exp_f32_e32 v141, v139
	v_mul_f32_e32 v135, 0xbfb8aa3b, v45
	v_rcp_f32_e32 v139, v137
	v_add_f32_e32 v137, 1.0, v140
	v_exp_f32_e32 v134, v134
	v_exp_f32_e32 v135, v135
	v_rcp_f32_e32 v140, v137
	v_add_f32_e32 v137, 1.0, v141
	v_mul_f32_e32 v141, 0xbfb8aa3b, v42
	v_exp_f32_e32 v142, v141
	v_mul_f32_e32 v141, 0xbfb8aa3b, v43
	v_exp_f32_e32 v143, v141
	v_add_f32_e32 v134, 1.0, v134
	v_add_f32_e32 v135, 1.0, v135
	v_rcp_f32_e32 v134, v134
	v_rcp_f32_e32 v135, v135
	v_rcp_f32_e32 v141, v137
	v_add_f32_e32 v137, 1.0, v142
	v_rcp_f32_e32 v142, v137
	v_add_f32_e32 v137, 1.0, v143
	v_add_u32_e32 v132, 0x90, v128
	v_mov_b32_e32 v133, v129
	v_rcp_f32_e32 v143, v137
	v_lshlrev_b64 v[132:133], 11, v[132:133]
	v_pk_mul_f32 v[134:135], v[44:45], v[134:135]
	v_pk_mul_f32 v[140:141], v[40:41], v[140:141]
	v_lshl_add_u64 v[132:133], s[50:51], 0, v[132:133]
	v_mul_f32_e32 v137, 0xbfb8aa3b, v36
	v_pk_mul_f32 v[138:139], v[46:47], v[138:139]
	v_lshl_add_u64 v[144:145], v[132:133], 0, s[4:5]
	v_cvt_pk_bf16_f32 v132, v134, v135
	v_cvt_pk_bf16_f32 v134, v140, v141
	v_exp_f32_e32 v137, v137
	v_mul_f32_e32 v140, 0xbfb8aa3b, v37
	v_pk_mul_f32 v[142:143], v[42:43], v[142:143]
	v_cvt_pk_bf16_f32 v133, v138, v139
	v_lshl_add_u64 v[138:139], v[144:145], 0, v[130:131]
	v_exp_f32_e32 v140, v140
	v_cvt_pk_bf16_f32 v135, v142, v143
	v_add_co_u32_e32 v138, vcc, s76, v138
	v_permlane16_swap_b32_e32 v132, v134
	v_permlane16_swap_b32_e32 v133, v135
	v_addc_co_u32_e32 v139, vcc, 0, v139, vcc
	global_store_dwordx4 v[138:139], v[132:135], off offset:2048 nt
	s_nop 1
	v_add_f32_e32 v132, 1.0, v137
	v_mul_f32_e32 v137, 0xbfb8aa3b, v32
	v_add_f32_e32 v133, 1.0, v140
	v_exp_f32_e32 v137, v137
	v_mul_f32_e32 v140, 0xbfb8aa3b, v33
	v_exp_f32_e32 v141, v140
	v_mul_f32_e32 v134, 0xbfb8aa3b, v38
	v_add_f32_e32 v137, 1.0, v137
	v_rcp_f32_e32 v140, v137
	v_add_f32_e32 v137, 1.0, v141
	v_mul_f32_e32 v141, 0xbfb8aa3b, v34
	v_mul_f32_e32 v135, 0xbfb8aa3b, v39
	v_exp_f32_e32 v142, v141
	v_mul_f32_e32 v141, 0xbfb8aa3b, v35
	v_exp_f32_e32 v134, v134
	v_exp_f32_e32 v135, v135
	v_exp_f32_e32 v143, v141
	v_rcp_f32_e32 v141, v137
	v_add_f32_e32 v137, 1.0, v142
	v_add_f32_e32 v134, 1.0, v134
	v_add_f32_e32 v135, 1.0, v135
	v_rcp_f32_e32 v142, v137
	v_add_f32_e32 v137, 1.0, v143
	v_rcp_f32_e32 v132, v132
	v_rcp_f32_e32 v133, v133
	v_rcp_f32_e32 v134, v134
	v_rcp_f32_e32 v135, v135
	v_rcp_f32_e32 v143, v137
	v_pk_mul_f32 v[132:133], v[36:37], v[132:133]
	v_pk_mul_f32 v[140:141], v[32:33], v[140:141]
	v_pk_mul_f32 v[134:135], v[38:39], v[134:135]
	v_pk_mul_f32 v[142:143], v[34:35], v[142:143]
	v_cvt_pk_bf16_f32 v132, v132, v133
	v_cvt_pk_bf16_f32 v133, v134, v135
	v_cvt_pk_bf16_f32 v134, v140, v141
	v_cvt_pk_bf16_f32 v135, v142, v143
	s_nop 0
	v_permlane16_swap_b32_e32 v132, v134
	v_permlane16_swap_b32_e32 v133, v135
	v_mul_f32_e32 v137, 0xbfb8aa3b, v30
	global_store_dwordx4 v[138:139], v[132:135], off offset:2304 nt
	v_exp_f32_e32 v137, v137
	v_mul_f32_e32 v138, 0xbfb8aa3b, v31
	v_exp_f32_e32 v139, v138
	v_mul_f32_e32 v134, 0xbfb8aa3b, v28
	v_add_f32_e32 v137, 1.0, v137
	v_rcp_f32_e32 v138, v137
	v_add_f32_e32 v137, 1.0, v139
	v_mul_f32_e32 v139, 0xbfb8aa3b, v24
	v_exp_f32_e32 v140, v139
	v_mul_f32_e32 v139, 0xbfb8aa3b, v25
	v_exp_f32_e32 v141, v139
	v_mul_f32_e32 v135, 0xbfb8aa3b, v29
	v_rcp_f32_e32 v139, v137
	v_add_f32_e32 v137, 1.0, v140
	v_exp_f32_e32 v134, v134
	v_exp_f32_e32 v135, v135
	v_rcp_f32_e32 v140, v137
	v_add_f32_e32 v137, 1.0, v141
	v_mul_f32_e32 v141, 0xbfb8aa3b, v26
	v_exp_f32_e32 v142, v141
	v_mul_f32_e32 v141, 0xbfb8aa3b, v27
	v_exp_f32_e32 v143, v141
	v_add_f32_e32 v134, 1.0, v134
	v_add_f32_e32 v135, 1.0, v135
	v_rcp_f32_e32 v134, v134
	v_rcp_f32_e32 v135, v135
	v_rcp_f32_e32 v141, v137
	v_add_f32_e32 v137, 1.0, v142
	v_rcp_f32_e32 v142, v137
	v_add_f32_e32 v137, 1.0, v143
	v_add_u32_e32 v132, 0xa0, v128
	v_mov_b32_e32 v133, v129
	v_rcp_f32_e32 v143, v137
	v_lshlrev_b64 v[132:133], 11, v[132:133]
	v_pk_mul_f32 v[134:135], v[28:29], v[134:135]
	v_pk_mul_f32 v[140:141], v[24:25], v[140:141]
	v_lshl_add_u64 v[132:133], s[50:51], 0, v[132:133]
	v_mul_f32_e32 v137, 0xbfb8aa3b, v20
	v_pk_mul_f32 v[138:139], v[30:31], v[138:139]
	v_lshl_add_u64 v[144:145], v[132:133], 0, s[4:5]
	v_cvt_pk_bf16_f32 v132, v134, v135
	v_cvt_pk_bf16_f32 v134, v140, v141
	v_exp_f32_e32 v137, v137
	v_mul_f32_e32 v140, 0xbfb8aa3b, v21
	v_pk_mul_f32 v[142:143], v[26:27], v[142:143]
	v_cvt_pk_bf16_f32 v133, v138, v139
	v_lshl_add_u64 v[138:139], v[144:145], 0, v[130:131]
	v_exp_f32_e32 v140, v140
	v_cvt_pk_bf16_f32 v135, v142, v143
	v_add_co_u32_e32 v138, vcc, s76, v138
	v_permlane16_swap_b32_e32 v132, v134
	v_permlane16_swap_b32_e32 v133, v135
	v_addc_co_u32_e32 v139, vcc, 0, v139, vcc
	global_store_dwordx4 v[138:139], v[132:135], off offset:2048 nt
	v_add_u32_e32 v128, 0xb0, v128
	s_nop 0
	v_add_f32_e32 v132, 1.0, v137
	v_mul_f32_e32 v137, 0xbfb8aa3b, v16
	v_add_f32_e32 v133, 1.0, v140
	v_exp_f32_e32 v137, v137
	v_mul_f32_e32 v140, 0xbfb8aa3b, v17
	v_exp_f32_e32 v141, v140
	v_mul_f32_e32 v134, 0xbfb8aa3b, v22
	v_add_f32_e32 v137, 1.0, v137
	v_rcp_f32_e32 v140, v137
	v_add_f32_e32 v137, 1.0, v141
	v_mul_f32_e32 v141, 0xbfb8aa3b, v18
	v_mul_f32_e32 v135, 0xbfb8aa3b, v23
	v_exp_f32_e32 v142, v141
	v_mul_f32_e32 v141, 0xbfb8aa3b, v19
	v_exp_f32_e32 v134, v134
	v_exp_f32_e32 v135, v135
	v_exp_f32_e32 v143, v141
	v_rcp_f32_e32 v141, v137
	v_add_f32_e32 v137, 1.0, v142
	v_add_f32_e32 v134, 1.0, v134
	v_add_f32_e32 v135, 1.0, v135
	v_rcp_f32_e32 v142, v137
	v_add_f32_e32 v137, 1.0, v143
	v_rcp_f32_e32 v132, v132
	v_rcp_f32_e32 v133, v133
	v_rcp_f32_e32 v134, v134
; __device__ __forceinline__ u32x2 pack4(f32x4 v) { u32x2 r; r.x = cvt_pk(v[0], v[1]); r.y = cvt_pk(v[2], v[3]); return r; }
; __device__ __forceinline__ float silu_f(float x) { return x * __builtin_amdgcn_rcpf(1.f + __builtin_amdgcn_exp2f(-1.4426950409f * x)); }
; __device__ __forceinline__ float gelu_f(float v) {
;   const float av = fabsf(v), t = __builtin_amdgcn_rcpf(av * 0.2316418882f + 1.0f);
;   float q = t * 0.5307027145f + (-0.7265760135f); q = q * t + 0.7107068705f; q = q * t + (-0.142248368f); q = q * t + 0.127414796f; q = q * t;
;   const float e = __builtin_amdgcn_exp2f((v * v) * (-0.72134752044f));
;   const float m = v * (q * e), r = v - m;
;   return v < 0.f ? m : r;
; }
; template <int SEC> __device__ __forceinline__ void epiB2(const Params& p, int row, int col32, f32x4 v0, f32x4 v1, int fq) {
;     ...
;   if (SEC == 0) { f32x4 o0 = {gelu_f(v0[0]), gelu_f(v0[1]), gelu_f(v0[2]), gelu_f(v0[3])}, o1 = {gelu_f(v1[0]), gelu_f(v1[1]), gelu_f(v1[2]), gelu_f(v1[3])};
;     store_pair16((u16*)(ws + OFF_UV) + (size_t)row * 1024 + col32, pack4(o0), pack4(o1), fq); }
;   else if (SEC == 1) { f32x4 o0 = {silu_f(v0[0]), silu_f(v0[1]), silu_f(v0[2]), silu_f(v0[3])}, o1 = {silu_f(v1[0]), silu_f(v1[1]), silu_f(v1[2]), silu_f(v1[3])};
;     store_pair16((u16*)(ws + OFF_ZS) + (size_t)row * 1024 + (col32 - 1024), pack4(o0), pack4(o1), fq); }
	v_rcp_f32_e32 v135, v135
	v_rcp_f32_e32 v143, v137
	v_pk_mul_f32 v[132:133], v[20:21], v[132:133]
	v_pk_mul_f32 v[140:141], v[16:17], v[140:141]
	v_pk_mul_f32 v[134:135], v[22:23], v[134:135]
	v_pk_mul_f32 v[142:143], v[18:19], v[142:143]
	v_cvt_pk_bf16_f32 v132, v132, v133
	v_cvt_pk_bf16_f32 v133, v134, v135
	v_cvt_pk_bf16_f32 v134, v140, v141
	v_cvt_pk_bf16_f32 v135, v142, v143
	s_nop 0
	v_permlane16_swap_b32_e32 v132, v134
	v_permlane16_swap_b32_e32 v133, v135
	global_store_dwordx4 v[138:139], v[132:135], off offset:2304 nt
	s_nop 1
	v_mul_f32_e32 v132, 0xbfb8aa3b, v12
	v_exp_f32_e32 v134, v132
	v_mul_f32_e32 v132, 0xbfb8aa3b, v13
	v_exp_f32_e32 v135, v132
	v_lshlrev_b64 v[132:133], 11, v[128:129]
	v_add_f32_e32 v128, 1.0, v134
	v_rcp_f32_e32 v134, v128
	v_add_f32_e32 v128, 1.0, v135
	v_mul_f32_e32 v135, 0xbfb8aa3b, v14
	v_exp_f32_e32 v137, v135
	v_mul_f32_e32 v135, 0xbfb8aa3b, v15
	v_exp_f32_e32 v139, v135
	v_rcp_f32_e32 v135, v128
	v_add_f32_e32 v128, 1.0, v137
	v_mul_f32_e32 v137, 0xbfb8aa3b, v8
	v_rcp_f32_e32 v138, v128
	v_add_f32_e32 v128, 1.0, v139
	v_exp_f32_e32 v137, v137
	v_mul_f32_e32 v139, 0xbfb8aa3b, v9
	v_exp_f32_e32 v141, v139
	v_rcp_f32_e32 v139, v128
	v_add_f32_e32 v128, 1.0, v137
	v_mul_f32_e32 v137, 0xbfb8aa3b, v10
	v_rcp_f32_e32 v140, v128
	v_add_f32_e32 v128, 1.0, v141
	v_exp_f32_e32 v137, v137
	v_mul_f32_e32 v141, 0xbfb8aa3b, v11
	v_exp_f32_e32 v143, v141
	v_rcp_f32_e32 v141, v128
	v_add_f32_e32 v128, 1.0, v137
	v_lshl_add_u64 v[132:133], s[50:51], 0, v[132:133]
	v_rcp_f32_e32 v142, v128
	v_add_f32_e32 v128, 1.0, v143
	v_lshl_add_u64 v[144:145], v[132:133], 0, s[4:5]
	v_rcp_f32_e32 v143, v128
	v_pk_mul_f32 v[138:139], v[14:15], v[138:139]
	v_lshl_add_u64 v[130:131], v[144:145], 0, v[130:131]
	v_mul_f32_e32 v128, 0xbfb8aa3b, v4
	v_cvt_pk_bf16_f32 v133, v138, v139
	v_add_co_u32_e32 v138, vcc, s76, v130
	v_exp_f32_e32 v128, v128
	v_mul_f32_e32 v130, 0xbfb8aa3b, v5
	v_addc_co_u32_e32 v139, vcc, 0, v131, vcc
	v_exp_f32_e32 v131, v130
	v_pk_mul_f32 v[134:135], v[12:13], v[134:135]
	v_pk_mul_f32 v[140:141], v[8:9], v[140:141]
	v_pk_mul_f32 v[142:143], v[10:11], v[142:143]
	v_cvt_pk_bf16_f32 v132, v134, v135
	v_cvt_pk_bf16_f32 v134, v140, v141
	v_cvt_pk_bf16_f32 v135, v142, v143
	v_add_f32_e32 v128, 1.0, v128
	v_permlane16_swap_b32_e32 v132, v134
	v_permlane16_swap_b32_e32 v133, v135
	v_rcp_f32_e32 v130, v128
	v_add_f32_e32 v128, 1.0, v131
	v_mul_f32_e32 v131, 0xbfb8aa3b, v6
	global_store_dwordx4 v[138:139], v[132:135], off offset:2048 nt
	s_mov_b64 s[4:5], 0
	s_nop 0
	v_exp_f32_e32 v132, v131
	v_mul_f32_e32 v131, 0xbfb8aa3b, v7
	v_exp_f32_e32 v133, v131
	v_rcp_f32_e32 v131, v128
	v_add_f32_e32 v128, 1.0, v132
	v_rcp_f32_e32 v132, v128
	v_add_f32_e32 v128, 1.0, v133
	v_mul_f32_e32 v133, 0xbfb8aa3b, v0
	v_exp_f32_e32 v134, v133
	v_mul_f32_e32 v133, 0xbfb8aa3b, v1
	v_exp_f32_e32 v135, v133
	v_rcp_f32_e32 v133, v128
	v_add_f32_e32 v128, 1.0, v134
	v_rcp_f32_e32 v134, v128
	v_add_f32_e32 v128, 1.0, v135
	v_mul_f32_e32 v135, 0xbfb8aa3b, v2
	v_exp_f32_e32 v137, v135
	v_mul_f32_e32 v135, 0xbfb8aa3b, v3
	v_exp_f32_e32 v141, v135
	v_rcp_f32_e32 v135, v128
	v_add_f32_e32 v128, 1.0, v137
	v_rcp_f32_e32 v140, v128
	v_add_f32_e32 v128, 1.0, v141
	v_rcp_f32_e32 v141, v128
	v_pk_mul_f32 v[130:131], v[4:5], v[130:131]
	v_pk_mul_f32 v[132:133], v[6:7], v[132:133]
	v_pk_mul_f32 v[134:135], v[0:1], v[134:135]
	v_pk_mul_f32 v[140:141], v[2:3], v[140:141]
	v_cvt_pk_bf16_f32 v130, v130, v131
	v_cvt_pk_bf16_f32 v131, v132, v133
	v_cvt_pk_bf16_f32 v132, v134, v135
	v_cvt_pk_bf16_f32 v133, v140, v141
	s_nop 0
	v_permlane16_swap_b32_e32 v130, v132
	v_permlane16_swap_b32_e32 v131, v133
	global_store_dwordx4 v[138:139], v[130:133], off offset:2304 nt
.LBB0_219:
	s_andn2_b64 vcc, exec, s[4:5]
	s_cbranch_vccnz .LBB0_189
	v_mbcnt_lo_u32_b32 v130, -1, 0
	v_mbcnt_hi_u32_b32 v130, -1, v130
	s_or_b32 s4, s38, s66
	v_and_or_b32 v128, v130, 15, s33
	v_and_b32_e32 v131, 16, v130
	v_ashrrev_i32_e32 v130, 2, v130
	v_and_b32_e32 v130, -8, v130
	v_add_u32_e32 v132, v130, v131
	v_fma_f32 v130, |v124|, s77, 1.0
	v_rcp_f32_e32 v138, v130
	v_mul_f32_e32 v130, v124, v124
	v_mul_f32_e32 v130, 0xbf38aa3b, v130
	v_exp_f32_e32 v140, v130
	v_fma_f32 v130, |v125|, s77, 1.0
	v_rcp_f32_e32 v139, v130
	v_mul_f32_e32 v130, v125, v125
	v_mul_f32_e32 v130, 0xbf38aa3b, v130
	s_mov_b32 s38, 0xbf3a00e3
	v_exp_f32_e32 v141, v130
	v_mov_b64_e32 v[130:131], s[38:39]
	v_pk_fma_f32 v[142:143], v[138:139], s[26:27], v[130:131] op_sel_hi:[1,0,0]
	v_cmp_gt_f32_e32 vcc, 0, v125
	v_pk_fma_f32 v[142:143], v[138:139], v[142:143], s[28:29] op_sel_hi:[1,1,0]
	v_lshlrev_b64 v[134:135], 11, v[128:129]
	v_pk_fma_f32 v[142:143], v[138:139], v[142:143], s[30:31] op_sel_hi:[1,1,0]
	s_ashr_i32 s5, s4, 31
	v_pk_fma_f32 v[142:143], v[138:139], v[142:143], s[34:35] op_sel_hi:[1,1,0]
	v_ashrrev_i32_e32 v133, 31, v132
	v_pk_mul_f32 v[138:139], v[138:139], v[142:143]
	s_lshl_b64 s[4:5], s[4:5], 1
	v_pk_mul_f32 v[138:139], v[140:141], v[138:139]
	s_nop 0
	v_pk_mul_f32 v[140:141], v[124:125], v[138:139]
	v_pk_fma_f32 v[138:139], v[124:125], v[138:139], v[124:125] neg_lo:[1,0,0] neg_hi:[1,0,0]
	v_mul_f32_e32 v125, v126, v126
	v_cndmask_b32_e32 v137, v139, v141, vcc
	v_cmp_gt_f32_e32 vcc, 0, v124
	v_mul_f32_e32 v125, 0xbf38aa3b, v125
	v_fma_f32 v124, |v126|, s77, 1.0
	v_cndmask_b32_e32 v142, v138, v140, vcc
	v_exp_f32_e32 v138, v125
	v_fma_f32 v125, |v127|, s77, 1.0
	v_rcp_f32_e32 v124, v124
	v_rcp_f32_e32 v125, v125
	v_mul_f32_e32 v139, v127, v127
	v_mul_f32_e32 v139, 0xbf38aa3b, v139
	v_exp_f32_e32 v139, v139
	v_pk_fma_f32 v[140:141], v[124:125], s[26:27], v[130:131] op_sel_hi:[1,0,0]
	v_cmp_gt_f32_e32 vcc, 0, v127
; __device__ __forceinline__ u32x2 pack4(f32x4 v) { u32x2 r; r.x = cvt_pk(v[0], v[1]); r.y = cvt_pk(v[2], v[3]); return r; }
; __device__ __forceinline__ float gelu_f(float v) {
;   const float av = fabsf(v), t = __builtin_amdgcn_rcpf(av * 0.2316418882f + 1.0f);
;   float q = t * 0.5307027145f + (-0.7265760135f); q = q * t + 0.7107068705f; q = q * t + (-0.142248368f); q = q * t + 0.127414796f; q = q * t;
;   const float e = __builtin_amdgcn_exp2f((v * v) * (-0.72134752044f));
;   const float m = v * (q * e), r = v - m;
;   return v < 0.f ? m : r;
; }
; template <int SEC> __device__ __forceinline__ void epiB2(const Params& p, int row, int col32, f32x4 v0, f32x4 v1, int fq) {
;     ...
;   if (SEC == 0) { f32x4 o0 = {gelu_f(v0[0]), gelu_f(v0[1]), gelu_f(v0[2]), gelu_f(v0[3])}, o1 = {gelu_f(v1[0]), gelu_f(v1[1]), gelu_f(v1[2]), gelu_f(v1[3])};
;     store_pair16((u16*)(ws + OFF_UV) + (size_t)row * 1024 + col32, pack4(o0), pack4(o1), fq); }
	v_pk_fma_f32 v[140:141], v[124:125], v[140:141], s[28:29] op_sel_hi:[1,1,0]
	s_nop 0
	v_pk_fma_f32 v[140:141], v[124:125], v[140:141], s[30:31] op_sel_hi:[1,1,0]
	s_nop 0
	v_pk_fma_f32 v[140:141], v[124:125], v[140:141], s[34:35] op_sel_hi:[1,1,0]
	s_nop 0
	v_pk_mul_f32 v[124:125], v[124:125], v[140:141]
	s_nop 0
	v_pk_mul_f32 v[124:125], v[138:139], v[124:125]
	s_nop 0
	v_pk_mul_f32 v[138:139], v[126:127], v[124:125]
	v_pk_fma_f32 v[124:125], v[126:127], v[124:125], v[126:127] neg_lo:[1,0,0] neg_hi:[1,0,0]
	v_mul_f32_e32 v127, v121, v121
	v_cndmask_b32_e32 v140, v125, v139, vcc
	v_mul_f32_e32 v125, v120, v120
	v_cmp_gt_f32_e32 vcc, 0, v126
	v_mul_f32_e32 v125, 0xbf38aa3b, v125
	v_exp_f32_e32 v126, v125
	v_cndmask_b32_e32 v141, v124, v138, vcc
	v_fma_f32 v124, |v120|, s77, 1.0
	v_fma_f32 v125, |v121|, s77, 1.0
	v_rcp_f32_e32 v124, v124
	v_rcp_f32_e32 v125, v125
	v_mul_f32_e32 v127, 0xbf38aa3b, v127
	v_exp_f32_e32 v127, v127
	v_cmp_gt_f32_e32 vcc, 0, v121
	v_pk_fma_f32 v[138:139], v[124:125], s[26:27], v[130:131] op_sel_hi:[1,0,0]
	s_nop 0
	v_pk_fma_f32 v[138:139], v[124:125], v[138:139], s[28:29] op_sel_hi:[1,1,0]
	s_nop 0
	v_pk_fma_f32 v[138:139], v[124:125], v[138:139], s[30:31] op_sel_hi:[1,1,0]
	s_nop 0
	v_pk_fma_f32 v[138:139], v[124:125], v[138:139], s[34:35] op_sel_hi:[1,1,0]
	s_nop 0
	v_pk_mul_f32 v[124:125], v[124:125], v[138:139]
	s_nop 0
	v_pk_mul_f32 v[124:125], v[126:127], v[124:125]
	s_nop 0
	v_pk_mul_f32 v[126:127], v[120:121], v[124:125]
	v_pk_fma_f32 v[124:125], v[120:121], v[124:125], v[120:121] neg_lo:[1,0,0] neg_hi:[1,0,0]
	v_mul_f32_e32 v121, v122, v122
	v_cndmask_b32_e32 v138, v125, v127, vcc
	v_cmp_gt_f32_e32 vcc, 0, v120
	v_mul_f32_e32 v121, 0xbf38aa3b, v121
	v_fma_f32 v120, |v122|, s77, 1.0
	v_cndmask_b32_e32 v139, v124, v126, vcc
	v_exp_f32_e32 v124, v121
	v_fma_f32 v121, |v123|, s77, 1.0
	v_rcp_f32_e32 v120, v120
	v_rcp_f32_e32 v121, v121
	v_mul_f32_e32 v125, v123, v123
	v_mul_f32_e32 v125, 0xbf38aa3b, v125
	v_exp_f32_e32 v125, v125
	v_pk_fma_f32 v[126:127], v[120:121], s[26:27], v[130:131] op_sel_hi:[1,0,0]
	v_cmp_gt_f32_e32 vcc, 0, v123
	v_pk_fma_f32 v[126:127], v[120:121], v[126:127], s[28:29] op_sel_hi:[1,1,0]
	s_nop 0
	v_pk_fma_f32 v[126:127], v[120:121], v[126:127], s[30:31] op_sel_hi:[1,1,0]
	s_nop 0
	v_pk_fma_f32 v[126:127], v[120:121], v[126:127], s[34:35] op_sel_hi:[1,1,0]
	s_nop 0
	v_pk_mul_f32 v[120:121], v[120:121], v[126:127]
	s_nop 0
	v_pk_mul_f32 v[120:121], v[124:125], v[120:121]
	s_nop 0
	v_pk_mul_f32 v[124:125], v[122:123], v[120:121]
	v_pk_fma_f32 v[120:121], v[122:123], v[120:121], v[122:123] neg_lo:[1,0,0] neg_hi:[1,0,0]
	v_cvt_pk_bf16_f32 v123, v141, v140
	v_cndmask_b32_e32 v125, v121, v125, vcc
	v_cmp_gt_f32_e32 vcc, 0, v122
	v_cvt_pk_bf16_f32 v122, v142, v137
	s_nop 0
	v_cndmask_b32_e32 v143, v120, v124, vcc
	v_lshl_add_u64 v[120:121], s[10:11], 0, v[134:135]
	v_lshl_add_u64 v[126:127], v[120:121], 0, s[4:5]
	v_cvt_pk_bf16_f32 v124, v139, v138
	v_cvt_pk_bf16_f32 v125, v143, v125
	v_lshlrev_b64 v[120:121], 1, v[132:133]
	v_permlane16_swap_b32_e32 v122, v124
	v_permlane16_swap_b32_e32 v123, v125
	v_lshl_add_u64 v[126:127], v[126:127], 0, v[120:121]
	global_store_dwordx4 v[126:127], v[122:125], off nt
	v_cmp_gt_f32_e32 vcc, 0, v117
	s_nop 0
	v_mul_f32_e32 v123, v116, v116
	v_mul_f32_e32 v123, 0xbf38aa3b, v123
	v_fma_f32 v122, |v116|, s77, 1.0
	v_exp_f32_e32 v124, v123
	v_fma_f32 v123, |v117|, s77, 1.0
	v_rcp_f32_e32 v122, v122
	v_rcp_f32_e32 v123, v123
	v_mul_f32_e32 v125, v117, v117
	v_mul_f32_e32 v125, 0xbf38aa3b, v125
	v_exp_f32_e32 v125, v125
	v_pk_fma_f32 v[132:133], v[122:123], s[26:27], v[130:131] op_sel_hi:[1,0,0]
	s_nop 0
	v_pk_fma_f32 v[132:133], v[122:123], v[132:133], s[28:29] op_sel_hi:[1,1,0]
	s_nop 0
	v_pk_fma_f32 v[132:133], v[122:123], v[132:133], s[30:31] op_sel_hi:[1,1,0]
	s_nop 0
	v_pk_fma_f32 v[132:133], v[122:123], v[132:133], s[34:35] op_sel_hi:[1,1,0]
	s_nop 0
	v_pk_mul_f32 v[122:123], v[122:123], v[132:133]
	s_nop 0
	v_pk_mul_f32 v[122:123], v[124:125], v[122:123]
	s_nop 0
	v_pk_mul_f32 v[124:125], v[116:117], v[122:123]
	v_pk_fma_f32 v[122:123], v[116:117], v[122:123], v[116:117] neg_lo:[1,0,0] neg_hi:[1,0,0]
	v_mul_f32_e32 v117, v118, v118
	v_cndmask_b32_e32 v132, v123, v125, vcc
	v_cmp_gt_f32_e32 vcc, 0, v116
	v_mul_f32_e32 v117, 0xbf38aa3b, v117
	v_fma_f32 v116, |v118|, s77, 1.0
	v_cndmask_b32_e32 v133, v122, v124, vcc
	v_exp_f32_e32 v122, v117
	v_fma_f32 v117, |v119|, s77, 1.0
	v_rcp_f32_e32 v116, v116
	v_rcp_f32_e32 v117, v117
	v_mul_f32_e32 v123, v119, v119
	v_mul_f32_e32 v123, 0xbf38aa3b, v123
	v_exp_f32_e32 v123, v123
	v_pk_fma_f32 v[124:125], v[116:117], s[26:27], v[130:131] op_sel_hi:[1,0,0]
	v_cmp_gt_f32_e32 vcc, 0, v119
	v_pk_fma_f32 v[124:125], v[116:117], v[124:125], s[28:29] op_sel_hi:[1,1,0]
	s_nop 0
	v_pk_fma_f32 v[124:125], v[116:117], v[124:125], s[30:31] op_sel_hi:[1,1,0]
	s_nop 0
	v_pk_fma_f32 v[124:125], v[116:117], v[124:125], s[34:35] op_sel_hi:[1,1,0]
	s_nop 0
	v_pk_mul_f32 v[116:117], v[116:117], v[124:125]
	s_nop 0
	v_pk_mul_f32 v[116:117], v[122:123], v[116:117]
	s_nop 0
	v_pk_mul_f32 v[122:123], v[118:119], v[116:117]
	v_pk_fma_f32 v[116:117], v[118:119], v[116:117], v[118:119] neg_lo:[1,0,0] neg_hi:[1,0,0]
	v_mul_f32_e32 v119, v113, v113
	v_cndmask_b32_e32 v124, v117, v123, vcc
	v_mul_f32_e32 v117, v112, v112
	v_cmp_gt_f32_e32 vcc, 0, v118
	v_mul_f32_e32 v117, 0xbf38aa3b, v117
	v_exp_f32_e32 v118, v117
	v_cndmask_b32_e32 v125, v116, v122, vcc
	v_fma_f32 v116, |v112|, s77, 1.0
	v_fma_f32 v117, |v113|, s77, 1.0
	v_rcp_f32_e32 v116, v116
	v_rcp_f32_e32 v117, v117
	v_mul_f32_e32 v119, 0xbf38aa3b, v119
	v_exp_f32_e32 v119, v119
; __device__ __forceinline__ u32x2 pack4(f32x4 v) { u32x2 r; r.x = cvt_pk(v[0], v[1]); r.y = cvt_pk(v[2], v[3]); return r; }
; __device__ __forceinline__ float gelu_f(float v) {
;   const float av = fabsf(v), t = __builtin_amdgcn_rcpf(av * 0.2316418882f + 1.0f);
;   float q = t * 0.5307027145f + (-0.7265760135f); q = q * t + 0.7107068705f; q = q * t + (-0.142248368f); q = q * t + 0.127414796f; q = q * t;
;   const float e = __builtin_amdgcn_exp2f((v * v) * (-0.72134752044f));
;   const float m = v * (q * e), r = v - m;
;   return v < 0.f ? m : r;
; }
; template <int SEC> __device__ __forceinline__ void epiB2(const Params& p, int row, int col32, f32x4 v0, f32x4 v1, int fq) {
;     ...
;   if (SEC == 0) { f32x4 o0 = {gelu_f(v0[0]), gelu_f(v0[1]), gelu_f(v0[2]), gelu_f(v0[3])}, o1 = {gelu_f(v1[0]), gelu_f(v1[1]), gelu_f(v1[2]), gelu_f(v1[3])};
;     store_pair16((u16*)(ws + OFF_UV) + (size_t)row * 1024 + col32, pack4(o0), pack4(o1), fq); }
	v_cmp_gt_f32_e32 vcc, 0, v113
	v_pk_fma_f32 v[122:123], v[116:117], s[26:27], v[130:131] op_sel_hi:[1,0,0]
	s_nop 0
	v_pk_fma_f32 v[122:123], v[116:117], v[122:123], s[28:29] op_sel_hi:[1,1,0]
	s_nop 0
	v_pk_fma_f32 v[122:123], v[116:117], v[122:123], s[30:31] op_sel_hi:[1,1,0]
	s_nop 0
	v_pk_fma_f32 v[122:123], v[116:117], v[122:123], s[34:35] op_sel_hi:[1,1,0]
	s_nop 0
	v_pk_mul_f32 v[116:117], v[116:117], v[122:123]
	s_nop 0
	v_pk_mul_f32 v[116:117], v[118:119], v[116:117]
	s_nop 0
	v_pk_mul_f32 v[118:119], v[112:113], v[116:117]
	v_pk_fma_f32 v[116:117], v[112:113], v[116:117], v[112:113] neg_lo:[1,0,0] neg_hi:[1,0,0]
	v_mul_f32_e32 v113, v114, v114
	v_cndmask_b32_e32 v122, v117, v119, vcc
	v_cmp_gt_f32_e32 vcc, 0, v112
	v_mul_f32_e32 v113, 0xbf38aa3b, v113
	v_fma_f32 v112, |v114|, s77, 1.0
	v_cndmask_b32_e32 v123, v116, v118, vcc
	v_exp_f32_e32 v116, v113
	v_fma_f32 v113, |v115|, s77, 1.0
	v_rcp_f32_e32 v112, v112
	v_rcp_f32_e32 v113, v113
	v_mul_f32_e32 v117, v115, v115
	v_mul_f32_e32 v117, 0xbf38aa3b, v117
	v_exp_f32_e32 v117, v117
	v_pk_fma_f32 v[118:119], v[112:113], s[26:27], v[130:131] op_sel_hi:[1,0,0]
	v_cmp_gt_f32_e32 vcc, 0, v115
	v_pk_fma_f32 v[118:119], v[112:113], v[118:119], s[28:29] op_sel_hi:[1,1,0]
	s_nop 0
	v_pk_fma_f32 v[118:119], v[112:113], v[118:119], s[30:31] op_sel_hi:[1,1,0]
	s_nop 0
	v_pk_fma_f32 v[118:119], v[112:113], v[118:119], s[34:35] op_sel_hi:[1,1,0]
	s_nop 0
	v_pk_mul_f32 v[112:113], v[112:113], v[118:119]
	s_nop 0
	v_pk_mul_f32 v[112:113], v[116:117], v[112:113]
	s_nop 0
	v_pk_mul_f32 v[116:117], v[114:115], v[112:113]
	v_pk_fma_f32 v[112:113], v[114:115], v[112:113], v[114:115] neg_lo:[1,0,0] neg_hi:[1,0,0]
	s_nop 0
	v_cndmask_b32_e32 v115, v113, v117, vcc
	v_cmp_gt_f32_e32 vcc, 0, v114
	v_cvt_pk_bf16_f32 v113, v125, v124
	v_cvt_pk_bf16_f32 v114, v123, v122
	v_cndmask_b32_e32 v116, v112, v116, vcc
	v_cvt_pk_bf16_f32 v112, v133, v132
	v_cvt_pk_bf16_f32 v115, v116, v115
	s_nop 0
	v_permlane16_swap_b32_e32 v112, v114
	v_permlane16_swap_b32_e32 v113, v115
	global_store_dwordx4 v[126:127], v[112:115], off offset:256 nt
	v_mul_f32_e32 v117, v109, v109
	v_mul_f32_e32 v117, 0xbf38aa3b, v117
	v_mul_f32_e32 v115, v108, v108
	v_mul_f32_e32 v115, 0xbf38aa3b, v115
	v_fma_f32 v114, |v108|, s77, 1.0
	v_exp_f32_e32 v116, v115
	v_fma_f32 v115, |v109|, s77, 1.0
	v_rcp_f32_e32 v114, v114
	v_rcp_f32_e32 v115, v115
	v_exp_f32_e32 v117, v117
	v_cmp_gt_f32_e32 vcc, 0, v109
	v_or_b32_e32 v112, 16, v128
	v_pk_fma_f32 v[118:119], v[114:115], s[26:27], v[130:131] op_sel_hi:[1,0,0]
	v_mov_b32_e32 v113, v129
	v_pk_fma_f32 v[118:119], v[114:115], v[118:119], s[28:29] op_sel_hi:[1,1,0]
	v_lshlrev_b64 v[112:113], 11, v[112:113]
	v_pk_fma_f32 v[118:119], v[114:115], v[118:119], s[30:31] op_sel_hi:[1,1,0]
	s_nop 0
	v_pk_fma_f32 v[118:119], v[114:115], v[118:119], s[34:35] op_sel_hi:[1,1,0]
	s_nop 0
	v_pk_mul_f32 v[114:115], v[114:115], v[118:119]
	s_nop 0
	v_pk_mul_f32 v[114:115], v[116:117], v[114:115]
	s_nop 0
	v_pk_mul_f32 v[116:117], v[108:109], v[114:115]
	v_pk_fma_f32 v[114:115], v[108:109], v[114:115], v[108:109] neg_lo:[1,0,0] neg_hi:[1,0,0]
	v_mul_f32_e32 v109, v110, v110
	v_cndmask_b32_e32 v118, v115, v117, vcc
	v_cmp_gt_f32_e32 vcc, 0, v108
	v_mul_f32_e32 v109, 0xbf38aa3b, v109
	v_fma_f32 v108, |v110|, s77, 1.0
	v_cndmask_b32_e32 v119, v114, v116, vcc
	v_exp_f32_e32 v114, v109
	v_fma_f32 v109, |v111|, s77, 1.0
	v_rcp_f32_e32 v108, v108
	v_rcp_f32_e32 v109, v109
	v_mul_f32_e32 v115, v111, v111
	v_mul_f32_e32 v115, 0xbf38aa3b, v115
	v_exp_f32_e32 v115, v115
	v_pk_fma_f32 v[116:117], v[108:109], s[26:27], v[130:131] op_sel_hi:[1,0,0]
	v_cmp_gt_f32_e32 vcc, 0, v111
	v_pk_fma_f32 v[116:117], v[108:109], v[116:117], s[28:29] op_sel_hi:[1,1,0]
	s_nop 0
	v_pk_fma_f32 v[116:117], v[108:109], v[116:117], s[30:31] op_sel_hi:[1,1,0]
	s_nop 0
	v_pk_fma_f32 v[116:117], v[108:109], v[116:117], s[34:35] op_sel_hi:[1,1,0]
	s_nop 0
	v_pk_mul_f32 v[108:109], v[108:109], v[116:117]
	s_nop 0
	v_pk_mul_f32 v[108:109], v[114:115], v[108:109]
	s_nop 0
	v_pk_mul_f32 v[114:115], v[110:111], v[108:109]
	v_pk_fma_f32 v[108:109], v[110:111], v[108:109], v[110:111] neg_lo:[1,0,0] neg_hi:[1,0,0]
	v_mul_f32_e32 v111, v105, v105
	v_cndmask_b32_e32 v116, v109, v115, vcc
	v_mul_f32_e32 v109, v104, v104
	v_cmp_gt_f32_e32 vcc, 0, v110
	v_mul_f32_e32 v109, 0xbf38aa3b, v109
	v_exp_f32_e32 v110, v109
	v_cndmask_b32_e32 v117, v108, v114, vcc
	v_fma_f32 v108, |v104|, s77, 1.0
	v_fma_f32 v109, |v105|, s77, 1.0
	v_rcp_f32_e32 v108, v108
	v_rcp_f32_e32 v109, v109
	v_mul_f32_e32 v111, 0xbf38aa3b, v111
	v_exp_f32_e32 v111, v111
	v_cmp_gt_f32_e32 vcc, 0, v105
	v_pk_fma_f32 v[114:115], v[108:109], s[26:27], v[130:131] op_sel_hi:[1,0,0]
	s_nop 0
	v_pk_fma_f32 v[114:115], v[108:109], v[114:115], s[28:29] op_sel_hi:[1,1,0]
	s_nop 0
	v_pk_fma_f32 v[114:115], v[108:109], v[114:115], s[30:31] op_sel_hi:[1,1,0]
	s_nop 0
	v_pk_fma_f32 v[114:115], v[108:109], v[114:115], s[34:35] op_sel_hi:[1,1,0]
	s_nop 0
	v_pk_mul_f32 v[108:109], v[108:109], v[114:115]
	s_nop 0
	v_pk_mul_f32 v[108:109], v[110:111], v[108:109]
	s_nop 0
	v_pk_mul_f32 v[110:111], v[104:105], v[108:109]
	v_pk_fma_f32 v[108:109], v[104:105], v[108:109], v[104:105] neg_lo:[1,0,0] neg_hi:[1,0,0]
	v_mul_f32_e32 v105, v106, v106
	v_cndmask_b32_e32 v114, v109, v111, vcc
	v_cmp_gt_f32_e32 vcc, 0, v104
	v_mul_f32_e32 v105, 0xbf38aa3b, v105
	v_fma_f32 v104, |v106|, s77, 1.0
	v_cndmask_b32_e32 v115, v108, v110, vcc
	v_exp_f32_e32 v108, v105
	v_fma_f32 v105, |v107|, s77, 1.0
	v_rcp_f32_e32 v104, v104
	v_rcp_f32_e32 v105, v105
	v_mul_f32_e32 v109, v107, v107
	v_mul_f32_e32 v109, 0xbf38aa3b, v109
	v_exp_f32_e32 v109, v109
; __device__ __forceinline__ u32x2 pack4(f32x4 v) { u32x2 r; r.x = cvt_pk(v[0], v[1]); r.y = cvt_pk(v[2], v[3]); return r; }
; __device__ __forceinline__ float gelu_f(float v) {
;   const float av = fabsf(v), t = __builtin_amdgcn_rcpf(av * 0.2316418882f + 1.0f);
;   float q = t * 0.5307027145f + (-0.7265760135f); q = q * t + 0.7107068705f; q = q * t + (-0.142248368f); q = q * t + 0.127414796f; q = q * t;
;   const float e = __builtin_amdgcn_exp2f((v * v) * (-0.72134752044f));
;   const float m = v * (q * e), r = v - m;
;   return v < 0.f ? m : r;
; }
; template <int SEC> __device__ __forceinline__ void epiB2(const Params& p, int row, int col32, f32x4 v0, f32x4 v1, int fq) {
;     ...
;   if (SEC == 0) { f32x4 o0 = {gelu_f(v0[0]), gelu_f(v0[1]), gelu_f(v0[2]), gelu_f(v0[3])}, o1 = {gelu_f(v1[0]), gelu_f(v1[1]), gelu_f(v1[2]), gelu_f(v1[3])};
;     store_pair16((u16*)(ws + OFF_UV) + (size_t)row * 1024 + col32, pack4(o0), pack4(o1), fq); }
	v_pk_fma_f32 v[110:111], v[104:105], s[26:27], v[130:131] op_sel_hi:[1,0,0]
	v_cmp_gt_f32_e32 vcc, 0, v107
	v_pk_fma_f32 v[110:111], v[104:105], v[110:111], s[28:29] op_sel_hi:[1,1,0]
	s_nop 0
	v_pk_fma_f32 v[110:111], v[104:105], v[110:111], s[30:31] op_sel_hi:[1,1,0]
	s_nop 0
	v_pk_fma_f32 v[110:111], v[104:105], v[110:111], s[34:35] op_sel_hi:[1,1,0]
	s_nop 0
	v_pk_mul_f32 v[104:105], v[104:105], v[110:111]
	s_nop 0
	v_pk_mul_f32 v[104:105], v[108:109], v[104:105]
	s_nop 0
	v_pk_mul_f32 v[108:109], v[106:107], v[104:105]
	v_pk_fma_f32 v[104:105], v[106:107], v[104:105], v[106:107] neg_lo:[1,0,0] neg_hi:[1,0,0]
	s_nop 0
	v_cndmask_b32_e32 v107, v105, v109, vcc
	v_cmp_gt_f32_e32 vcc, 0, v106
	v_cvt_pk_bf16_f32 v106, v115, v114
	s_nop 0
	v_cndmask_b32_e32 v110, v104, v108, vcc
	v_lshl_add_u64 v[104:105], s[10:11], 0, v[112:113]
	v_lshl_add_u64 v[108:109], v[104:105], 0, s[4:5]
	v_cvt_pk_bf16_f32 v104, v119, v118
	v_cvt_pk_bf16_f32 v105, v117, v116
	v_cvt_pk_bf16_f32 v107, v110, v107
	v_permlane16_swap_b32_e32 v104, v106
	s_nop 0
	v_permlane16_swap_b32_e32 v105, v107
	v_lshl_add_u64 v[108:109], v[108:109], 0, v[120:121]
	global_store_dwordx4 v[108:109], v[104:107], off nt
	v_cmp_gt_f32_e32 vcc, 0, v101
	s_nop 0
	v_mul_f32_e32 v105, v100, v100
	v_mul_f32_e32 v105, 0xbf38aa3b, v105
	v_fma_f32 v104, |v100|, s77, 1.0
	v_exp_f32_e32 v106, v105
	v_fma_f32 v105, |v101|, s77, 1.0
	v_rcp_f32_e32 v104, v104
	v_rcp_f32_e32 v105, v105
	v_mul_f32_e32 v107, v101, v101
	v_mul_f32_e32 v107, 0xbf38aa3b, v107
	v_exp_f32_e32 v107, v107
	v_pk_fma_f32 v[110:111], v[104:105], s[26:27], v[130:131] op_sel_hi:[1,0,0]
	s_nop 0
	v_pk_fma_f32 v[110:111], v[104:105], v[110:111], s[28:29] op_sel_hi:[1,1,0]
	s_nop 0
	v_pk_fma_f32 v[110:111], v[104:105], v[110:111], s[30:31] op_sel_hi:[1,1,0]
	s_nop 0
	v_pk_fma_f32 v[110:111], v[104:105], v[110:111], s[34:35] op_sel_hi:[1,1,0]
	s_nop 0
	v_pk_mul_f32 v[104:105], v[104:105], v[110:111]
	s_nop 0
	v_pk_mul_f32 v[104:105], v[106:107], v[104:105]
	s_nop 0
	v_pk_mul_f32 v[106:107], v[100:101], v[104:105]
	v_pk_fma_f32 v[104:105], v[100:101], v[104:105], v[100:101] neg_lo:[1,0,0] neg_hi:[1,0,0]
	v_mul_f32_e32 v101, v102, v102
	v_cndmask_b32_e32 v110, v105, v107, vcc
	v_cmp_gt_f32_e32 vcc, 0, v100
	v_mul_f32_e32 v101, 0xbf38aa3b, v101
	v_fma_f32 v100, |v102|, s77, 1.0
	v_cndmask_b32_e32 v111, v104, v106, vcc
	v_exp_f32_e32 v104, v101
	v_fma_f32 v101, |v103|, s77, 1.0
	v_rcp_f32_e32 v100, v100
	v_rcp_f32_e32 v101, v101
	v_mul_f32_e32 v105, v103, v103
	v_mul_f32_e32 v105, 0xbf38aa3b, v105
	v_exp_f32_e32 v105, v105
	v_pk_fma_f32 v[106:107], v[100:101], s[26:27], v[130:131] op_sel_hi:[1,0,0]
	v_cmp_gt_f32_e32 vcc, 0, v103
	v_pk_fma_f32 v[106:107], v[100:101], v[106:107], s[28:29] op_sel_hi:[1,1,0]
	s_nop 0
	v_pk_fma_f32 v[106:107], v[100:101], v[106:107], s[30:31] op_sel_hi:[1,1,0]
	s_nop 0
	v_pk_fma_f32 v[106:107], v[100:101], v[106:107], s[34:35] op_sel_hi:[1,1,0]
	s_nop 0
	v_pk_mul_f32 v[100:101], v[100:101], v[106:107]
	s_nop 0
	v_pk_mul_f32 v[100:101], v[104:105], v[100:101]
	s_nop 0
	v_pk_mul_f32 v[104:105], v[102:103], v[100:101]
	v_pk_fma_f32 v[100:101], v[102:103], v[100:101], v[102:103] neg_lo:[1,0,0] neg_hi:[1,0,0]
	v_mul_f32_e32 v103, v97, v97
	v_cndmask_b32_e32 v106, v101, v105, vcc
	v_mul_f32_e32 v101, v96, v96
	v_cmp_gt_f32_e32 vcc, 0, v102
	v_mul_f32_e32 v101, 0xbf38aa3b, v101
	v_exp_f32_e32 v102, v101
	v_cndmask_b32_e32 v107, v100, v104, vcc
	v_fma_f32 v100, |v96|, s77, 1.0
	v_fma_f32 v101, |v97|, s77, 1.0
	v_rcp_f32_e32 v100, v100
	v_rcp_f32_e32 v101, v101
	v_mul_f32_e32 v103, 0xbf38aa3b, v103
	v_exp_f32_e32 v103, v103
	v_cmp_gt_f32_e32 vcc, 0, v97
	v_pk_fma_f32 v[104:105], v[100:101], s[26:27], v[130:131] op_sel_hi:[1,0,0]
	s_nop 0
	v_pk_fma_f32 v[104:105], v[100:101], v[104:105], s[28:29] op_sel_hi:[1,1,0]
	s_nop 0
	v_pk_fma_f32 v[104:105], v[100:101], v[104:105], s[30:31] op_sel_hi:[1,1,0]
	s_nop 0
	v_pk_fma_f32 v[104:105], v[100:101], v[104:105], s[34:35] op_sel_hi:[1,1,0]
	s_nop 0
	v_pk_mul_f32 v[100:101], v[100:101], v[104:105]
	s_nop 0
	v_pk_mul_f32 v[100:101], v[102:103], v[100:101]
	s_nop 0
	v_pk_mul_f32 v[102:103], v[96:97], v[100:101]
	v_pk_fma_f32 v[100:101], v[96:97], v[100:101], v[96:97] neg_lo:[1,0,0] neg_hi:[1,0,0]
	v_mul_f32_e32 v97, v98, v98
	v_cndmask_b32_e32 v104, v101, v103, vcc
	v_cmp_gt_f32_e32 vcc, 0, v96
	v_mul_f32_e32 v97, 0xbf38aa3b, v97
	v_fma_f32 v96, |v98|, s77, 1.0
	v_cndmask_b32_e32 v105, v100, v102, vcc
	v_exp_f32_e32 v100, v97
	v_fma_f32 v97, |v99|, s77, 1.0
	v_rcp_f32_e32 v96, v96
	v_rcp_f32_e32 v97, v97
	v_mul_f32_e32 v101, v99, v99
	v_mul_f32_e32 v101, 0xbf38aa3b, v101
	v_exp_f32_e32 v101, v101
	v_pk_fma_f32 v[102:103], v[96:97], s[26:27], v[130:131] op_sel_hi:[1,0,0]
	v_cmp_gt_f32_e32 vcc, 0, v99
	v_pk_fma_f32 v[102:103], v[96:97], v[102:103], s[28:29] op_sel_hi:[1,1,0]
	s_nop 0
	v_pk_fma_f32 v[102:103], v[96:97], v[102:103], s[30:31] op_sel_hi:[1,1,0]
	s_nop 0
	v_pk_fma_f32 v[102:103], v[96:97], v[102:103], s[34:35] op_sel_hi:[1,1,0]
	s_nop 0
	v_pk_mul_f32 v[96:97], v[96:97], v[102:103]
	s_nop 0
	v_pk_mul_f32 v[96:97], v[100:101], v[96:97]
	s_nop 0
	v_pk_mul_f32 v[100:101], v[98:99], v[96:97]
	v_pk_fma_f32 v[96:97], v[98:99], v[96:97], v[98:99] neg_lo:[1,0,0] neg_hi:[1,0,0]
	s_nop 0
	v_cndmask_b32_e32 v99, v97, v101, vcc
	v_cmp_gt_f32_e32 vcc, 0, v98
	v_cvt_pk_bf16_f32 v97, v107, v106
	v_cvt_pk_bf16_f32 v98, v105, v104
	v_cndmask_b32_e32 v100, v96, v100, vcc
	v_cvt_pk_bf16_f32 v96, v111, v110
	v_cvt_pk_bf16_f32 v99, v100, v99
	s_nop 0
	v_permlane16_swap_b32_e32 v96, v98
	v_permlane16_swap_b32_e32 v97, v99
	global_store_dwordx4 v[108:109], v[96:99], off offset:256 nt
; __device__ __forceinline__ u32x2 pack4(f32x4 v) { u32x2 r; r.x = cvt_pk(v[0], v[1]); r.y = cvt_pk(v[2], v[3]); return r; }
; __device__ __forceinline__ float gelu_f(float v) {
;   const float av = fabsf(v), t = __builtin_amdgcn_rcpf(av * 0.2316418882f + 1.0f);
;   float q = t * 0.5307027145f + (-0.7265760135f); q = q * t + 0.7107068705f; q = q * t + (-0.142248368f); q = q * t + 0.127414796f; q = q * t;
;   const float e = __builtin_amdgcn_exp2f((v * v) * (-0.72134752044f));
;   const float m = v * (q * e), r = v - m;
;   return v < 0.f ? m : r;
; }
; template <int SEC> __device__ __forceinline__ void epiB2(const Params& p, int row, int col32, f32x4 v0, f32x4 v1, int fq) {
;     ...
;   if (SEC == 0) { f32x4 o0 = {gelu_f(v0[0]), gelu_f(v0[1]), gelu_f(v0[2]), gelu_f(v0[3])}, o1 = {gelu_f(v1[0]), gelu_f(v1[1]), gelu_f(v1[2]), gelu_f(v1[3])};
;     store_pair16((u16*)(ws + OFF_UV) + (size_t)row * 1024 + col32, pack4(o0), pack4(o1), fq); }
	v_mul_f32_e32 v101, v93, v93
	v_mul_f32_e32 v101, 0xbf38aa3b, v101
	v_mul_f32_e32 v99, v92, v92
	v_mul_f32_e32 v99, 0xbf38aa3b, v99
	v_fma_f32 v98, |v92|, s77, 1.0
	v_exp_f32_e32 v100, v99
	v_fma_f32 v99, |v93|, s77, 1.0
	v_rcp_f32_e32 v98, v98
	v_rcp_f32_e32 v99, v99
	v_exp_f32_e32 v101, v101
	v_cmp_gt_f32_e32 vcc, 0, v93
	v_or_b32_e32 v96, 32, v128
	v_pk_fma_f32 v[102:103], v[98:99], s[26:27], v[130:131] op_sel_hi:[1,0,0]
	v_mov_b32_e32 v97, v129
	v_pk_fma_f32 v[102:103], v[98:99], v[102:103], s[28:29] op_sel_hi:[1,1,0]
	v_lshlrev_b64 v[96:97], 11, v[96:97]
	v_pk_fma_f32 v[102:103], v[98:99], v[102:103], s[30:31] op_sel_hi:[1,1,0]
	s_nop 0
	v_pk_fma_f32 v[102:103], v[98:99], v[102:103], s[34:35] op_sel_hi:[1,1,0]
	s_nop 0
	v_pk_mul_f32 v[98:99], v[98:99], v[102:103]
	s_nop 0
	v_pk_mul_f32 v[98:99], v[100:101], v[98:99]
	s_nop 0
	v_pk_mul_f32 v[100:101], v[92:93], v[98:99]
	v_pk_fma_f32 v[98:99], v[92:93], v[98:99], v[92:93] neg_lo:[1,0,0] neg_hi:[1,0,0]
	v_mul_f32_e32 v93, v94, v94
	v_cndmask_b32_e32 v102, v99, v101, vcc
	v_cmp_gt_f32_e32 vcc, 0, v92
	v_mul_f32_e32 v93, 0xbf38aa3b, v93
	v_fma_f32 v92, |v94|, s77, 1.0
	v_cndmask_b32_e32 v103, v98, v100, vcc
	v_exp_f32_e32 v98, v93
	v_fma_f32 v93, |v95|, s77, 1.0
	v_rcp_f32_e32 v92, v92
	v_rcp_f32_e32 v93, v93
	v_mul_f32_e32 v99, v95, v95
	v_mul_f32_e32 v99, 0xbf38aa3b, v99
	v_exp_f32_e32 v99, v99
	v_pk_fma_f32 v[100:101], v[92:93], s[26:27], v[130:131] op_sel_hi:[1,0,0]
	v_cmp_gt_f32_e32 vcc, 0, v95
	v_pk_fma_f32 v[100:101], v[92:93], v[100:101], s[28:29] op_sel_hi:[1,1,0]
	s_nop 0
	v_pk_fma_f32 v[100:101], v[92:93], v[100:101], s[30:31] op_sel_hi:[1,1,0]
	s_nop 0
	v_pk_fma_f32 v[100:101], v[92:93], v[100:101], s[34:35] op_sel_hi:[1,1,0]
	s_nop 0
	v_pk_mul_f32 v[92:93], v[92:93], v[100:101]
	s_nop 0
	v_pk_mul_f32 v[92:93], v[98:99], v[92:93]
	s_nop 0
	v_pk_mul_f32 v[98:99], v[94:95], v[92:93]
	v_pk_fma_f32 v[92:93], v[94:95], v[92:93], v[94:95] neg_lo:[1,0,0] neg_hi:[1,0,0]
	v_mul_f32_e32 v95, v89, v89
	v_cndmask_b32_e32 v100, v93, v99, vcc
	v_mul_f32_e32 v93, v88, v88
	v_cmp_gt_f32_e32 vcc, 0, v94
	v_mul_f32_e32 v93, 0xbf38aa3b, v93
	v_exp_f32_e32 v94, v93
	v_cndmask_b32_e32 v101, v92, v98, vcc
	v_fma_f32 v92, |v88|, s77, 1.0
	v_fma_f32 v93, |v89|, s77, 1.0
	v_rcp_f32_e32 v92, v92
	v_rcp_f32_e32 v93, v93
	v_mul_f32_e32 v95, 0xbf38aa3b, v95
	v_exp_f32_e32 v95, v95
	v_cmp_gt_f32_e32 vcc, 0, v89
	v_pk_fma_f32 v[98:99], v[92:93], s[26:27], v[130:131] op_sel_hi:[1,0,0]
	s_nop 0
	v_pk_fma_f32 v[98:99], v[92:93], v[98:99], s[28:29] op_sel_hi:[1,1,0]
	s_nop 0
	v_pk_fma_f32 v[98:99], v[92:93], v[98:99], s[30:31] op_sel_hi:[1,1,0]
	s_nop 0
	v_pk_fma_f32 v[98:99], v[92:93], v[98:99], s[34:35] op_sel_hi:[1,1,0]
	s_nop 0
	v_pk_mul_f32 v[92:93], v[92:93], v[98:99]
	s_nop 0
	v_pk_mul_f32 v[92:93], v[94:95], v[92:93]
	s_nop 0
	v_pk_mul_f32 v[94:95], v[88:89], v[92:93]
	v_pk_fma_f32 v[92:93], v[88:89], v[92:93], v[88:89] neg_lo:[1,0,0] neg_hi:[1,0,0]
	v_mul_f32_e32 v89, v90, v90
	v_cndmask_b32_e32 v98, v93, v95, vcc
	v_cmp_gt_f32_e32 vcc, 0, v88
	v_mul_f32_e32 v89, 0xbf38aa3b, v89
	v_fma_f32 v88, |v90|, s77, 1.0
	v_cndmask_b32_e32 v99, v92, v94, vcc
	v_exp_f32_e32 v92, v89
	v_fma_f32 v89, |v91|, s77, 1.0
	v_rcp_f32_e32 v88, v88
	v_rcp_f32_e32 v89, v89
	v_mul_f32_e32 v93, v91, v91
	v_mul_f32_e32 v93, 0xbf38aa3b, v93
	v_exp_f32_e32 v93, v93
	v_pk_fma_f32 v[94:95], v[88:89], s[26:27], v[130:131] op_sel_hi:[1,0,0]
	v_cmp_gt_f32_e32 vcc, 0, v91
	v_pk_fma_f32 v[94:95], v[88:89], v[94:95], s[28:29] op_sel_hi:[1,1,0]
	s_nop 0
	v_pk_fma_f32 v[94:95], v[88:89], v[94:95], s[30:31] op_sel_hi:[1,1,0]
	s_nop 0
	v_pk_fma_f32 v[94:95], v[88:89], v[94:95], s[34:35] op_sel_hi:[1,1,0]
	s_nop 0
	v_pk_mul_f32 v[88:89], v[88:89], v[94:95]
	s_nop 0
	v_pk_mul_f32 v[88:89], v[92:93], v[88:89]
	s_nop 0
	v_pk_mul_f32 v[92:93], v[90:91], v[88:89]
	v_pk_fma_f32 v[88:89], v[90:91], v[88:89], v[90:91] neg_lo:[1,0,0] neg_hi:[1,0,0]
	s_nop 0
	v_cndmask_b32_e32 v91, v89, v93, vcc
	v_cmp_gt_f32_e32 vcc, 0, v90
	v_cvt_pk_bf16_f32 v90, v99, v98
	s_nop 0
	v_cndmask_b32_e32 v94, v88, v92, vcc
	v_lshl_add_u64 v[88:89], s[10:11], 0, v[96:97]
	v_lshl_add_u64 v[92:93], v[88:89], 0, s[4:5]
	v_cvt_pk_bf16_f32 v88, v103, v102
	v_cvt_pk_bf16_f32 v89, v101, v100
	v_cvt_pk_bf16_f32 v91, v94, v91
	v_permlane16_swap_b32_e32 v88, v90
	s_nop 0
	v_permlane16_swap_b32_e32 v89, v91
	v_lshl_add_u64 v[92:93], v[92:93], 0, v[120:121]
	global_store_dwordx4 v[92:93], v[88:91], off nt
	v_cmp_gt_f32_e32 vcc, 0, v85
	s_nop 0
	v_mul_f32_e32 v89, v84, v84
	v_mul_f32_e32 v89, 0xbf38aa3b, v89
	v_fma_f32 v88, |v84|, s77, 1.0
	v_exp_f32_e32 v90, v89
	v_fma_f32 v89, |v85|, s77, 1.0
	v_rcp_f32_e32 v88, v88
	v_rcp_f32_e32 v89, v89
	v_mul_f32_e32 v91, v85, v85
	v_mul_f32_e32 v91, 0xbf38aa3b, v91
	v_exp_f32_e32 v91, v91
	v_pk_fma_f32 v[94:95], v[88:89], s[26:27], v[130:131] op_sel_hi:[1,0,0]
	s_nop 0
	v_pk_fma_f32 v[94:95], v[88:89], v[94:95], s[28:29] op_sel_hi:[1,1,0]
	s_nop 0
	v_pk_fma_f32 v[94:95], v[88:89], v[94:95], s[30:31] op_sel_hi:[1,1,0]
	s_nop 0
	v_pk_fma_f32 v[94:95], v[88:89], v[94:95], s[34:35] op_sel_hi:[1,1,0]
	s_nop 0
	v_pk_mul_f32 v[88:89], v[88:89], v[94:95]
	s_nop 0
	v_pk_mul_f32 v[88:89], v[90:91], v[88:89]
	s_nop 0
	v_pk_mul_f32 v[90:91], v[84:85], v[88:89]
	v_pk_fma_f32 v[88:89], v[84:85], v[88:89], v[84:85] neg_lo:[1,0,0] neg_hi:[1,0,0]
	v_mul_f32_e32 v85, v86, v86
	v_cndmask_b32_e32 v94, v89, v91, vcc
	v_cmp_gt_f32_e32 vcc, 0, v84
	v_mul_f32_e32 v85, 0xbf38aa3b, v85
	v_fma_f32 v84, |v86|, s77, 1.0
	v_cndmask_b32_e32 v95, v88, v90, vcc
	v_exp_f32_e32 v88, v85
	v_fma_f32 v85, |v87|, s77, 1.0
	v_rcp_f32_e32 v84, v84
	v_rcp_f32_e32 v85, v85
; __device__ __forceinline__ u32x2 pack4(f32x4 v) { u32x2 r; r.x = cvt_pk(v[0], v[1]); r.y = cvt_pk(v[2], v[3]); return r; }
; __device__ __forceinline__ float gelu_f(float v) {
;   const float av = fabsf(v), t = __builtin_amdgcn_rcpf(av * 0.2316418882f + 1.0f);
;   float q = t * 0.5307027145f + (-0.7265760135f); q = q * t + 0.7107068705f; q = q * t + (-0.142248368f); q = q * t + 0.127414796f; q = q * t;
;   const float e = __builtin_amdgcn_exp2f((v * v) * (-0.72134752044f));
;   const float m = v * (q * e), r = v - m;
;   return v < 0.f ? m : r;
; }
; template <int SEC> __device__ __forceinline__ void epiB2(const Params& p, int row, int col32, f32x4 v0, f32x4 v1, int fq) {
;     ...
;   if (SEC == 0) { f32x4 o0 = {gelu_f(v0[0]), gelu_f(v0[1]), gelu_f(v0[2]), gelu_f(v0[3])}, o1 = {gelu_f(v1[0]), gelu_f(v1[1]), gelu_f(v1[2]), gelu_f(v1[3])};
;     store_pair16((u16*)(ws + OFF_UV) + (size_t)row * 1024 + col32, pack4(o0), pack4(o1), fq); }
	v_mul_f32_e32 v89, v87, v87
	v_mul_f32_e32 v89, 0xbf38aa3b, v89
	v_exp_f32_e32 v89, v89
	v_pk_fma_f32 v[90:91], v[84:85], s[26:27], v[130:131] op_sel_hi:[1,0,0]
	v_cmp_gt_f32_e32 vcc, 0, v87
	v_pk_fma_f32 v[90:91], v[84:85], v[90:91], s[28:29] op_sel_hi:[1,1,0]
	s_nop 0
	v_pk_fma_f32 v[90:91], v[84:85], v[90:91], s[30:31] op_sel_hi:[1,1,0]
	s_nop 0
	v_pk_fma_f32 v[90:91], v[84:85], v[90:91], s[34:35] op_sel_hi:[1,1,0]
	s_nop 0
	v_pk_mul_f32 v[84:85], v[84:85], v[90:91]
	s_nop 0
	v_pk_mul_f32 v[84:85], v[88:89], v[84:85]
	s_nop 0
	v_pk_mul_f32 v[88:89], v[86:87], v[84:85]
	v_pk_fma_f32 v[84:85], v[86:87], v[84:85], v[86:87] neg_lo:[1,0,0] neg_hi:[1,0,0]
	v_mul_f32_e32 v87, v81, v81
	v_cndmask_b32_e32 v90, v85, v89, vcc
	v_mul_f32_e32 v85, v80, v80
	v_cmp_gt_f32_e32 vcc, 0, v86
	v_mul_f32_e32 v85, 0xbf38aa3b, v85
	v_exp_f32_e32 v86, v85
	v_cndmask_b32_e32 v91, v84, v88, vcc
	v_fma_f32 v84, |v80|, s77, 1.0
	v_fma_f32 v85, |v81|, s77, 1.0
	v_rcp_f32_e32 v84, v84
	v_rcp_f32_e32 v85, v85
	v_mul_f32_e32 v87, 0xbf38aa3b, v87
	v_exp_f32_e32 v87, v87
	v_cmp_gt_f32_e32 vcc, 0, v81
	v_pk_fma_f32 v[88:89], v[84:85], s[26:27], v[130:131] op_sel_hi:[1,0,0]
	s_nop 0
	v_pk_fma_f32 v[88:89], v[84:85], v[88:89], s[28:29] op_sel_hi:[1,1,0]
	s_nop 0
	v_pk_fma_f32 v[88:89], v[84:85], v[88:89], s[30:31] op_sel_hi:[1,1,0]
	s_nop 0
	v_pk_fma_f32 v[88:89], v[84:85], v[88:89], s[34:35] op_sel_hi:[1,1,0]
	s_nop 0
	v_pk_mul_f32 v[84:85], v[84:85], v[88:89]
	s_nop 0
	v_pk_mul_f32 v[84:85], v[86:87], v[84:85]
	s_nop 0
	v_pk_mul_f32 v[86:87], v[80:81], v[84:85]
	v_pk_fma_f32 v[84:85], v[80:81], v[84:85], v[80:81] neg_lo:[1,0,0] neg_hi:[1,0,0]
	v_mul_f32_e32 v81, v82, v82
	v_cndmask_b32_e32 v88, v85, v87, vcc
	v_cmp_gt_f32_e32 vcc, 0, v80
	v_mul_f32_e32 v81, 0xbf38aa3b, v81
	v_fma_f32 v80, |v82|, s77, 1.0
	v_cndmask_b32_e32 v89, v84, v86, vcc
	v_exp_f32_e32 v84, v81
	v_fma_f32 v81, |v83|, s77, 1.0
	v_rcp_f32_e32 v80, v80
	v_rcp_f32_e32 v81, v81
	v_mul_f32_e32 v85, v83, v83
	v_mul_f32_e32 v85, 0xbf38aa3b, v85
	v_exp_f32_e32 v85, v85
	v_pk_fma_f32 v[86:87], v[80:81], s[26:27], v[130:131] op_sel_hi:[1,0,0]
	v_cmp_gt_f32_e32 vcc, 0, v83
	v_pk_fma_f32 v[86:87], v[80:81], v[86:87], s[28:29] op_sel_hi:[1,1,0]
	s_nop 0
	v_pk_fma_f32 v[86:87], v[80:81], v[86:87], s[30:31] op_sel_hi:[1,1,0]
	s_nop 0
	v_pk_fma_f32 v[86:87], v[80:81], v[86:87], s[34:35] op_sel_hi:[1,1,0]
	s_nop 0
	v_pk_mul_f32 v[80:81], v[80:81], v[86:87]
	s_nop 0
	v_pk_mul_f32 v[80:81], v[84:85], v[80:81]
	s_nop 0
	v_pk_mul_f32 v[84:85], v[82:83], v[80:81]
	v_pk_fma_f32 v[80:81], v[82:83], v[80:81], v[82:83] neg_lo:[1,0,0] neg_hi:[1,0,0]
	s_nop 0
	v_cndmask_b32_e32 v83, v81, v85, vcc
	v_cmp_gt_f32_e32 vcc, 0, v82
	v_cvt_pk_bf16_f32 v81, v91, v90
	v_cvt_pk_bf16_f32 v82, v89, v88
	v_cndmask_b32_e32 v84, v80, v84, vcc
	v_cvt_pk_bf16_f32 v80, v95, v94
	v_cvt_pk_bf16_f32 v83, v84, v83
	s_nop 0
	v_permlane16_swap_b32_e32 v80, v82
	v_permlane16_swap_b32_e32 v81, v83
	global_store_dwordx4 v[92:93], v[80:83], off offset:256 nt
	v_mul_f32_e32 v85, v77, v77
	v_mul_f32_e32 v85, 0xbf38aa3b, v85
	v_mul_f32_e32 v83, v76, v76
	v_mul_f32_e32 v83, 0xbf38aa3b, v83
	v_fma_f32 v82, |v76|, s77, 1.0
	v_exp_f32_e32 v84, v83
	v_fma_f32 v83, |v77|, s77, 1.0
	v_rcp_f32_e32 v82, v82
	v_rcp_f32_e32 v83, v83
	v_exp_f32_e32 v85, v85
	v_cmp_gt_f32_e32 vcc, 0, v77
	v_or_b32_e32 v80, 48, v128
	v_pk_fma_f32 v[86:87], v[82:83], s[26:27], v[130:131] op_sel_hi:[1,0,0]
	v_mov_b32_e32 v81, v129
	v_pk_fma_f32 v[86:87], v[82:83], v[86:87], s[28:29] op_sel_hi:[1,1,0]
	v_lshlrev_b64 v[80:81], 11, v[80:81]
	v_pk_fma_f32 v[86:87], v[82:83], v[86:87], s[30:31] op_sel_hi:[1,1,0]
	s_nop 0
	v_pk_fma_f32 v[86:87], v[82:83], v[86:87], s[34:35] op_sel_hi:[1,1,0]
	s_nop 0
	v_pk_mul_f32 v[82:83], v[82:83], v[86:87]
	s_nop 0
	v_pk_mul_f32 v[82:83], v[84:85], v[82:83]
	s_nop 0
	v_pk_mul_f32 v[84:85], v[76:77], v[82:83]
	v_pk_fma_f32 v[82:83], v[76:77], v[82:83], v[76:77] neg_lo:[1,0,0] neg_hi:[1,0,0]
	v_mul_f32_e32 v77, v78, v78
	v_cndmask_b32_e32 v86, v83, v85, vcc
	v_cmp_gt_f32_e32 vcc, 0, v76
	v_mul_f32_e32 v77, 0xbf38aa3b, v77
	v_fma_f32 v76, |v78|, s77, 1.0
	v_cndmask_b32_e32 v87, v82, v84, vcc
	v_exp_f32_e32 v82, v77
	v_fma_f32 v77, |v79|, s77, 1.0
	v_rcp_f32_e32 v76, v76
	v_rcp_f32_e32 v77, v77
	v_mul_f32_e32 v83, v79, v79
	v_mul_f32_e32 v83, 0xbf38aa3b, v83
	v_exp_f32_e32 v83, v83
	v_pk_fma_f32 v[84:85], v[76:77], s[26:27], v[130:131] op_sel_hi:[1,0,0]
	v_cmp_gt_f32_e32 vcc, 0, v79
	v_pk_fma_f32 v[84:85], v[76:77], v[84:85], s[28:29] op_sel_hi:[1,1,0]
	s_nop 0
	v_pk_fma_f32 v[84:85], v[76:77], v[84:85], s[30:31] op_sel_hi:[1,1,0]
	s_nop 0
	v_pk_fma_f32 v[84:85], v[76:77], v[84:85], s[34:35] op_sel_hi:[1,1,0]
	s_nop 0
	v_pk_mul_f32 v[76:77], v[76:77], v[84:85]
	s_nop 0
	v_pk_mul_f32 v[76:77], v[82:83], v[76:77]
	s_nop 0
	v_pk_mul_f32 v[82:83], v[78:79], v[76:77]
	v_pk_fma_f32 v[76:77], v[78:79], v[76:77], v[78:79] neg_lo:[1,0,0] neg_hi:[1,0,0]
	v_mul_f32_e32 v79, v73, v73
	v_cndmask_b32_e32 v84, v77, v83, vcc
	v_mul_f32_e32 v77, v72, v72
	v_cmp_gt_f32_e32 vcc, 0, v78
	v_mul_f32_e32 v77, 0xbf38aa3b, v77
	v_exp_f32_e32 v78, v77
	v_cndmask_b32_e32 v85, v76, v82, vcc
	v_fma_f32 v76, |v72|, s77, 1.0
	v_fma_f32 v77, |v73|, s77, 1.0
	v_rcp_f32_e32 v76, v76
	v_rcp_f32_e32 v77, v77
	v_mul_f32_e32 v79, 0xbf38aa3b, v79
	v_exp_f32_e32 v79, v79
	v_cmp_gt_f32_e32 vcc, 0, v73
	v_pk_fma_f32 v[82:83], v[76:77], s[26:27], v[130:131] op_sel_hi:[1,0,0]
	s_nop 0
	v_pk_fma_f32 v[82:83], v[76:77], v[82:83], s[28:29] op_sel_hi:[1,1,0]
	s_nop 0
	v_pk_fma_f32 v[82:83], v[76:77], v[82:83], s[30:31] op_sel_hi:[1,1,0]
	s_nop 0
	v_pk_fma_f32 v[82:83], v[76:77], v[82:83], s[34:35] op_sel_hi:[1,1,0]
; __device__ __forceinline__ u32x2 pack4(f32x4 v) { u32x2 r; r.x = cvt_pk(v[0], v[1]); r.y = cvt_pk(v[2], v[3]); return r; }
; __device__ __forceinline__ float gelu_f(float v) {
;   const float av = fabsf(v), t = __builtin_amdgcn_rcpf(av * 0.2316418882f + 1.0f);
;   float q = t * 0.5307027145f + (-0.7265760135f); q = q * t + 0.7107068705f; q = q * t + (-0.142248368f); q = q * t + 0.127414796f; q = q * t;
;   const float e = __builtin_amdgcn_exp2f((v * v) * (-0.72134752044f));
;   const float m = v * (q * e), r = v - m;
;   return v < 0.f ? m : r;
; }
; template <int SEC> __device__ __forceinline__ void epiB2(const Params& p, int row, int col32, f32x4 v0, f32x4 v1, int fq) {
;     ...
;   if (SEC == 0) { f32x4 o0 = {gelu_f(v0[0]), gelu_f(v0[1]), gelu_f(v0[2]), gelu_f(v0[3])}, o1 = {gelu_f(v1[0]), gelu_f(v1[1]), gelu_f(v1[2]), gelu_f(v1[3])};
;     store_pair16((u16*)(ws + OFF_UV) + (size_t)row * 1024 + col32, pack4(o0), pack4(o1), fq); }
	s_nop 0
	v_pk_mul_f32 v[76:77], v[76:77], v[82:83]
	s_nop 0
	v_pk_mul_f32 v[76:77], v[78:79], v[76:77]
	s_nop 0
	v_pk_mul_f32 v[78:79], v[72:73], v[76:77]
	v_pk_fma_f32 v[76:77], v[72:73], v[76:77], v[72:73] neg_lo:[1,0,0] neg_hi:[1,0,0]
	v_mul_f32_e32 v73, v74, v74
	v_cndmask_b32_e32 v82, v77, v79, vcc
	v_cmp_gt_f32_e32 vcc, 0, v72
	v_mul_f32_e32 v73, 0xbf38aa3b, v73
	v_fma_f32 v72, |v74|, s77, 1.0
	v_cndmask_b32_e32 v83, v76, v78, vcc
	v_exp_f32_e32 v76, v73
	v_fma_f32 v73, |v75|, s77, 1.0
	v_rcp_f32_e32 v72, v72
	v_rcp_f32_e32 v73, v73
	v_mul_f32_e32 v77, v75, v75
	v_mul_f32_e32 v77, 0xbf38aa3b, v77
	v_exp_f32_e32 v77, v77
	v_pk_fma_f32 v[78:79], v[72:73], s[26:27], v[130:131] op_sel_hi:[1,0,0]
	v_cmp_gt_f32_e32 vcc, 0, v75
	v_pk_fma_f32 v[78:79], v[72:73], v[78:79], s[28:29] op_sel_hi:[1,1,0]
	s_nop 0
	v_pk_fma_f32 v[78:79], v[72:73], v[78:79], s[30:31] op_sel_hi:[1,1,0]
	s_nop 0
	v_pk_fma_f32 v[78:79], v[72:73], v[78:79], s[34:35] op_sel_hi:[1,1,0]
	s_nop 0
	v_pk_mul_f32 v[72:73], v[72:73], v[78:79]
	s_nop 0
	v_pk_mul_f32 v[72:73], v[76:77], v[72:73]
	s_nop 0
	v_pk_mul_f32 v[76:77], v[74:75], v[72:73]
	v_pk_fma_f32 v[72:73], v[74:75], v[72:73], v[74:75] neg_lo:[1,0,0] neg_hi:[1,0,0]
	s_nop 0
	v_cndmask_b32_e32 v75, v73, v77, vcc
	v_cmp_gt_f32_e32 vcc, 0, v74
	v_cvt_pk_bf16_f32 v74, v83, v82
	s_nop 0
	v_cndmask_b32_e32 v78, v72, v76, vcc
	v_lshl_add_u64 v[72:73], s[10:11], 0, v[80:81]
	v_lshl_add_u64 v[76:77], v[72:73], 0, s[4:5]
	v_cvt_pk_bf16_f32 v72, v87, v86
	v_cvt_pk_bf16_f32 v73, v85, v84
	v_cvt_pk_bf16_f32 v75, v78, v75
	v_permlane16_swap_b32_e32 v72, v74
	s_nop 0
	v_permlane16_swap_b32_e32 v73, v75
	v_lshl_add_u64 v[76:77], v[76:77], 0, v[120:121]
	global_store_dwordx4 v[76:77], v[72:75], off nt
	v_cmp_gt_f32_e32 vcc, 0, v69
	s_nop 0
	v_mul_f32_e32 v73, v68, v68
	v_mul_f32_e32 v73, 0xbf38aa3b, v73
	v_fma_f32 v72, |v68|, s77, 1.0
	v_exp_f32_e32 v74, v73
	v_fma_f32 v73, |v69|, s77, 1.0
	v_rcp_f32_e32 v72, v72
	v_rcp_f32_e32 v73, v73
	v_mul_f32_e32 v75, v69, v69
	v_mul_f32_e32 v75, 0xbf38aa3b, v75
	v_exp_f32_e32 v75, v75
	v_pk_fma_f32 v[78:79], v[72:73], s[26:27], v[130:131] op_sel_hi:[1,0,0]
	s_nop 0
	v_pk_fma_f32 v[78:79], v[72:73], v[78:79], s[28:29] op_sel_hi:[1,1,0]
	s_nop 0
	v_pk_fma_f32 v[78:79], v[72:73], v[78:79], s[30:31] op_sel_hi:[1,1,0]
	s_nop 0
	v_pk_fma_f32 v[78:79], v[72:73], v[78:79], s[34:35] op_sel_hi:[1,1,0]
	s_nop 0
	v_pk_mul_f32 v[72:73], v[72:73], v[78:79]
	s_nop 0
	v_pk_mul_f32 v[72:73], v[74:75], v[72:73]
	s_nop 0
	v_pk_mul_f32 v[74:75], v[68:69], v[72:73]
	v_pk_fma_f32 v[72:73], v[68:69], v[72:73], v[68:69] neg_lo:[1,0,0] neg_hi:[1,0,0]
	v_mul_f32_e32 v69, v70, v70
	v_cndmask_b32_e32 v78, v73, v75, vcc
	v_cmp_gt_f32_e32 vcc, 0, v68
	v_mul_f32_e32 v69, 0xbf38aa3b, v69
	v_fma_f32 v68, |v70|, s77, 1.0
	v_cndmask_b32_e32 v79, v72, v74, vcc
	v_exp_f32_e32 v72, v69
	v_fma_f32 v69, |v71|, s77, 1.0
	v_rcp_f32_e32 v68, v68
	v_rcp_f32_e32 v69, v69
	v_mul_f32_e32 v73, v71, v71
	v_mul_f32_e32 v73, 0xbf38aa3b, v73
	v_exp_f32_e32 v73, v73
	v_pk_fma_f32 v[74:75], v[68:69], s[26:27], v[130:131] op_sel_hi:[1,0,0]
	v_cmp_gt_f32_e32 vcc, 0, v71
	v_pk_fma_f32 v[74:75], v[68:69], v[74:75], s[28:29] op_sel_hi:[1,1,0]
	s_nop 0
	v_pk_fma_f32 v[74:75], v[68:69], v[74:75], s[30:31] op_sel_hi:[1,1,0]
	s_nop 0
	v_pk_fma_f32 v[74:75], v[68:69], v[74:75], s[34:35] op_sel_hi:[1,1,0]
	s_nop 0
	v_pk_mul_f32 v[68:69], v[68:69], v[74:75]
	s_nop 0
	v_pk_mul_f32 v[68:69], v[72:73], v[68:69]
	s_nop 0
	v_pk_mul_f32 v[72:73], v[70:71], v[68:69]
	v_pk_fma_f32 v[68:69], v[70:71], v[68:69], v[70:71] neg_lo:[1,0,0] neg_hi:[1,0,0]
	v_mul_f32_e32 v71, v65, v65
	v_cndmask_b32_e32 v74, v69, v73, vcc
	v_mul_f32_e32 v69, v64, v64
	v_cmp_gt_f32_e32 vcc, 0, v70
	v_mul_f32_e32 v69, 0xbf38aa3b, v69
	v_exp_f32_e32 v70, v69
	v_cndmask_b32_e32 v75, v68, v72, vcc
	v_fma_f32 v68, |v64|, s77, 1.0
	v_fma_f32 v69, |v65|, s77, 1.0
	v_rcp_f32_e32 v68, v68
	v_rcp_f32_e32 v69, v69
	v_mul_f32_e32 v71, 0xbf38aa3b, v71
	v_exp_f32_e32 v71, v71
	v_cmp_gt_f32_e32 vcc, 0, v65
	v_pk_fma_f32 v[72:73], v[68:69], s[26:27], v[130:131] op_sel_hi:[1,0,0]
	s_nop 0
	v_pk_fma_f32 v[72:73], v[68:69], v[72:73], s[28:29] op_sel_hi:[1,1,0]
	s_nop 0
	v_pk_fma_f32 v[72:73], v[68:69], v[72:73], s[30:31] op_sel_hi:[1,1,0]
	s_nop 0
	v_pk_fma_f32 v[72:73], v[68:69], v[72:73], s[34:35] op_sel_hi:[1,1,0]
	s_nop 0
	v_pk_mul_f32 v[68:69], v[68:69], v[72:73]
	s_nop 0
	v_pk_mul_f32 v[68:69], v[70:71], v[68:69]
	s_nop 0
	v_pk_mul_f32 v[70:71], v[64:65], v[68:69]
	v_pk_fma_f32 v[68:69], v[64:65], v[68:69], v[64:65] neg_lo:[1,0,0] neg_hi:[1,0,0]
	v_mul_f32_e32 v65, v66, v66
	v_cndmask_b32_e32 v72, v69, v71, vcc
	v_cmp_gt_f32_e32 vcc, 0, v64
	v_mul_f32_e32 v65, 0xbf38aa3b, v65
	v_fma_f32 v64, |v66|, s77, 1.0
	v_cndmask_b32_e32 v73, v68, v70, vcc
	v_exp_f32_e32 v68, v65
	v_fma_f32 v65, |v67|, s77, 1.0
	v_rcp_f32_e32 v64, v64
	v_rcp_f32_e32 v65, v65
	v_mul_f32_e32 v69, v67, v67
	v_mul_f32_e32 v69, 0xbf38aa3b, v69
	v_exp_f32_e32 v69, v69
	v_pk_fma_f32 v[70:71], v[64:65], s[26:27], v[130:131] op_sel_hi:[1,0,0]
	v_cmp_gt_f32_e32 vcc, 0, v67
	v_pk_fma_f32 v[70:71], v[64:65], v[70:71], s[28:29] op_sel_hi:[1,1,0]
	s_nop 0
	v_pk_fma_f32 v[70:71], v[64:65], v[70:71], s[30:31] op_sel_hi:[1,1,0]
	s_nop 0
	v_pk_fma_f32 v[70:71], v[64:65], v[70:71], s[34:35] op_sel_hi:[1,1,0]
	s_nop 0
	v_pk_mul_f32 v[64:65], v[64:65], v[70:71]
	s_nop 0
	v_pk_mul_f32 v[64:65], v[68:69], v[64:65]
	s_nop 0
	v_pk_mul_f32 v[68:69], v[66:67], v[64:65]
	v_pk_fma_f32 v[64:65], v[66:67], v[64:65], v[66:67] neg_lo:[1,0,0] neg_hi:[1,0,0]
	s_nop 0
	v_cndmask_b32_e32 v67, v65, v69, vcc
	v_cmp_gt_f32_e32 vcc, 0, v66
	v_cvt_pk_bf16_f32 v65, v75, v74
; __device__ __forceinline__ u32x2 pack4(f32x4 v) { u32x2 r; r.x = cvt_pk(v[0], v[1]); r.y = cvt_pk(v[2], v[3]); return r; }
; __device__ __forceinline__ float gelu_f(float v) {
;   const float av = fabsf(v), t = __builtin_amdgcn_rcpf(av * 0.2316418882f + 1.0f);
;   float q = t * 0.5307027145f + (-0.7265760135f); q = q * t + 0.7107068705f; q = q * t + (-0.142248368f); q = q * t + 0.127414796f; q = q * t;
;   const float e = __builtin_amdgcn_exp2f((v * v) * (-0.72134752044f));
;   const float m = v * (q * e), r = v - m;
;   return v < 0.f ? m : r;
; }
; template <int SEC> __device__ __forceinline__ void epiB2(const Params& p, int row, int col32, f32x4 v0, f32x4 v1, int fq) {
;     ...
;   if (SEC == 0) { f32x4 o0 = {gelu_f(v0[0]), gelu_f(v0[1]), gelu_f(v0[2]), gelu_f(v0[3])}, o1 = {gelu_f(v1[0]), gelu_f(v1[1]), gelu_f(v1[2]), gelu_f(v1[3])};
;     store_pair16((u16*)(ws + OFF_UV) + (size_t)row * 1024 + col32, pack4(o0), pack4(o1), fq); }
	v_cvt_pk_bf16_f32 v66, v73, v72
	v_cndmask_b32_e32 v68, v64, v68, vcc
	v_cvt_pk_bf16_f32 v64, v79, v78
	v_cvt_pk_bf16_f32 v67, v68, v67
	s_nop 0
	v_permlane16_swap_b32_e32 v64, v66
	v_permlane16_swap_b32_e32 v65, v67
	global_store_dwordx4 v[76:77], v[64:67], off offset:256 nt
	v_mul_f32_e32 v69, v61, v61
	v_mul_f32_e32 v69, 0xbf38aa3b, v69
	v_mul_f32_e32 v67, v60, v60
	v_mul_f32_e32 v67, 0xbf38aa3b, v67
	v_fma_f32 v66, |v60|, s77, 1.0
	v_exp_f32_e32 v68, v67
	v_fma_f32 v67, |v61|, s77, 1.0
	v_rcp_f32_e32 v66, v66
	v_rcp_f32_e32 v67, v67
	v_exp_f32_e32 v69, v69
	v_cmp_gt_f32_e32 vcc, 0, v61
	v_add_u32_e32 v64, 0x80, v128
	v_pk_fma_f32 v[70:71], v[66:67], s[26:27], v[130:131] op_sel_hi:[1,0,0]
	v_mov_b32_e32 v65, v129
	v_pk_fma_f32 v[70:71], v[66:67], v[70:71], s[28:29] op_sel_hi:[1,1,0]
	v_lshlrev_b64 v[64:65], 11, v[64:65]
	v_pk_fma_f32 v[70:71], v[66:67], v[70:71], s[30:31] op_sel_hi:[1,1,0]
	s_nop 0
	v_pk_fma_f32 v[70:71], v[66:67], v[70:71], s[34:35] op_sel_hi:[1,1,0]
	s_nop 0
	v_pk_mul_f32 v[66:67], v[66:67], v[70:71]
	s_nop 0
	v_pk_mul_f32 v[66:67], v[68:69], v[66:67]
	s_nop 0
	v_pk_mul_f32 v[68:69], v[60:61], v[66:67]
	v_pk_fma_f32 v[66:67], v[60:61], v[66:67], v[60:61] neg_lo:[1,0,0] neg_hi:[1,0,0]
	v_mul_f32_e32 v61, v62, v62
	v_cndmask_b32_e32 v70, v67, v69, vcc
	v_cmp_gt_f32_e32 vcc, 0, v60
	v_mul_f32_e32 v61, 0xbf38aa3b, v61
	v_fma_f32 v60, |v62|, s77, 1.0
	v_cndmask_b32_e32 v71, v66, v68, vcc
	v_exp_f32_e32 v66, v61
	v_fma_f32 v61, |v63|, s77, 1.0
	v_rcp_f32_e32 v60, v60
	v_rcp_f32_e32 v61, v61
	v_mul_f32_e32 v67, v63, v63
	v_mul_f32_e32 v67, 0xbf38aa3b, v67
	v_exp_f32_e32 v67, v67
	v_pk_fma_f32 v[68:69], v[60:61], s[26:27], v[130:131] op_sel_hi:[1,0,0]
	v_cmp_gt_f32_e32 vcc, 0, v63
	v_pk_fma_f32 v[68:69], v[60:61], v[68:69], s[28:29] op_sel_hi:[1,1,0]
	s_nop 0
	v_pk_fma_f32 v[68:69], v[60:61], v[68:69], s[30:31] op_sel_hi:[1,1,0]
	s_nop 0
	v_pk_fma_f32 v[68:69], v[60:61], v[68:69], s[34:35] op_sel_hi:[1,1,0]
	s_nop 0
	v_pk_mul_f32 v[60:61], v[60:61], v[68:69]
	s_nop 0
	v_pk_mul_f32 v[60:61], v[66:67], v[60:61]
	s_nop 0
	v_pk_mul_f32 v[66:67], v[62:63], v[60:61]
	v_pk_fma_f32 v[60:61], v[62:63], v[60:61], v[62:63] neg_lo:[1,0,0] neg_hi:[1,0,0]
	v_mul_f32_e32 v63, v57, v57
	v_cndmask_b32_e32 v68, v61, v67, vcc
	v_mul_f32_e32 v61, v56, v56
	v_cmp_gt_f32_e32 vcc, 0, v62
	v_mul_f32_e32 v61, 0xbf38aa3b, v61
	v_exp_f32_e32 v62, v61
	v_cndmask_b32_e32 v69, v60, v66, vcc
	v_fma_f32 v60, |v56|, s77, 1.0
	v_fma_f32 v61, |v57|, s77, 1.0
	v_rcp_f32_e32 v60, v60
	v_rcp_f32_e32 v61, v61
	v_mul_f32_e32 v63, 0xbf38aa3b, v63
	v_exp_f32_e32 v63, v63
	v_cmp_gt_f32_e32 vcc, 0, v57
	v_pk_fma_f32 v[66:67], v[60:61], s[26:27], v[130:131] op_sel_hi:[1,0,0]
	s_nop 0
	v_pk_fma_f32 v[66:67], v[60:61], v[66:67], s[28:29] op_sel_hi:[1,1,0]
	s_nop 0
	v_pk_fma_f32 v[66:67], v[60:61], v[66:67], s[30:31] op_sel_hi:[1,1,0]
	s_nop 0
	v_pk_fma_f32 v[66:67], v[60:61], v[66:67], s[34:35] op_sel_hi:[1,1,0]
	s_nop 0
	v_pk_mul_f32 v[60:61], v[60:61], v[66:67]
	s_nop 0
	v_pk_mul_f32 v[60:61], v[62:63], v[60:61]
	s_nop 0
	v_pk_mul_f32 v[62:63], v[56:57], v[60:61]
	v_pk_fma_f32 v[60:61], v[56:57], v[60:61], v[56:57] neg_lo:[1,0,0] neg_hi:[1,0,0]
	v_mul_f32_e32 v57, v58, v58
	v_cndmask_b32_e32 v66, v61, v63, vcc
	v_cmp_gt_f32_e32 vcc, 0, v56
	v_mul_f32_e32 v57, 0xbf38aa3b, v57
	v_fma_f32 v56, |v58|, s77, 1.0
	v_cndmask_b32_e32 v67, v60, v62, vcc
	v_exp_f32_e32 v60, v57
	v_fma_f32 v57, |v59|, s77, 1.0
	v_rcp_f32_e32 v56, v56
	v_rcp_f32_e32 v57, v57
	v_mul_f32_e32 v61, v59, v59
	v_mul_f32_e32 v61, 0xbf38aa3b, v61
	v_exp_f32_e32 v61, v61
	v_pk_fma_f32 v[62:63], v[56:57], s[26:27], v[130:131] op_sel_hi:[1,0,0]
	v_cmp_gt_f32_e32 vcc, 0, v59
	v_pk_fma_f32 v[62:63], v[56:57], v[62:63], s[28:29] op_sel_hi:[1,1,0]
	s_nop 0
	v_pk_fma_f32 v[62:63], v[56:57], v[62:63], s[30:31] op_sel_hi:[1,1,0]
	s_nop 0
	v_pk_fma_f32 v[62:63], v[56:57], v[62:63], s[34:35] op_sel_hi:[1,1,0]
	s_nop 0
	v_pk_mul_f32 v[56:57], v[56:57], v[62:63]
	s_nop 0
	v_pk_mul_f32 v[56:57], v[60:61], v[56:57]
	s_nop 0
	v_pk_mul_f32 v[60:61], v[58:59], v[56:57]
	v_pk_fma_f32 v[56:57], v[58:59], v[56:57], v[58:59] neg_lo:[1,0,0] neg_hi:[1,0,0]
	s_nop 0
	v_cndmask_b32_e32 v59, v57, v61, vcc
	v_cmp_gt_f32_e32 vcc, 0, v58
	v_cvt_pk_bf16_f32 v58, v67, v66
	s_nop 0
	v_cndmask_b32_e32 v62, v56, v60, vcc
	v_lshl_add_u64 v[56:57], s[10:11], 0, v[64:65]
	v_lshl_add_u64 v[60:61], v[56:57], 0, s[4:5]
	v_cvt_pk_bf16_f32 v56, v71, v70
	v_cvt_pk_bf16_f32 v57, v69, v68
	v_cvt_pk_bf16_f32 v59, v62, v59
	v_permlane16_swap_b32_e32 v56, v58
	s_nop 0
	v_permlane16_swap_b32_e32 v57, v59
	v_lshl_add_u64 v[60:61], v[60:61], 0, v[120:121]
	global_store_dwordx4 v[60:61], v[56:59], off nt
	v_cmp_gt_f32_e32 vcc, 0, v53
	s_nop 0
	v_mul_f32_e32 v57, v52, v52
	v_mul_f32_e32 v57, 0xbf38aa3b, v57
	v_fma_f32 v56, |v52|, s77, 1.0
	v_exp_f32_e32 v58, v57
	v_fma_f32 v57, |v53|, s77, 1.0
	v_rcp_f32_e32 v56, v56
	v_rcp_f32_e32 v57, v57
	v_mul_f32_e32 v59, v53, v53
	v_mul_f32_e32 v59, 0xbf38aa3b, v59
	v_exp_f32_e32 v59, v59
	v_pk_fma_f32 v[62:63], v[56:57], s[26:27], v[130:131] op_sel_hi:[1,0,0]
	s_nop 0
	v_pk_fma_f32 v[62:63], v[56:57], v[62:63], s[28:29] op_sel_hi:[1,1,0]
	s_nop 0
	v_pk_fma_f32 v[62:63], v[56:57], v[62:63], s[30:31] op_sel_hi:[1,1,0]
	s_nop 0
	v_pk_fma_f32 v[62:63], v[56:57], v[62:63], s[34:35] op_sel_hi:[1,1,0]
	s_nop 0
	v_pk_mul_f32 v[56:57], v[56:57], v[62:63]
	s_nop 0
	v_pk_mul_f32 v[56:57], v[58:59], v[56:57]
	s_nop 0
	v_pk_mul_f32 v[58:59], v[52:53], v[56:57]
	v_pk_fma_f32 v[56:57], v[52:53], v[56:57], v[52:53] neg_lo:[1,0,0] neg_hi:[1,0,0]
	v_mul_f32_e32 v53, v54, v54
	v_cndmask_b32_e32 v62, v57, v59, vcc
	v_cmp_gt_f32_e32 vcc, 0, v52
; __device__ __forceinline__ u32x2 pack4(f32x4 v) { u32x2 r; r.x = cvt_pk(v[0], v[1]); r.y = cvt_pk(v[2], v[3]); return r; }
; __device__ __forceinline__ float gelu_f(float v) {
;   const float av = fabsf(v), t = __builtin_amdgcn_rcpf(av * 0.2316418882f + 1.0f);
;   float q = t * 0.5307027145f + (-0.7265760135f); q = q * t + 0.7107068705f; q = q * t + (-0.142248368f); q = q * t + 0.127414796f; q = q * t;
;   const float e = __builtin_amdgcn_exp2f((v * v) * (-0.72134752044f));
;   const float m = v * (q * e), r = v - m;
;   return v < 0.f ? m : r;
; }
; template <int SEC> __device__ __forceinline__ void epiB2(const Params& p, int row, int col32, f32x4 v0, f32x4 v1, int fq) {
;     ...
;   if (SEC == 0) { f32x4 o0 = {gelu_f(v0[0]), gelu_f(v0[1]), gelu_f(v0[2]), gelu_f(v0[3])}, o1 = {gelu_f(v1[0]), gelu_f(v1[1]), gelu_f(v1[2]), gelu_f(v1[3])};
;     store_pair16((u16*)(ws + OFF_UV) + (size_t)row * 1024 + col32, pack4(o0), pack4(o1), fq); }
	v_mul_f32_e32 v53, 0xbf38aa3b, v53
	v_fma_f32 v52, |v54|, s77, 1.0
	v_cndmask_b32_e32 v63, v56, v58, vcc
	v_exp_f32_e32 v56, v53
	v_fma_f32 v53, |v55|, s77, 1.0
	v_rcp_f32_e32 v52, v52
	v_rcp_f32_e32 v53, v53
	v_mul_f32_e32 v57, v55, v55
	v_mul_f32_e32 v57, 0xbf38aa3b, v57
	v_exp_f32_e32 v57, v57
	v_pk_fma_f32 v[58:59], v[52:53], s[26:27], v[130:131] op_sel_hi:[1,0,0]
	v_cmp_gt_f32_e32 vcc, 0, v55
	v_pk_fma_f32 v[58:59], v[52:53], v[58:59], s[28:29] op_sel_hi:[1,1,0]
	s_nop 0
	v_pk_fma_f32 v[58:59], v[52:53], v[58:59], s[30:31] op_sel_hi:[1,1,0]
	s_nop 0
	v_pk_fma_f32 v[58:59], v[52:53], v[58:59], s[34:35] op_sel_hi:[1,1,0]
	s_nop 0
	v_pk_mul_f32 v[52:53], v[52:53], v[58:59]
	s_nop 0
	v_pk_mul_f32 v[52:53], v[56:57], v[52:53]
	s_nop 0
	v_pk_mul_f32 v[56:57], v[54:55], v[52:53]
	v_pk_fma_f32 v[52:53], v[54:55], v[52:53], v[54:55] neg_lo:[1,0,0] neg_hi:[1,0,0]
	v_mul_f32_e32 v55, v49, v49
	v_cndmask_b32_e32 v58, v53, v57, vcc
	v_mul_f32_e32 v53, v48, v48
	v_cmp_gt_f32_e32 vcc, 0, v54
	v_mul_f32_e32 v53, 0xbf38aa3b, v53
	v_exp_f32_e32 v54, v53
	v_cndmask_b32_e32 v59, v52, v56, vcc
	v_fma_f32 v52, |v48|, s77, 1.0
	v_fma_f32 v53, |v49|, s77, 1.0
	v_rcp_f32_e32 v52, v52
	v_rcp_f32_e32 v53, v53
	v_mul_f32_e32 v55, 0xbf38aa3b, v55
	v_exp_f32_e32 v55, v55
	v_cmp_gt_f32_e32 vcc, 0, v49
	v_pk_fma_f32 v[56:57], v[52:53], s[26:27], v[130:131] op_sel_hi:[1,0,0]
	s_nop 0
	v_pk_fma_f32 v[56:57], v[52:53], v[56:57], s[28:29] op_sel_hi:[1,1,0]
	s_nop 0
	v_pk_fma_f32 v[56:57], v[52:53], v[56:57], s[30:31] op_sel_hi:[1,1,0]
	s_nop 0
	v_pk_fma_f32 v[56:57], v[52:53], v[56:57], s[34:35] op_sel_hi:[1,1,0]
	s_nop 0
	v_pk_mul_f32 v[52:53], v[52:53], v[56:57]
	s_nop 0
	v_pk_mul_f32 v[52:53], v[54:55], v[52:53]
	s_nop 0
	v_pk_mul_f32 v[54:55], v[48:49], v[52:53]
	v_pk_fma_f32 v[52:53], v[48:49], v[52:53], v[48:49] neg_lo:[1,0,0] neg_hi:[1,0,0]
	v_mul_f32_e32 v49, v50, v50
	v_cndmask_b32_e32 v56, v53, v55, vcc
	v_cmp_gt_f32_e32 vcc, 0, v48
	v_mul_f32_e32 v49, 0xbf38aa3b, v49
	v_fma_f32 v48, |v50|, s77, 1.0
	v_cndmask_b32_e32 v57, v52, v54, vcc
	v_exp_f32_e32 v52, v49
	v_fma_f32 v49, |v51|, s77, 1.0
	v_rcp_f32_e32 v48, v48
	v_rcp_f32_e32 v49, v49
	v_mul_f32_e32 v53, v51, v51
	v_mul_f32_e32 v53, 0xbf38aa3b, v53
	v_exp_f32_e32 v53, v53
	v_pk_fma_f32 v[54:55], v[48:49], s[26:27], v[130:131] op_sel_hi:[1,0,0]
	v_cmp_gt_f32_e32 vcc, 0, v51
	v_pk_fma_f32 v[54:55], v[48:49], v[54:55], s[28:29] op_sel_hi:[1,1,0]
	s_nop 0
	v_pk_fma_f32 v[54:55], v[48:49], v[54:55], s[30:31] op_sel_hi:[1,1,0]
	s_nop 0
	v_pk_fma_f32 v[54:55], v[48:49], v[54:55], s[34:35] op_sel_hi:[1,1,0]
	s_nop 0
	v_pk_mul_f32 v[48:49], v[48:49], v[54:55]
	s_nop 0
	v_pk_mul_f32 v[48:49], v[52:53], v[48:49]
	s_nop 0
	v_pk_mul_f32 v[52:53], v[50:51], v[48:49]
	v_pk_fma_f32 v[48:49], v[50:51], v[48:49], v[50:51] neg_lo:[1,0,0] neg_hi:[1,0,0]
	s_nop 0
	v_cndmask_b32_e32 v51, v49, v53, vcc
	v_cmp_gt_f32_e32 vcc, 0, v50
	v_cvt_pk_bf16_f32 v49, v59, v58
	v_cvt_pk_bf16_f32 v50, v57, v56
	v_cndmask_b32_e32 v52, v48, v52, vcc
	v_cvt_pk_bf16_f32 v48, v63, v62
	v_cvt_pk_bf16_f32 v51, v52, v51
	s_nop 0
	v_permlane16_swap_b32_e32 v48, v50
	v_permlane16_swap_b32_e32 v49, v51
	global_store_dwordx4 v[60:61], v[48:51], off offset:256 nt
	v_mul_f32_e32 v53, v45, v45
	v_mul_f32_e32 v53, 0xbf38aa3b, v53
	v_mul_f32_e32 v51, v44, v44
	v_mul_f32_e32 v51, 0xbf38aa3b, v51
	v_fma_f32 v50, |v44|, s77, 1.0
	v_exp_f32_e32 v52, v51
	v_fma_f32 v51, |v45|, s77, 1.0
	v_rcp_f32_e32 v50, v50
	v_rcp_f32_e32 v51, v51
	v_exp_f32_e32 v53, v53
	v_cmp_gt_f32_e32 vcc, 0, v45
	v_add_u32_e32 v48, 0x90, v128
	v_pk_fma_f32 v[54:55], v[50:51], s[26:27], v[130:131] op_sel_hi:[1,0,0]
	v_mov_b32_e32 v49, v129
	v_pk_fma_f32 v[54:55], v[50:51], v[54:55], s[28:29] op_sel_hi:[1,1,0]
	v_lshlrev_b64 v[48:49], 11, v[48:49]
	v_pk_fma_f32 v[54:55], v[50:51], v[54:55], s[30:31] op_sel_hi:[1,1,0]
	s_nop 0
	v_pk_fma_f32 v[54:55], v[50:51], v[54:55], s[34:35] op_sel_hi:[1,1,0]
	s_nop 0
	v_pk_mul_f32 v[50:51], v[50:51], v[54:55]
	s_nop 0
	v_pk_mul_f32 v[50:51], v[52:53], v[50:51]
	s_nop 0
	v_pk_mul_f32 v[52:53], v[44:45], v[50:51]
	v_pk_fma_f32 v[50:51], v[44:45], v[50:51], v[44:45] neg_lo:[1,0,0] neg_hi:[1,0,0]
	v_mul_f32_e32 v45, v46, v46
	v_cndmask_b32_e32 v54, v51, v53, vcc
	v_cmp_gt_f32_e32 vcc, 0, v44
	v_mul_f32_e32 v45, 0xbf38aa3b, v45
	v_fma_f32 v44, |v46|, s77, 1.0
	v_cndmask_b32_e32 v55, v50, v52, vcc
	v_exp_f32_e32 v50, v45
	v_fma_f32 v45, |v47|, s77, 1.0
	v_rcp_f32_e32 v44, v44
	v_rcp_f32_e32 v45, v45
	v_mul_f32_e32 v51, v47, v47
	v_mul_f32_e32 v51, 0xbf38aa3b, v51
	v_exp_f32_e32 v51, v51
	v_pk_fma_f32 v[52:53], v[44:45], s[26:27], v[130:131] op_sel_hi:[1,0,0]
	v_cmp_gt_f32_e32 vcc, 0, v47
	v_pk_fma_f32 v[52:53], v[44:45], v[52:53], s[28:29] op_sel_hi:[1,1,0]
	s_nop 0
	v_pk_fma_f32 v[52:53], v[44:45], v[52:53], s[30:31] op_sel_hi:[1,1,0]
	s_nop 0
	v_pk_fma_f32 v[52:53], v[44:45], v[52:53], s[34:35] op_sel_hi:[1,1,0]
	s_nop 0
	v_pk_mul_f32 v[44:45], v[44:45], v[52:53]
	s_nop 0
	v_pk_mul_f32 v[44:45], v[50:51], v[44:45]
	s_nop 0
	v_pk_mul_f32 v[50:51], v[46:47], v[44:45]
	v_pk_fma_f32 v[44:45], v[46:47], v[44:45], v[46:47] neg_lo:[1,0,0] neg_hi:[1,0,0]
	v_mul_f32_e32 v47, v41, v41
	v_cndmask_b32_e32 v52, v45, v51, vcc
	v_mul_f32_e32 v45, v40, v40
	v_cmp_gt_f32_e32 vcc, 0, v46
	v_mul_f32_e32 v45, 0xbf38aa3b, v45
	v_exp_f32_e32 v46, v45
	v_cndmask_b32_e32 v53, v44, v50, vcc
	v_fma_f32 v44, |v40|, s77, 1.0
	v_fma_f32 v45, |v41|, s77, 1.0
	v_rcp_f32_e32 v44, v44
	v_rcp_f32_e32 v45, v45
	v_mul_f32_e32 v47, 0xbf38aa3b, v47
	v_exp_f32_e32 v47, v47
	v_cmp_gt_f32_e32 vcc, 0, v41
	v_pk_fma_f32 v[50:51], v[44:45], s[26:27], v[130:131] op_sel_hi:[1,0,0]
	s_nop 0
; __device__ __forceinline__ u32x2 pack4(f32x4 v) { u32x2 r; r.x = cvt_pk(v[0], v[1]); r.y = cvt_pk(v[2], v[3]); return r; }
; __device__ __forceinline__ float gelu_f(float v) {
;   const float av = fabsf(v), t = __builtin_amdgcn_rcpf(av * 0.2316418882f + 1.0f);
;   float q = t * 0.5307027145f + (-0.7265760135f); q = q * t + 0.7107068705f; q = q * t + (-0.142248368f); q = q * t + 0.127414796f; q = q * t;
;   const float e = __builtin_amdgcn_exp2f((v * v) * (-0.72134752044f));
;   const float m = v * (q * e), r = v - m;
;   return v < 0.f ? m : r;
; }
; template <int SEC> __device__ __forceinline__ void epiB2(const Params& p, int row, int col32, f32x4 v0, f32x4 v1, int fq) {
;     ...
;   if (SEC == 0) { f32x4 o0 = {gelu_f(v0[0]), gelu_f(v0[1]), gelu_f(v0[2]), gelu_f(v0[3])}, o1 = {gelu_f(v1[0]), gelu_f(v1[1]), gelu_f(v1[2]), gelu_f(v1[3])};
;     store_pair16((u16*)(ws + OFF_UV) + (size_t)row * 1024 + col32, pack4(o0), pack4(o1), fq); }
	v_pk_fma_f32 v[50:51], v[44:45], v[50:51], s[28:29] op_sel_hi:[1,1,0]
	s_nop 0
	v_pk_fma_f32 v[50:51], v[44:45], v[50:51], s[30:31] op_sel_hi:[1,1,0]
	s_nop 0
	v_pk_fma_f32 v[50:51], v[44:45], v[50:51], s[34:35] op_sel_hi:[1,1,0]
	s_nop 0
	v_pk_mul_f32 v[44:45], v[44:45], v[50:51]
	s_nop 0
	v_pk_mul_f32 v[44:45], v[46:47], v[44:45]
	s_nop 0
	v_pk_mul_f32 v[46:47], v[40:41], v[44:45]
	v_pk_fma_f32 v[44:45], v[40:41], v[44:45], v[40:41] neg_lo:[1,0,0] neg_hi:[1,0,0]
	v_mul_f32_e32 v41, v42, v42
	v_cndmask_b32_e32 v50, v45, v47, vcc
	v_cmp_gt_f32_e32 vcc, 0, v40
	v_mul_f32_e32 v41, 0xbf38aa3b, v41
	v_fma_f32 v40, |v42|, s77, 1.0
	v_cndmask_b32_e32 v51, v44, v46, vcc
	v_exp_f32_e32 v44, v41
	v_fma_f32 v41, |v43|, s77, 1.0
	v_rcp_f32_e32 v40, v40
	v_rcp_f32_e32 v41, v41
	v_mul_f32_e32 v45, v43, v43
	v_mul_f32_e32 v45, 0xbf38aa3b, v45
	v_exp_f32_e32 v45, v45
	v_pk_fma_f32 v[46:47], v[40:41], s[26:27], v[130:131] op_sel_hi:[1,0,0]
	v_cmp_gt_f32_e32 vcc, 0, v43
	v_pk_fma_f32 v[46:47], v[40:41], v[46:47], s[28:29] op_sel_hi:[1,1,0]
	s_nop 0
	v_pk_fma_f32 v[46:47], v[40:41], v[46:47], s[30:31] op_sel_hi:[1,1,0]
	s_nop 0
	v_pk_fma_f32 v[46:47], v[40:41], v[46:47], s[34:35] op_sel_hi:[1,1,0]
	s_nop 0
	v_pk_mul_f32 v[40:41], v[40:41], v[46:47]
	s_nop 0
	v_pk_mul_f32 v[40:41], v[44:45], v[40:41]
	s_nop 0
	v_pk_mul_f32 v[44:45], v[42:43], v[40:41]
	v_pk_fma_f32 v[40:41], v[42:43], v[40:41], v[42:43] neg_lo:[1,0,0] neg_hi:[1,0,0]
	s_nop 0
	v_cndmask_b32_e32 v43, v41, v45, vcc
	v_cmp_gt_f32_e32 vcc, 0, v42
	v_cvt_pk_bf16_f32 v42, v51, v50
	s_nop 0
	v_cndmask_b32_e32 v46, v40, v44, vcc
	v_lshl_add_u64 v[40:41], s[10:11], 0, v[48:49]
	v_lshl_add_u64 v[44:45], v[40:41], 0, s[4:5]
	v_cvt_pk_bf16_f32 v40, v55, v54
	v_cvt_pk_bf16_f32 v41, v53, v52
	v_cvt_pk_bf16_f32 v43, v46, v43
	v_permlane16_swap_b32_e32 v40, v42
	s_nop 0
	v_permlane16_swap_b32_e32 v41, v43
	v_lshl_add_u64 v[44:45], v[44:45], 0, v[120:121]
	global_store_dwordx4 v[44:45], v[40:43], off nt
	v_cmp_gt_f32_e32 vcc, 0, v37
	s_nop 0
	v_mul_f32_e32 v41, v36, v36
	v_mul_f32_e32 v41, 0xbf38aa3b, v41
	v_fma_f32 v40, |v36|, s77, 1.0
	v_exp_f32_e32 v42, v41
	v_fma_f32 v41, |v37|, s77, 1.0
	v_rcp_f32_e32 v40, v40
	v_rcp_f32_e32 v41, v41
	v_mul_f32_e32 v43, v37, v37
	v_mul_f32_e32 v43, 0xbf38aa3b, v43
	v_exp_f32_e32 v43, v43
	v_pk_fma_f32 v[46:47], v[40:41], s[26:27], v[130:131] op_sel_hi:[1,0,0]
	s_nop 0
	v_pk_fma_f32 v[46:47], v[40:41], v[46:47], s[28:29] op_sel_hi:[1,1,0]
	s_nop 0
	v_pk_fma_f32 v[46:47], v[40:41], v[46:47], s[30:31] op_sel_hi:[1,1,0]
	s_nop 0
	v_pk_fma_f32 v[46:47], v[40:41], v[46:47], s[34:35] op_sel_hi:[1,1,0]
	s_nop 0
	v_pk_mul_f32 v[40:41], v[40:41], v[46:47]
	s_nop 0
	v_pk_mul_f32 v[40:41], v[42:43], v[40:41]
	s_nop 0
	v_pk_mul_f32 v[42:43], v[36:37], v[40:41]
	v_pk_fma_f32 v[40:41], v[36:37], v[40:41], v[36:37] neg_lo:[1,0,0] neg_hi:[1,0,0]
	v_mul_f32_e32 v37, v38, v38
	v_cndmask_b32_e32 v46, v41, v43, vcc
	v_cmp_gt_f32_e32 vcc, 0, v36
	v_mul_f32_e32 v37, 0xbf38aa3b, v37
	v_fma_f32 v36, |v38|, s77, 1.0
	v_cndmask_b32_e32 v47, v40, v42, vcc
	v_exp_f32_e32 v40, v37
	v_fma_f32 v37, |v39|, s77, 1.0
	v_rcp_f32_e32 v36, v36
	v_rcp_f32_e32 v37, v37
	v_mul_f32_e32 v41, v39, v39
	v_mul_f32_e32 v41, 0xbf38aa3b, v41
	v_exp_f32_e32 v41, v41
	v_pk_fma_f32 v[42:43], v[36:37], s[26:27], v[130:131] op_sel_hi:[1,0,0]
	v_cmp_gt_f32_e32 vcc, 0, v39
	v_pk_fma_f32 v[42:43], v[36:37], v[42:43], s[28:29] op_sel_hi:[1,1,0]
	s_nop 0
	v_pk_fma_f32 v[42:43], v[36:37], v[42:43], s[30:31] op_sel_hi:[1,1,0]
	s_nop 0
	v_pk_fma_f32 v[42:43], v[36:37], v[42:43], s[34:35] op_sel_hi:[1,1,0]
	s_nop 0
	v_pk_mul_f32 v[36:37], v[36:37], v[42:43]
	s_nop 0
	v_pk_mul_f32 v[36:37], v[40:41], v[36:37]
	s_nop 0
	v_pk_mul_f32 v[40:41], v[38:39], v[36:37]
	v_pk_fma_f32 v[36:37], v[38:39], v[36:37], v[38:39] neg_lo:[1,0,0] neg_hi:[1,0,0]
	v_mul_f32_e32 v39, v33, v33
	v_cndmask_b32_e32 v42, v37, v41, vcc
	v_mul_f32_e32 v37, v32, v32
	v_cmp_gt_f32_e32 vcc, 0, v38
	v_mul_f32_e32 v37, 0xbf38aa3b, v37
	v_exp_f32_e32 v38, v37
	v_cndmask_b32_e32 v43, v36, v40, vcc
	v_fma_f32 v36, |v32|, s77, 1.0
	v_fma_f32 v37, |v33|, s77, 1.0
	v_rcp_f32_e32 v36, v36
	v_rcp_f32_e32 v37, v37
	v_mul_f32_e32 v39, 0xbf38aa3b, v39
	v_exp_f32_e32 v39, v39
	v_cmp_gt_f32_e32 vcc, 0, v33
	v_pk_fma_f32 v[40:41], v[36:37], s[26:27], v[130:131] op_sel_hi:[1,0,0]
	s_nop 0
	v_pk_fma_f32 v[40:41], v[36:37], v[40:41], s[28:29] op_sel_hi:[1,1,0]
	s_nop 0
	v_pk_fma_f32 v[40:41], v[36:37], v[40:41], s[30:31] op_sel_hi:[1,1,0]
	s_nop 0
	v_pk_fma_f32 v[40:41], v[36:37], v[40:41], s[34:35] op_sel_hi:[1,1,0]
	s_nop 0
	v_pk_mul_f32 v[36:37], v[36:37], v[40:41]
	s_nop 0
	v_pk_mul_f32 v[36:37], v[38:39], v[36:37]
	s_nop 0
	v_pk_mul_f32 v[38:39], v[32:33], v[36:37]
	v_pk_fma_f32 v[36:37], v[32:33], v[36:37], v[32:33] neg_lo:[1,0,0] neg_hi:[1,0,0]
	v_mul_f32_e32 v33, v34, v34
	v_cndmask_b32_e32 v40, v37, v39, vcc
	v_cmp_gt_f32_e32 vcc, 0, v32
	v_mul_f32_e32 v33, 0xbf38aa3b, v33
	v_fma_f32 v32, |v34|, s77, 1.0
	v_cndmask_b32_e32 v41, v36, v38, vcc
	v_exp_f32_e32 v36, v33
	v_fma_f32 v33, |v35|, s77, 1.0
	v_rcp_f32_e32 v32, v32
	v_rcp_f32_e32 v33, v33
	v_mul_f32_e32 v37, v35, v35
	v_mul_f32_e32 v37, 0xbf38aa3b, v37
	v_exp_f32_e32 v37, v37
	v_pk_fma_f32 v[38:39], v[32:33], s[26:27], v[130:131] op_sel_hi:[1,0,0]
	v_cmp_gt_f32_e32 vcc, 0, v35
	v_pk_fma_f32 v[38:39], v[32:33], v[38:39], s[28:29] op_sel_hi:[1,1,0]
	s_nop 0
	v_pk_fma_f32 v[38:39], v[32:33], v[38:39], s[30:31] op_sel_hi:[1,1,0]
	s_nop 0
	v_pk_fma_f32 v[38:39], v[32:33], v[38:39], s[34:35] op_sel_hi:[1,1,0]
	s_nop 0
	v_pk_mul_f32 v[32:33], v[32:33], v[38:39]
	s_nop 0
	v_pk_mul_f32 v[32:33], v[36:37], v[32:33]
	s_nop 0
; __device__ __forceinline__ u32x2 pack4(f32x4 v) { u32x2 r; r.x = cvt_pk(v[0], v[1]); r.y = cvt_pk(v[2], v[3]); return r; }
; __device__ __forceinline__ float gelu_f(float v) {
;   const float av = fabsf(v), t = __builtin_amdgcn_rcpf(av * 0.2316418882f + 1.0f);
;   float q = t * 0.5307027145f + (-0.7265760135f); q = q * t + 0.7107068705f; q = q * t + (-0.142248368f); q = q * t + 0.127414796f; q = q * t;
;   const float e = __builtin_amdgcn_exp2f((v * v) * (-0.72134752044f));
;   const float m = v * (q * e), r = v - m;
;   return v < 0.f ? m : r;
; }
; template <int SEC> __device__ __forceinline__ void epiB2(const Params& p, int row, int col32, f32x4 v0, f32x4 v1, int fq) {
;     ...
;   if (SEC == 0) { f32x4 o0 = {gelu_f(v0[0]), gelu_f(v0[1]), gelu_f(v0[2]), gelu_f(v0[3])}, o1 = {gelu_f(v1[0]), gelu_f(v1[1]), gelu_f(v1[2]), gelu_f(v1[3])};
;     store_pair16((u16*)(ws + OFF_UV) + (size_t)row * 1024 + col32, pack4(o0), pack4(o1), fq); }
	v_pk_mul_f32 v[36:37], v[34:35], v[32:33]
	v_pk_fma_f32 v[32:33], v[34:35], v[32:33], v[34:35] neg_lo:[1,0,0] neg_hi:[1,0,0]
	s_nop 0
	v_cndmask_b32_e32 v35, v33, v37, vcc
	v_cmp_gt_f32_e32 vcc, 0, v34
	v_cvt_pk_bf16_f32 v33, v43, v42
	v_cvt_pk_bf16_f32 v34, v41, v40
	v_cndmask_b32_e32 v36, v32, v36, vcc
	v_cvt_pk_bf16_f32 v32, v47, v46
	v_cvt_pk_bf16_f32 v35, v36, v35
	s_nop 0
	v_permlane16_swap_b32_e32 v32, v34
	v_permlane16_swap_b32_e32 v33, v35
	global_store_dwordx4 v[44:45], v[32:35], off offset:256 nt
	v_mul_f32_e32 v37, v29, v29
	v_mul_f32_e32 v37, 0xbf38aa3b, v37
	v_mul_f32_e32 v35, v28, v28
	v_mul_f32_e32 v35, 0xbf38aa3b, v35
	v_fma_f32 v34, |v28|, s77, 1.0
	v_exp_f32_e32 v36, v35
	v_fma_f32 v35, |v29|, s77, 1.0
	v_rcp_f32_e32 v34, v34
	v_rcp_f32_e32 v35, v35
	v_exp_f32_e32 v37, v37
	v_cmp_gt_f32_e32 vcc, 0, v29
	v_add_u32_e32 v32, 0xa0, v128
	v_pk_fma_f32 v[38:39], v[34:35], s[26:27], v[130:131] op_sel_hi:[1,0,0]
	v_mov_b32_e32 v33, v129
	v_pk_fma_f32 v[38:39], v[34:35], v[38:39], s[28:29] op_sel_hi:[1,1,0]
	v_lshlrev_b64 v[32:33], 11, v[32:33]
	v_pk_fma_f32 v[38:39], v[34:35], v[38:39], s[30:31] op_sel_hi:[1,1,0]
	v_add_u32_e32 v128, 0xb0, v128
	v_pk_fma_f32 v[38:39], v[34:35], v[38:39], s[34:35] op_sel_hi:[1,1,0]
	s_nop 0
	v_pk_mul_f32 v[34:35], v[34:35], v[38:39]
	s_nop 0
	v_pk_mul_f32 v[34:35], v[36:37], v[34:35]
	s_nop 0
	v_pk_mul_f32 v[36:37], v[28:29], v[34:35]
	v_pk_fma_f32 v[34:35], v[28:29], v[34:35], v[28:29] neg_lo:[1,0,0] neg_hi:[1,0,0]
	v_mul_f32_e32 v29, v30, v30
	v_cndmask_b32_e32 v38, v35, v37, vcc
	v_cmp_gt_f32_e32 vcc, 0, v28
	v_mul_f32_e32 v29, 0xbf38aa3b, v29
	v_fma_f32 v28, |v30|, s77, 1.0
	v_cndmask_b32_e32 v39, v34, v36, vcc
	v_exp_f32_e32 v34, v29
	v_fma_f32 v29, |v31|, s77, 1.0
	v_rcp_f32_e32 v28, v28
	v_rcp_f32_e32 v29, v29
	v_mul_f32_e32 v35, v31, v31
	v_mul_f32_e32 v35, 0xbf38aa3b, v35
	v_exp_f32_e32 v35, v35
	v_pk_fma_f32 v[36:37], v[28:29], s[26:27], v[130:131] op_sel_hi:[1,0,0]
	v_cmp_gt_f32_e32 vcc, 0, v31
	v_pk_fma_f32 v[36:37], v[28:29], v[36:37], s[28:29] op_sel_hi:[1,1,0]
	s_nop 0
	v_pk_fma_f32 v[36:37], v[28:29], v[36:37], s[30:31] op_sel_hi:[1,1,0]
	s_nop 0
	v_pk_fma_f32 v[36:37], v[28:29], v[36:37], s[34:35] op_sel_hi:[1,1,0]
	s_nop 0
	v_pk_mul_f32 v[28:29], v[28:29], v[36:37]
	s_nop 0
	v_pk_mul_f32 v[28:29], v[34:35], v[28:29]
	s_nop 0
	v_pk_mul_f32 v[34:35], v[30:31], v[28:29]
	v_pk_fma_f32 v[28:29], v[30:31], v[28:29], v[30:31] neg_lo:[1,0,0] neg_hi:[1,0,0]
	v_mul_f32_e32 v31, v25, v25
	v_cndmask_b32_e32 v36, v29, v35, vcc
	v_mul_f32_e32 v29, v24, v24
	v_cmp_gt_f32_e32 vcc, 0, v30
	v_mul_f32_e32 v29, 0xbf38aa3b, v29
	v_exp_f32_e32 v30, v29
	v_cndmask_b32_e32 v37, v28, v34, vcc
	v_fma_f32 v28, |v24|, s77, 1.0
	v_fma_f32 v29, |v25|, s77, 1.0
	v_rcp_f32_e32 v28, v28
	v_rcp_f32_e32 v29, v29
	v_mul_f32_e32 v31, 0xbf38aa3b, v31
	v_exp_f32_e32 v31, v31
	v_cmp_gt_f32_e32 vcc, 0, v25
	v_pk_fma_f32 v[34:35], v[28:29], s[26:27], v[130:131] op_sel_hi:[1,0,0]
	s_nop 0
	v_pk_fma_f32 v[34:35], v[28:29], v[34:35], s[28:29] op_sel_hi:[1,1,0]
	s_nop 0
	v_pk_fma_f32 v[34:35], v[28:29], v[34:35], s[30:31] op_sel_hi:[1,1,0]
	s_nop 0
	v_pk_fma_f32 v[34:35], v[28:29], v[34:35], s[34:35] op_sel_hi:[1,1,0]
	s_nop 0
	v_pk_mul_f32 v[28:29], v[28:29], v[34:35]
	s_nop 0
	v_pk_mul_f32 v[28:29], v[30:31], v[28:29]
	s_nop 0
	v_pk_mul_f32 v[30:31], v[24:25], v[28:29]
	v_pk_fma_f32 v[28:29], v[24:25], v[28:29], v[24:25] neg_lo:[1,0,0] neg_hi:[1,0,0]
	v_mul_f32_e32 v25, v26, v26
	v_cndmask_b32_e32 v34, v29, v31, vcc
	v_cmp_gt_f32_e32 vcc, 0, v24
	v_mul_f32_e32 v25, 0xbf38aa3b, v25
	v_fma_f32 v24, |v26|, s77, 1.0
	v_cndmask_b32_e32 v35, v28, v30, vcc
	v_exp_f32_e32 v28, v25
	v_fma_f32 v25, |v27|, s77, 1.0
	v_rcp_f32_e32 v24, v24
	v_rcp_f32_e32 v25, v25
	v_mul_f32_e32 v29, v27, v27
	v_mul_f32_e32 v29, 0xbf38aa3b, v29
	v_exp_f32_e32 v29, v29
	v_pk_fma_f32 v[30:31], v[24:25], s[26:27], v[130:131] op_sel_hi:[1,0,0]
	v_cmp_gt_f32_e32 vcc, 0, v27
	v_pk_fma_f32 v[30:31], v[24:25], v[30:31], s[28:29] op_sel_hi:[1,1,0]
	s_nop 0
	v_pk_fma_f32 v[30:31], v[24:25], v[30:31], s[30:31] op_sel_hi:[1,1,0]
	s_nop 0
	v_pk_fma_f32 v[30:31], v[24:25], v[30:31], s[34:35] op_sel_hi:[1,1,0]
	s_nop 0
	v_pk_mul_f32 v[24:25], v[24:25], v[30:31]
	s_nop 0
	v_pk_mul_f32 v[24:25], v[28:29], v[24:25]
	s_nop 0
	v_pk_mul_f32 v[28:29], v[26:27], v[24:25]
	v_pk_fma_f32 v[24:25], v[26:27], v[24:25], v[26:27] neg_lo:[1,0,0] neg_hi:[1,0,0]
	s_nop 0
	v_cndmask_b32_e32 v27, v25, v29, vcc
	v_cmp_gt_f32_e32 vcc, 0, v26
	v_cvt_pk_bf16_f32 v26, v35, v34
	s_nop 0
	v_cndmask_b32_e32 v30, v24, v28, vcc
	v_lshl_add_u64 v[24:25], s[10:11], 0, v[32:33]
	v_lshl_add_u64 v[28:29], v[24:25], 0, s[4:5]
	v_cvt_pk_bf16_f32 v24, v39, v38
	v_cvt_pk_bf16_f32 v25, v37, v36
	v_cvt_pk_bf16_f32 v27, v30, v27
	v_permlane16_swap_b32_e32 v24, v26
	s_nop 0
	v_permlane16_swap_b32_e32 v25, v27
	v_lshl_add_u64 v[28:29], v[28:29], 0, v[120:121]
	global_store_dwordx4 v[28:29], v[24:27], off nt
	v_cmp_gt_f32_e32 vcc, 0, v21
	s_nop 0
	v_mul_f32_e32 v25, v20, v20
	v_mul_f32_e32 v25, 0xbf38aa3b, v25
	v_fma_f32 v24, |v20|, s77, 1.0
	v_exp_f32_e32 v26, v25
	v_fma_f32 v25, |v21|, s77, 1.0
	v_rcp_f32_e32 v24, v24
	v_rcp_f32_e32 v25, v25
	v_mul_f32_e32 v27, v21, v21
	v_mul_f32_e32 v27, 0xbf38aa3b, v27
	v_exp_f32_e32 v27, v27
	v_pk_fma_f32 v[30:31], v[24:25], s[26:27], v[130:131] op_sel_hi:[1,0,0]
	s_nop 0
	v_pk_fma_f32 v[30:31], v[24:25], v[30:31], s[28:29] op_sel_hi:[1,1,0]
	s_nop 0
	v_pk_fma_f32 v[30:31], v[24:25], v[30:31], s[30:31] op_sel_hi:[1,1,0]
	s_nop 0
	v_pk_fma_f32 v[30:31], v[24:25], v[30:31], s[34:35] op_sel_hi:[1,1,0]
	s_nop 0
	v_pk_mul_f32 v[24:25], v[24:25], v[30:31]
	s_nop 0
; __device__ __forceinline__ u32x2 pack4(f32x4 v) { u32x2 r; r.x = cvt_pk(v[0], v[1]); r.y = cvt_pk(v[2], v[3]); return r; }
; __device__ __forceinline__ float gelu_f(float v) {
;   const float av = fabsf(v), t = __builtin_amdgcn_rcpf(av * 0.2316418882f + 1.0f);
;   float q = t * 0.5307027145f + (-0.7265760135f); q = q * t + 0.7107068705f; q = q * t + (-0.142248368f); q = q * t + 0.127414796f; q = q * t;
;   const float e = __builtin_amdgcn_exp2f((v * v) * (-0.72134752044f));
;   const float m = v * (q * e), r = v - m;
;   return v < 0.f ? m : r;
; }
; template <int SEC> __device__ __forceinline__ void epiB2(const Params& p, int row, int col32, f32x4 v0, f32x4 v1, int fq) {
;     ...
;   if (SEC == 0) { f32x4 o0 = {gelu_f(v0[0]), gelu_f(v0[1]), gelu_f(v0[2]), gelu_f(v0[3])}, o1 = {gelu_f(v1[0]), gelu_f(v1[1]), gelu_f(v1[2]), gelu_f(v1[3])};
;     store_pair16((u16*)(ws + OFF_UV) + (size_t)row * 1024 + col32, pack4(o0), pack4(o1), fq); }
	v_pk_mul_f32 v[24:25], v[26:27], v[24:25]
	s_nop 0
	v_pk_mul_f32 v[26:27], v[20:21], v[24:25]
	v_pk_fma_f32 v[24:25], v[20:21], v[24:25], v[20:21] neg_lo:[1,0,0] neg_hi:[1,0,0]
	v_mul_f32_e32 v21, v22, v22
	v_cndmask_b32_e32 v30, v25, v27, vcc
	v_cmp_gt_f32_e32 vcc, 0, v20
	v_mul_f32_e32 v21, 0xbf38aa3b, v21
	v_fma_f32 v20, |v22|, s77, 1.0
	v_cndmask_b32_e32 v31, v24, v26, vcc
	v_exp_f32_e32 v24, v21
	v_fma_f32 v21, |v23|, s77, 1.0
	v_rcp_f32_e32 v20, v20
	v_rcp_f32_e32 v21, v21
	v_mul_f32_e32 v25, v23, v23
	v_mul_f32_e32 v25, 0xbf38aa3b, v25
	v_exp_f32_e32 v25, v25
	v_pk_fma_f32 v[26:27], v[20:21], s[26:27], v[130:131] op_sel_hi:[1,0,0]
	v_cmp_gt_f32_e32 vcc, 0, v23
	v_pk_fma_f32 v[26:27], v[20:21], v[26:27], s[28:29] op_sel_hi:[1,1,0]
	s_nop 0
	v_pk_fma_f32 v[26:27], v[20:21], v[26:27], s[30:31] op_sel_hi:[1,1,0]
	s_nop 0
	v_pk_fma_f32 v[26:27], v[20:21], v[26:27], s[34:35] op_sel_hi:[1,1,0]
	s_nop 0
	v_pk_mul_f32 v[20:21], v[20:21], v[26:27]
	s_nop 0
	v_pk_mul_f32 v[20:21], v[24:25], v[20:21]
	s_nop 0
	v_pk_mul_f32 v[24:25], v[22:23], v[20:21]
	v_pk_fma_f32 v[20:21], v[22:23], v[20:21], v[22:23] neg_lo:[1,0,0] neg_hi:[1,0,0]
	v_mul_f32_e32 v23, v17, v17
	v_cndmask_b32_e32 v26, v21, v25, vcc
	v_mul_f32_e32 v21, v16, v16
	v_cmp_gt_f32_e32 vcc, 0, v22
	v_mul_f32_e32 v21, 0xbf38aa3b, v21
	v_exp_f32_e32 v22, v21
	v_cndmask_b32_e32 v27, v20, v24, vcc
	v_fma_f32 v20, |v16|, s77, 1.0
	v_fma_f32 v21, |v17|, s77, 1.0
	v_rcp_f32_e32 v20, v20
	v_rcp_f32_e32 v21, v21
	v_mul_f32_e32 v23, 0xbf38aa3b, v23
	v_exp_f32_e32 v23, v23
	v_cmp_gt_f32_e32 vcc, 0, v17
	v_pk_fma_f32 v[24:25], v[20:21], s[26:27], v[130:131] op_sel_hi:[1,0,0]
	s_nop 0
	v_pk_fma_f32 v[24:25], v[20:21], v[24:25], s[28:29] op_sel_hi:[1,1,0]
	s_nop 0
	v_pk_fma_f32 v[24:25], v[20:21], v[24:25], s[30:31] op_sel_hi:[1,1,0]
	s_nop 0
	v_pk_fma_f32 v[24:25], v[20:21], v[24:25], s[34:35] op_sel_hi:[1,1,0]
	s_nop 0
	v_pk_mul_f32 v[20:21], v[20:21], v[24:25]
	s_nop 0
	v_pk_mul_f32 v[20:21], v[22:23], v[20:21]
	s_nop 0
	v_pk_mul_f32 v[22:23], v[16:17], v[20:21]
	v_pk_fma_f32 v[20:21], v[16:17], v[20:21], v[16:17] neg_lo:[1,0,0] neg_hi:[1,0,0]
	v_mul_f32_e32 v17, v18, v18
	v_cndmask_b32_e32 v24, v21, v23, vcc
	v_cmp_gt_f32_e32 vcc, 0, v16
	v_mul_f32_e32 v17, 0xbf38aa3b, v17
	v_fma_f32 v16, |v18|, s77, 1.0
	v_cndmask_b32_e32 v25, v20, v22, vcc
	v_exp_f32_e32 v20, v17
	v_fma_f32 v17, |v19|, s77, 1.0
	v_rcp_f32_e32 v16, v16
	v_rcp_f32_e32 v17, v17
	v_mul_f32_e32 v21, v19, v19
	v_mul_f32_e32 v21, 0xbf38aa3b, v21
	v_exp_f32_e32 v21, v21
	v_pk_fma_f32 v[22:23], v[16:17], s[26:27], v[130:131] op_sel_hi:[1,0,0]
	v_cmp_gt_f32_e32 vcc, 0, v19
	v_pk_fma_f32 v[22:23], v[16:17], v[22:23], s[28:29] op_sel_hi:[1,1,0]
	s_nop 0
	v_pk_fma_f32 v[22:23], v[16:17], v[22:23], s[30:31] op_sel_hi:[1,1,0]
	s_nop 0
	v_pk_fma_f32 v[22:23], v[16:17], v[22:23], s[34:35] op_sel_hi:[1,1,0]
	s_nop 0
	v_pk_mul_f32 v[16:17], v[16:17], v[22:23]
	s_nop 0
	v_pk_mul_f32 v[16:17], v[20:21], v[16:17]
	s_nop 0
	v_pk_mul_f32 v[20:21], v[18:19], v[16:17]
	v_pk_fma_f32 v[16:17], v[18:19], v[16:17], v[18:19] neg_lo:[1,0,0] neg_hi:[1,0,0]
	s_nop 0
	v_cndmask_b32_e32 v19, v17, v21, vcc
	v_cmp_gt_f32_e32 vcc, 0, v18
	v_cvt_pk_bf16_f32 v17, v27, v26
	v_cvt_pk_bf16_f32 v18, v25, v24
	v_cndmask_b32_e32 v20, v16, v20, vcc
	v_cvt_pk_bf16_f32 v16, v31, v30
	v_cvt_pk_bf16_f32 v19, v20, v19
	s_nop 0
	v_permlane16_swap_b32_e32 v16, v18
	v_permlane16_swap_b32_e32 v17, v19
	global_store_dwordx4 v[28:29], v[16:19], off offset:256 nt
	v_mul_f32_e32 v21, v13, v13
	v_mul_f32_e32 v21, 0xbf38aa3b, v21
	v_mul_f32_e32 v19, v12, v12
	v_mul_f32_e32 v19, 0xbf38aa3b, v19
	v_fma_f32 v18, |v12|, s77, 1.0
	v_exp_f32_e32 v20, v19
	v_fma_f32 v19, |v13|, s77, 1.0
	v_rcp_f32_e32 v18, v18
	v_rcp_f32_e32 v19, v19
	v_exp_f32_e32 v21, v21
	v_cmp_gt_f32_e32 vcc, 0, v13
	v_lshlrev_b64 v[16:17], 11, v[128:129]
	v_pk_fma_f32 v[22:23], v[18:19], s[26:27], v[130:131] op_sel_hi:[1,0,0]
	s_nop 0
	v_pk_fma_f32 v[22:23], v[18:19], v[22:23], s[28:29] op_sel_hi:[1,1,0]
	s_nop 0
	v_pk_fma_f32 v[22:23], v[18:19], v[22:23], s[30:31] op_sel_hi:[1,1,0]
	s_nop 0
	v_pk_fma_f32 v[22:23], v[18:19], v[22:23], s[34:35] op_sel_hi:[1,1,0]
	s_nop 0
	v_pk_mul_f32 v[18:19], v[18:19], v[22:23]
	s_nop 0
	v_pk_mul_f32 v[18:19], v[20:21], v[18:19]
	s_nop 0
	v_pk_mul_f32 v[20:21], v[12:13], v[18:19]
	v_pk_fma_f32 v[18:19], v[12:13], v[18:19], v[12:13] neg_lo:[1,0,0] neg_hi:[1,0,0]
	v_mul_f32_e32 v13, v14, v14
	v_cndmask_b32_e32 v22, v19, v21, vcc
	v_cmp_gt_f32_e32 vcc, 0, v12
	v_mul_f32_e32 v13, 0xbf38aa3b, v13
	v_fma_f32 v12, |v14|, s77, 1.0
	v_cndmask_b32_e32 v23, v18, v20, vcc
	v_exp_f32_e32 v18, v13
	v_fma_f32 v13, |v15|, s77, 1.0
	v_rcp_f32_e32 v12, v12
	v_rcp_f32_e32 v13, v13
	v_mul_f32_e32 v19, v15, v15
	v_mul_f32_e32 v19, 0xbf38aa3b, v19
	v_exp_f32_e32 v19, v19
	v_pk_fma_f32 v[20:21], v[12:13], s[26:27], v[130:131] op_sel_hi:[1,0,0]
	v_cmp_gt_f32_e32 vcc, 0, v15
	v_pk_fma_f32 v[20:21], v[12:13], v[20:21], s[28:29] op_sel_hi:[1,1,0]
	s_nop 0
	v_pk_fma_f32 v[20:21], v[12:13], v[20:21], s[30:31] op_sel_hi:[1,1,0]
	s_nop 0
	v_pk_fma_f32 v[20:21], v[12:13], v[20:21], s[34:35] op_sel_hi:[1,1,0]
	s_nop 0
	v_pk_mul_f32 v[12:13], v[12:13], v[20:21]
	s_nop 0
	v_pk_mul_f32 v[12:13], v[18:19], v[12:13]
	s_nop 0
	v_pk_mul_f32 v[18:19], v[14:15], v[12:13]
	v_pk_fma_f32 v[12:13], v[14:15], v[12:13], v[14:15] neg_lo:[1,0,0] neg_hi:[1,0,0]
	v_mul_f32_e32 v15, v9, v9
	v_cndmask_b32_e32 v20, v13, v19, vcc
	v_mul_f32_e32 v13, v8, v8
	v_cmp_gt_f32_e32 vcc, 0, v14
	v_mul_f32_e32 v13, 0xbf38aa3b, v13
	v_exp_f32_e32 v14, v13
	v_cndmask_b32_e32 v21, v12, v18, vcc
	v_fma_f32 v12, |v8|, s77, 1.0
	v_fma_f32 v13, |v9|, s77, 1.0
; __device__ __forceinline__ u32x2 pack4(f32x4 v) { u32x2 r; r.x = cvt_pk(v[0], v[1]); r.y = cvt_pk(v[2], v[3]); return r; }
; __device__ __forceinline__ float gelu_f(float v) {
;   const float av = fabsf(v), t = __builtin_amdgcn_rcpf(av * 0.2316418882f + 1.0f);
;   float q = t * 0.5307027145f + (-0.7265760135f); q = q * t + 0.7107068705f; q = q * t + (-0.142248368f); q = q * t + 0.127414796f; q = q * t;
;   const float e = __builtin_amdgcn_exp2f((v * v) * (-0.72134752044f));
;   const float m = v * (q * e), r = v - m;
;   return v < 0.f ? m : r;
; }
; template <int SEC> __device__ __forceinline__ void epiB2(const Params& p, int row, int col32, f32x4 v0, f32x4 v1, int fq) {
;     ...
;   if (SEC == 0) { f32x4 o0 = {gelu_f(v0[0]), gelu_f(v0[1]), gelu_f(v0[2]), gelu_f(v0[3])}, o1 = {gelu_f(v1[0]), gelu_f(v1[1]), gelu_f(v1[2]), gelu_f(v1[3])};
;     store_pair16((u16*)(ws + OFF_UV) + (size_t)row * 1024 + col32, pack4(o0), pack4(o1), fq); }
	v_rcp_f32_e32 v12, v12
	v_rcp_f32_e32 v13, v13
	v_mul_f32_e32 v15, 0xbf38aa3b, v15
	v_exp_f32_e32 v15, v15
	v_cmp_gt_f32_e32 vcc, 0, v9
	v_pk_fma_f32 v[18:19], v[12:13], s[26:27], v[130:131] op_sel_hi:[1,0,0]
	s_nop 0
	v_pk_fma_f32 v[18:19], v[12:13], v[18:19], s[28:29] op_sel_hi:[1,1,0]
	s_nop 0
	v_pk_fma_f32 v[18:19], v[12:13], v[18:19], s[30:31] op_sel_hi:[1,1,0]
	s_nop 0
	v_pk_fma_f32 v[18:19], v[12:13], v[18:19], s[34:35] op_sel_hi:[1,1,0]
	s_nop 0
	v_pk_mul_f32 v[12:13], v[12:13], v[18:19]
	s_nop 0
	v_pk_mul_f32 v[12:13], v[14:15], v[12:13]
	s_nop 0
	v_pk_mul_f32 v[14:15], v[8:9], v[12:13]
	v_pk_fma_f32 v[12:13], v[8:9], v[12:13], v[8:9] neg_lo:[1,0,0] neg_hi:[1,0,0]
	v_mul_f32_e32 v9, v10, v10
	v_cndmask_b32_e32 v18, v13, v15, vcc
	v_cmp_gt_f32_e32 vcc, 0, v8
	v_mul_f32_e32 v9, 0xbf38aa3b, v9
	v_fma_f32 v8, |v10|, s77, 1.0
	v_cndmask_b32_e32 v19, v12, v14, vcc
	v_exp_f32_e32 v12, v9
	v_fma_f32 v9, |v11|, s77, 1.0
	v_rcp_f32_e32 v8, v8
	v_rcp_f32_e32 v9, v9
	v_mul_f32_e32 v13, v11, v11
	v_mul_f32_e32 v13, 0xbf38aa3b, v13
	v_exp_f32_e32 v13, v13
	v_pk_fma_f32 v[14:15], v[8:9], s[26:27], v[130:131] op_sel_hi:[1,0,0]
	v_cmp_gt_f32_e32 vcc, 0, v11
	v_pk_fma_f32 v[14:15], v[8:9], v[14:15], s[28:29] op_sel_hi:[1,1,0]
	s_nop 0
	v_pk_fma_f32 v[14:15], v[8:9], v[14:15], s[30:31] op_sel_hi:[1,1,0]
	s_nop 0
	v_pk_fma_f32 v[14:15], v[8:9], v[14:15], s[34:35] op_sel_hi:[1,1,0]
	s_nop 0
	v_pk_mul_f32 v[8:9], v[8:9], v[14:15]
	s_nop 0
	v_pk_mul_f32 v[8:9], v[12:13], v[8:9]
	s_nop 0
	v_pk_mul_f32 v[12:13], v[10:11], v[8:9]
	v_pk_fma_f32 v[8:9], v[10:11], v[8:9], v[10:11] neg_lo:[1,0,0] neg_hi:[1,0,0]
	s_nop 0
	v_cndmask_b32_e32 v11, v9, v13, vcc
	v_cmp_gt_f32_e32 vcc, 0, v10
	v_cvt_pk_bf16_f32 v10, v19, v18
	s_nop 0
	v_cndmask_b32_e32 v14, v8, v12, vcc
	v_lshl_add_u64 v[8:9], s[10:11], 0, v[16:17]
	v_lshl_add_u64 v[12:13], v[8:9], 0, s[4:5]
	v_cvt_pk_bf16_f32 v8, v23, v22
	v_cvt_pk_bf16_f32 v9, v21, v20
	v_cvt_pk_bf16_f32 v11, v14, v11
	v_permlane16_swap_b32_e32 v8, v10
	s_nop 0
	v_permlane16_swap_b32_e32 v9, v11
	v_lshl_add_u64 v[12:13], v[12:13], 0, v[120:121]
	global_store_dwordx4 v[12:13], v[8:11], off nt
	v_cmp_gt_f32_e32 vcc, 0, v5
	s_nop 0
	v_mul_f32_e32 v9, v4, v4
	v_mul_f32_e32 v9, 0xbf38aa3b, v9
	v_fma_f32 v8, |v4|, s77, 1.0
	v_exp_f32_e32 v10, v9
	v_fma_f32 v9, |v5|, s77, 1.0
	v_rcp_f32_e32 v8, v8
	v_rcp_f32_e32 v9, v9
	v_mul_f32_e32 v11, v5, v5
	v_mul_f32_e32 v11, 0xbf38aa3b, v11
	v_exp_f32_e32 v11, v11
	v_pk_fma_f32 v[14:15], v[8:9], s[26:27], v[130:131] op_sel_hi:[1,0,0]
	s_nop 0
	v_pk_fma_f32 v[14:15], v[8:9], v[14:15], s[28:29] op_sel_hi:[1,1,0]
	s_nop 0
	v_pk_fma_f32 v[14:15], v[8:9], v[14:15], s[30:31] op_sel_hi:[1,1,0]
	s_nop 0
	v_pk_fma_f32 v[14:15], v[8:9], v[14:15], s[34:35] op_sel_hi:[1,1,0]
	s_nop 0
	v_pk_mul_f32 v[8:9], v[8:9], v[14:15]
	s_nop 0
	v_pk_mul_f32 v[8:9], v[10:11], v[8:9]
	s_nop 0
	v_pk_mul_f32 v[10:11], v[4:5], v[8:9]
	v_pk_fma_f32 v[8:9], v[4:5], v[8:9], v[4:5] neg_lo:[1,0,0] neg_hi:[1,0,0]
	v_mul_f32_e32 v5, v6, v6
	v_cndmask_b32_e32 v14, v9, v11, vcc
	v_cmp_gt_f32_e32 vcc, 0, v4
	v_mul_f32_e32 v5, 0xbf38aa3b, v5
	v_fma_f32 v4, |v6|, s77, 1.0
	v_cndmask_b32_e32 v15, v8, v10, vcc
	v_exp_f32_e32 v8, v5
	v_fma_f32 v5, |v7|, s77, 1.0
	v_rcp_f32_e32 v4, v4
	v_rcp_f32_e32 v5, v5
	v_mul_f32_e32 v9, v7, v7
	v_mul_f32_e32 v9, 0xbf38aa3b, v9
	v_exp_f32_e32 v9, v9
	v_pk_fma_f32 v[10:11], v[4:5], s[26:27], v[130:131] op_sel_hi:[1,0,0]
	v_cmp_gt_f32_e32 vcc, 0, v7
	v_pk_fma_f32 v[10:11], v[4:5], v[10:11], s[28:29] op_sel_hi:[1,1,0]
	s_nop 0
	v_pk_fma_f32 v[10:11], v[4:5], v[10:11], s[30:31] op_sel_hi:[1,1,0]
	s_nop 0
	v_pk_fma_f32 v[10:11], v[4:5], v[10:11], s[34:35] op_sel_hi:[1,1,0]
	s_nop 0
	v_pk_mul_f32 v[4:5], v[4:5], v[10:11]
	s_nop 0
	v_pk_mul_f32 v[4:5], v[8:9], v[4:5]
	s_nop 0
	v_pk_mul_f32 v[8:9], v[6:7], v[4:5]
	v_pk_fma_f32 v[4:5], v[6:7], v[4:5], v[6:7] neg_lo:[1,0,0] neg_hi:[1,0,0]
	v_mul_f32_e32 v7, v1, v1
	v_cndmask_b32_e32 v10, v5, v9, vcc
	v_mul_f32_e32 v5, v0, v0
	v_cmp_gt_f32_e32 vcc, 0, v6
	v_mul_f32_e32 v5, 0xbf38aa3b, v5
	v_exp_f32_e32 v6, v5
	v_cndmask_b32_e32 v11, v4, v8, vcc
	v_fma_f32 v4, |v0|, s77, 1.0
	v_fma_f32 v5, |v1|, s77, 1.0
	v_rcp_f32_e32 v4, v4
	v_rcp_f32_e32 v5, v5
	v_mul_f32_e32 v7, 0xbf38aa3b, v7
	v_exp_f32_e32 v7, v7
	v_cmp_gt_f32_e32 vcc, 0, v1
	v_pk_fma_f32 v[8:9], v[4:5], s[26:27], v[130:131] op_sel_hi:[1,0,0]
	s_nop 0
	v_pk_fma_f32 v[8:9], v[4:5], v[8:9], s[28:29] op_sel_hi:[1,1,0]
	s_nop 0
	v_pk_fma_f32 v[8:9], v[4:5], v[8:9], s[30:31] op_sel_hi:[1,1,0]
	s_nop 0
	v_pk_fma_f32 v[8:9], v[4:5], v[8:9], s[34:35] op_sel_hi:[1,1,0]
	s_nop 0
	v_pk_mul_f32 v[4:5], v[4:5], v[8:9]
	s_nop 0
	v_pk_mul_f32 v[4:5], v[6:7], v[4:5]
	s_nop 0
	v_pk_mul_f32 v[6:7], v[0:1], v[4:5]
	v_pk_fma_f32 v[4:5], v[0:1], v[4:5], v[0:1] neg_lo:[1,0,0] neg_hi:[1,0,0]
	v_mul_f32_e32 v1, v2, v2
	v_cndmask_b32_e32 v8, v5, v7, vcc
	v_cmp_gt_f32_e32 vcc, 0, v0
	v_mul_f32_e32 v1, 0xbf38aa3b, v1
	v_fma_f32 v0, |v2|, s77, 1.0
	v_cndmask_b32_e32 v9, v4, v6, vcc
	v_exp_f32_e32 v4, v1
	v_fma_f32 v1, |v3|, s77, 1.0
	v_rcp_f32_e32 v0, v0
	v_rcp_f32_e32 v1, v1
	v_mul_f32_e32 v5, v3, v3
	v_mul_f32_e32 v5, 0xbf38aa3b, v5
	v_exp_f32_e32 v5, v5
	v_pk_fma_f32 v[6:7], v[0:1], s[26:27], v[130:131] op_sel_hi:[1,0,0]
	v_cmp_gt_f32_e32 vcc, 0, v3
	v_pk_fma_f32 v[6:7], v[0:1], v[6:7], s[28:29] op_sel_hi:[1,1,0]
	s_nop 0
	v_pk_fma_f32 v[6:7], v[0:1], v[6:7], s[30:31] op_sel_hi:[1,1,0]
	s_nop 0
	v_pk_fma_f32 v[6:7], v[0:1], v[6:7], s[34:35] op_sel_hi:[1,1,0]
	s_nop 0
	v_pk_mul_f32 v[0:1], v[0:1], v[6:7]
	s_nop 0
	v_pk_mul_f32 v[0:1], v[4:5], v[0:1]
	s_nop 0
	v_pk_mul_f32 v[4:5], v[2:3], v[0:1]
	v_pk_fma_f32 v[0:1], v[2:3], v[0:1], v[2:3] neg_lo:[1,0,0] neg_hi:[1,0,0]
	s_nop 0
	v_cndmask_b32_e32 v3, v1, v5, vcc
	v_cmp_gt_f32_e32 vcc, 0, v2
	v_cvt_pk_bf16_f32 v1, v11, v10
	v_cvt_pk_bf16_f32 v2, v9, v8
	v_cndmask_b32_e32 v4, v0, v4, vcc
	v_cvt_pk_bf16_f32 v0, v15, v14
	v_cvt_pk_bf16_f32 v3, v4, v3
	s_nop 0
	v_permlane16_swap_b32_e32 v0, v2
	v_permlane16_swap_b32_e32 v1, v3
	global_store_dwordx4 v[12:13], v[0:3], off offset:256 nt
	s_branch .LBB0_189
